# stack: attention O epilogue + combine loop rewrites, full-line lane-contiguous stores on FFN1 x2 and RKV GEMMs, relaxed post-epilogue vmcnt(24) in the first two waits of each non-first GEMM unit
# speedup vs baseline: 1.0167x; 1.0093x over previous
; #define PG8_STAGE(bufoff, gbase, voff) do { _Pragma("unroll") for (int _i = 0; _i < 2; ++_i) \
;         __builtin_amdgcn_global_load_lds((const unsigned*)((const char*)(gbase) + (voff)[_i]), (PG8_LAS unsigned*)(lds + (bufoff) + ldsw + _i * 8192), 16, 0, 0); } while (0)
; #define PG8_LDA(dst, b, h) do { _Pragma("unroll") for (int m = 0; m < 4; ++m) _Pragma("unroll") for (int k = 0; k < 2; ++k) dst[m][k] = *(const PG8_LAS bf16x8*)(lds + PG8_SA(b, h) + aoff + m * 2048 + k * 1024); } while (0)
; #define PG8_LDB(dst, b, h) do { _Pragma("unroll") for (int n = 0; n < 2; ++n) _Pragma("unroll") for (int k = 0; k < 2; ++k) dst[n][k] = *(const PG8_LAS bf16x8*)(lds + PG8_SB(b, h) + boff + n * 2048 + k * 1024); } while (0)
; #define PG8_MMA(ai, bj, At, Bt) do { __builtin_amdgcn_s_setprio(1); _Pragma("unroll") for (int m = 0; m < 4; ++m) _Pragma("unroll") for (int n = 0; n < 2; ++n) _Pragma("unroll") for (int k = 0; k < 2; ++k) \
;         acc[ai][bj][m][n] = __builtin_amdgcn_mfma_f32_16x16x32_bf16(Bt[n][k], At[m][k], acc[ai][bj][m][n], 0, 0, 0); __builtin_amdgcn_s_setprio(0); } while (0)
; #define PG8_WAIT_V(n) asm volatile("s_waitcnt vmcnt(" #n ")" ::: "memory")
; #define PG8_WAIT_L(n) asm volatile("s_waitcnt lgkmcnt(" #n ")" ::: "memory")
; #define PG8_BAR __builtin_amdgcn_s_barrier()
; #define PG8_SCHED __builtin_amdgcn_sched_barrier(0)
; template <class Epi, class Sched, bool ALIGN_EPI = false, bool SP2 = false>
; __device__ __forceinline__ void gemm_phase(PG8_LAS unsigned char* lds, const Gemm g, const Sched& S, const Epi& E) {
;     ...
;             const bool last = (t == nt - 2);
;             const char* a1 = cA + (size_t)(t + 1) * kstep;
;             const char* a2 = last ? nA : cA + (size_t)(t + 2) * kstep; const char* b2 = last ? nB : cB + (size_t)(t + 2) * kstep;
;             const char* a3 = a2 + kstep; const char* b3 = b2 + kstep;
;             if (last && has_next) S.a_ready(nxt);
;             if constexpr (SP2) {
;             PG8_LDB(B0, 0, 0); PG8_LDB(B1, 0, 1); PG8_SCHED; PG8_LDA(At, 0, 0); PG8_STAGE(PG8_SA(1, 1), a1 + hstep, voffA);
;             PG8_WAIT_V(8); PG8_WAIT_L(0); PG8_BAR; PG8_MMA(0, 0, At, B0); PG8_MMA(0, 1, At, B1); PG8_BAR; PG8_SCHED;
.LBB0_37:
	s_add_u32 s7, s56, 0xffe00080
	s_addc_u32 s58, s57, -1
	s_add_i32 s62, 0, 0x10000
	s_cmpk_eq_i32 s51, 0x7c
	s_cselect_b32 s61, s34, s58
	s_cselect_b32 s60, s35, s7
	v_add_u32_e32 v140, s62, v143
	s_cselect_b32 s59, s37, s49
	s_cselect_b32 s58, s45, s47
	s_add_i32 s7, 0, 0x14000
	ds_read_b128 v[146:149], v140
	ds_read_b128 v[150:153], v140 offset:1024
	ds_read_b128 v[154:157], v140 offset:2048
	ds_read_b128 v[158:161], v140 offset:3072
	v_add_u32_e32 v140, s7, v143
	ds_read_b128 v[162:165], v140
	ds_read_b128 v[166:169], v140 offset:1024
	ds_read_b128 v[170:173], v140 offset:2048
	ds_read_b128 v[174:177], v140 offset:3072
	v_lshl_add_u64 v[140:141], s[56:57], 0, v[136:137]
	s_add_i32 m0, s10, 0xc000
	ds_read_b128 v[178:181], v145
	ds_read_b128 v[182:185], v145 offset:1024
	ds_read_b128 v[186:189], v145 offset:2048
	ds_read_b128 v[190:193], v145 offset:3072
	ds_read_b128 v[214:217], v145 offset:4096
	ds_read_b128 v[220:223], v145 offset:5120
	ds_read_b128 v[224:227], v145 offset:6144
	ds_read_b128 v[228:231], v145 offset:7168
	global_load_lds_dwordx4 v[140:141], off
	v_lshl_add_u64 v[140:141], s[56:57], 0, v[138:139]
	s_add_i32 m0, s10, 0xe000
	s_nop 0
	global_load_lds_dwordx4 v[140:141], off
	s_cmp_lt_i32 s51, 0
	s_cbranch_scc0 .Lrx19_0_norm
	s_cmp_lt_u32 s33, 2
	s_cbranch_scc1 .Lrx19_0_norm
	s_waitcnt vmcnt(24)
	s_branch .Lrx19_0_join

; #define PG8_STAGE(bufoff, gbase, voff) do { _Pragma("unroll") for (int _i = 0; _i < 2; ++_i) \
;         __builtin_amdgcn_global_load_lds((const unsigned*)((const char*)(gbase) + (voff)[_i]), (PG8_LAS unsigned*)(lds + (bufoff) + ldsw + _i * 8192), 16, 0, 0); } while (0)
; #define PG8_LDA(dst, b, h) do { _Pragma("unroll") for (int m = 0; m < 4; ++m) _Pragma("unroll") for (int k = 0; k < 2; ++k) dst[m][k] = *(const PG8_LAS bf16x8*)(lds + PG8_SA(b, h) + aoff + m * 2048 + k * 1024); } while (0)
; #define PG8_MMA(ai, bj, At, Bt) do { __builtin_amdgcn_s_setprio(1); _Pragma("unroll") for (int m = 0; m < 4; ++m) _Pragma("unroll") for (int n = 0; n < 2; ++n) _Pragma("unroll") for (int k = 0; k < 2; ++k) \
;         acc[ai][bj][m][n] = __builtin_amdgcn_mfma_f32_16x16x32_bf16(Bt[n][k], At[m][k], acc[ai][bj][m][n], 0, 0, 0); __builtin_amdgcn_s_setprio(0); } while (0)
; #define PG8_WAIT_V(n) asm volatile("s_waitcnt vmcnt(" #n ")" ::: "memory")
; #define PG8_WAIT_L(n) asm volatile("s_waitcnt lgkmcnt(" #n ")" ::: "memory")
; #define PG8_BAR __builtin_amdgcn_s_barrier()
; #define PG8_SCHED __builtin_amdgcn_sched_barrier(0)
; template <class Epi, class Sched, bool ALIGN_EPI = false, bool SP2 = false>
; __device__ __forceinline__ void gemm_phase(PG8_LAS unsigned char* lds, const Gemm g, const Sched& S, const Epi& E) {
;     ...
;             PG8_WAIT_V(8); PG8_WAIT_L(0); PG8_BAR; PG8_MMA(0, 0, At, B0); PG8_MMA(0, 1, At, B1); PG8_BAR; PG8_SCHED;
;             PG8_LDA(At, 0, 1); PG8_STAGE(PG8_SB(0, 0), b2, voffB); PG8_STAGE(PG8_SB(0, 1), b2 + hstep, voffB); PG8_STAGE(PG8_SA(0, 0), a2, voffA);
.Lrx19_0_join:
	s_waitcnt lgkmcnt(0)
	s_barrier
	s_setprio 1
	s_waitcnt lgkmcnt(0)
	v_mfma_f32_16x16x32_bf16 v[124:127], v[146:149], v[178:181], v[124:127]
	v_mfma_f32_16x16x32_bf16 v[120:123], v[154:157], v[178:181], v[120:123]
	v_mfma_f32_16x16x32_bf16 v[116:119], v[146:149], v[186:189], v[116:119]
	v_mfma_f32_16x16x32_bf16 v[108:111], v[154:157], v[186:189], v[108:111]
	v_mfma_f32_16x16x32_bf16 v[100:103], v[146:149], v[214:217], v[100:103]
	v_mfma_f32_16x16x32_bf16 v[92:95], v[154:157], v[214:217], v[92:95]
	v_mfma_f32_16x16x32_bf16 v[84:87], v[146:149], v[224:227], v[84:87]
	v_mfma_f32_16x16x32_bf16 v[76:79], v[154:157], v[224:227], v[76:79]
	v_mfma_f32_16x16x32_bf16 v[124:127], v[150:153], v[182:185], v[124:127]
	v_mfma_f32_16x16x32_bf16 v[120:123], v[158:161], v[182:185], v[120:123]
	v_mfma_f32_16x16x32_bf16 v[116:119], v[150:153], v[190:193], v[116:119]
	v_mfma_f32_16x16x32_bf16 v[108:111], v[158:161], v[190:193], v[108:111]
	v_mfma_f32_16x16x32_bf16 v[100:103], v[150:153], v[220:223], v[100:103]
	v_mfma_f32_16x16x32_bf16 v[92:95], v[158:161], v[220:223], v[92:95]
	v_mfma_f32_16x16x32_bf16 v[84:87], v[150:153], v[228:231], v[84:87]
	v_mfma_f32_16x16x32_bf16 v[76:79], v[158:161], v[228:231], v[76:79]
	s_setprio 0
	s_setprio 1
	v_mfma_f32_16x16x32_bf16 v[112:115], v[162:165], v[178:181], v[112:115]
	v_mfma_f32_16x16x32_bf16 v[104:107], v[170:173], v[178:181], v[104:107]
	v_mfma_f32_16x16x32_bf16 v[96:99], v[162:165], v[186:189], v[96:99]
	v_mfma_f32_16x16x32_bf16 v[88:91], v[170:173], v[186:189], v[88:91]
	v_mfma_f32_16x16x32_bf16 v[80:83], v[162:165], v[214:217], v[80:83]
	v_mfma_f32_16x16x32_bf16 v[72:75], v[170:173], v[214:217], v[72:75]
	v_mfma_f32_16x16x32_bf16 v[68:71], v[162:165], v[224:227], v[68:71]
	v_mfma_f32_16x16x32_bf16 v[64:67], v[170:173], v[224:227], v[64:67]
	v_mfma_f32_16x16x32_bf16 v[112:115], v[166:169], v[182:185], v[112:115]
	v_mfma_f32_16x16x32_bf16 v[104:107], v[174:177], v[182:185], v[104:107]
	v_mfma_f32_16x16x32_bf16 v[96:99], v[166:169], v[190:193], v[96:99]
	v_mfma_f32_16x16x32_bf16 v[88:91], v[174:177], v[190:193], v[88:91]
	v_mfma_f32_16x16x32_bf16 v[80:83], v[166:169], v[220:223], v[80:83]
	v_mfma_f32_16x16x32_bf16 v[72:75], v[174:177], v[220:223], v[72:75]
	v_mfma_f32_16x16x32_bf16 v[68:71], v[166:169], v[228:231], v[68:71]
	v_mfma_f32_16x16x32_bf16 v[64:67], v[174:177], v[228:231], v[64:67]
	s_setprio 0
	s_barrier
	s_add_i32 s62, s62, s2
	v_lshl_add_u64 v[140:141], s[58:59], 0, v[128:129]
	s_mov_b32 m0, s62
	ds_read_b128 v[178:181], v145 offset:16384
	ds_read_b128 v[182:185], v145 offset:17408
	ds_read_b128 v[186:189], v145 offset:18432
	ds_read_b128 v[190:193], v145 offset:19456
	ds_read_b128 v[214:217], v145 offset:20480
	ds_read_b128 v[220:223], v145 offset:21504
	ds_read_b128 v[224:227], v145 offset:22528
	ds_read_b128 v[228:231], v145 offset:23552
	global_load_lds_dwordx4 v[140:141], off
	s_add_i32 m0, s62, 0x2000
	s_add_u32 s62, s58, 0x200000
	v_lshl_add_u64 v[206:207], s[58:59], 0, v[130:131]
	s_addc_u32 s63, s59, 0
	s_add_i32 s7, s7, s2
	global_load_lds_dwordx4 v[206:207], off
	v_lshl_add_u64 v[232:233], s[62:63], 0, v[128:129]
	s_mov_b32 m0, s7
	v_lshl_add_u64 v[234:235], s[60:61], 0, v[132:133]
	global_load_lds_dwordx4 v[232:233], off
	v_lshl_add_u64 v[232:233], s[62:63], 0, v[130:131]
	s_add_i32 m0, s7, 0x2000
	s_nop 0
	global_load_lds_dwordx4 v[232:233], off
	v_lshl_add_u64 v[232:233], s[60:61], 0, v[134:135]
	s_mov_b32 m0, s10
	s_nop 0
	global_load_lds_dwordx4 v[232:233], off
	s_mov_b32 m0, s17
	s_nop 0
	global_load_lds_dwordx4 v[234:235], off
	s_cmp_lt_i32 s51, 0
	s_cbranch_scc0 .Lrx19_1_norm
	s_cmp_lt_u32 s33, 2
	s_cbranch_scc1 .Lrx19_1_norm
	s_waitcnt vmcnt(24)
	s_branch .Lrx19_1_join

; #define PG8_STAGE(bufoff, gbase, voff) do { _Pragma("unroll") for (int _i = 0; _i < 2; ++_i) \
;         __builtin_amdgcn_global_load_lds((const unsigned*)((const char*)(gbase) + (voff)[_i]), (PG8_LAS unsigned*)(lds + (bufoff) + ldsw + _i * 8192), 16, 0, 0); } while (0)
; #define PG8_LDA(dst, b, h) do { _Pragma("unroll") for (int m = 0; m < 4; ++m) _Pragma("unroll") for (int k = 0; k < 2; ++k) dst[m][k] = *(const PG8_LAS bf16x8*)(lds + PG8_SA(b, h) + aoff + m * 2048 + k * 1024); } while (0)
; #define PG8_LDB(dst, b, h) do { _Pragma("unroll") for (int n = 0; n < 2; ++n) _Pragma("unroll") for (int k = 0; k < 2; ++k) dst[n][k] = *(const PG8_LAS bf16x8*)(lds + PG8_SB(b, h) + boff + n * 2048 + k * 1024); } while (0)
; #define PG8_MMA(ai, bj, At, Bt) do { __builtin_amdgcn_s_setprio(1); _Pragma("unroll") for (int m = 0; m < 4; ++m) _Pragma("unroll") for (int n = 0; n < 2; ++n) _Pragma("unroll") for (int k = 0; k < 2; ++k) \
;         acc[ai][bj][m][n] = __builtin_amdgcn_mfma_f32_16x16x32_bf16(Bt[n][k], At[m][k], acc[ai][bj][m][n], 0, 0, 0); __builtin_amdgcn_s_setprio(0); } while (0)
; #define PG8_WAIT_V(n) asm volatile("s_waitcnt vmcnt(" #n ")" ::: "memory")
; #define PG8_WAIT_L(n) asm volatile("s_waitcnt lgkmcnt(" #n ")" ::: "memory")
; #define PG8_BAR __builtin_amdgcn_s_barrier()
; #define PG8_SCHED __builtin_amdgcn_sched_barrier(0)
; template <class Epi, class Sched, bool ALIGN_EPI = false, bool SP2 = false>
; __device__ __forceinline__ void gemm_phase(PG8_LAS unsigned char* lds, const Gemm g, const Sched& S, const Epi& E) {
;     ...
;             PG8_WAIT_V(8); PG8_WAIT_L(0); PG8_BAR; PG8_MMA(1, 0, At, B0); PG8_MMA(1, 1, At, B1); PG8_BAR; PG8_SCHED;
;             PG8_LDB(B0, 1, 0); PG8_LDB(B1, 1, 1); PG8_SCHED; PG8_LDA(At, 1, 0); PG8_STAGE(PG8_SA(0, 1), a2 + hstep, voffA);
;             PG8_WAIT_V(8); PG8_WAIT_L(0); PG8_BAR; PG8_MMA(0, 0, At, B0); PG8_MMA(0, 1, At, B1); PG8_BAR; PG8_SCHED;
.Lrx19_1_join:
	s_waitcnt lgkmcnt(0)
	s_barrier
	s_setprio 1
	s_waitcnt lgkmcnt(0)
	v_mfma_f32_16x16x32_bf16 v[60:63], v[146:149], v[178:181], v[60:63]
	v_mfma_f32_16x16x32_bf16 v[56:59], v[154:157], v[178:181], v[56:59]
	v_mfma_f32_16x16x32_bf16 v[52:55], v[146:149], v[186:189], v[52:55]
	v_mfma_f32_16x16x32_bf16 v[44:47], v[154:157], v[186:189], v[44:47]
	v_mfma_f32_16x16x32_bf16 v[36:39], v[146:149], v[214:217], v[36:39]
	v_mfma_f32_16x16x32_bf16 v[28:31], v[154:157], v[214:217], v[28:31]
	v_mfma_f32_16x16x32_bf16 v[20:23], v[146:149], v[224:227], v[20:23]
	v_mfma_f32_16x16x32_bf16 v[12:15], v[154:157], v[224:227], v[12:15]
	v_mfma_f32_16x16x32_bf16 v[60:63], v[150:153], v[182:185], v[60:63]
	v_mfma_f32_16x16x32_bf16 v[56:59], v[158:161], v[182:185], v[56:59]
	v_mfma_f32_16x16x32_bf16 v[52:55], v[150:153], v[190:193], v[52:55]
	v_mfma_f32_16x16x32_bf16 v[44:47], v[158:161], v[190:193], v[44:47]
	v_mfma_f32_16x16x32_bf16 v[36:39], v[150:153], v[220:223], v[36:39]
	v_mfma_f32_16x16x32_bf16 v[28:31], v[158:161], v[220:223], v[28:31]
	v_mfma_f32_16x16x32_bf16 v[20:23], v[150:153], v[228:231], v[20:23]
	v_mfma_f32_16x16x32_bf16 v[12:15], v[158:161], v[228:231], v[12:15]
	s_setprio 0
	s_setprio 1
	v_mfma_f32_16x16x32_bf16 v[48:51], v[162:165], v[178:181], v[48:51]
	v_mfma_f32_16x16x32_bf16 v[40:43], v[170:173], v[178:181], v[40:43]
	v_mfma_f32_16x16x32_bf16 v[32:35], v[162:165], v[186:189], v[32:35]
	v_mfma_f32_16x16x32_bf16 v[24:27], v[170:173], v[186:189], v[24:27]
	v_mfma_f32_16x16x32_bf16 v[16:19], v[162:165], v[214:217], v[16:19]
	v_mfma_f32_16x16x32_bf16 v[8:11], v[170:173], v[214:217], v[8:11]
	v_mfma_f32_16x16x32_bf16 v[4:7], v[162:165], v[224:227], v[4:7]
	v_mfma_f32_16x16x32_bf16 v[0:3], v[170:173], v[224:227], v[0:3]
	v_mfma_f32_16x16x32_bf16 v[48:51], v[166:169], v[182:185], v[48:51]
	v_mfma_f32_16x16x32_bf16 v[40:43], v[174:177], v[182:185], v[40:43]
	v_mfma_f32_16x16x32_bf16 v[32:35], v[166:169], v[190:193], v[32:35]
	v_mfma_f32_16x16x32_bf16 v[24:27], v[174:177], v[190:193], v[24:27]
	v_mfma_f32_16x16x32_bf16 v[16:19], v[166:169], v[220:223], v[16:19]
	v_mfma_f32_16x16x32_bf16 v[8:11], v[174:177], v[220:223], v[8:11]
	v_mfma_f32_16x16x32_bf16 v[4:7], v[166:169], v[228:231], v[4:7]
	v_mfma_f32_16x16x32_bf16 v[0:3], v[174:177], v[228:231], v[0:3]
	s_setprio 0
	s_barrier
	s_add_i32 s7, 0, 0x18000
	s_add_i32 s62, 0, 0x1c000
	v_add_u32_e32 v158, s7, v143
	v_add_u32_e32 v174, s62, v143
	ds_read_b128 v[146:149], v158
	ds_read_b128 v[150:153], v158 offset:1024
	ds_read_b128 v[154:157], v158 offset:2048
	ds_read_b128 v[158:161], v158 offset:3072
	ds_read_b128 v[162:165], v174
	ds_read_b128 v[166:169], v174 offset:1024
	ds_read_b128 v[170:173], v174 offset:2048
	ds_read_b128 v[174:177], v174 offset:3072
	s_add_u32 s60, s60, 0x200000
	s_addc_u32 s61, s61, 0
	s_mov_b32 m0, s26
	v_lshl_add_u64 v[236:237], s[60:61], 0, v[134:135]
	ds_read_b128 v[178:181], v145 offset:32768
	ds_read_b128 v[182:185], v145 offset:33792
	ds_read_b128 v[186:189], v145 offset:34816
	ds_read_b128 v[190:193], v145 offset:35840
	ds_read_b128 v[214:217], v145 offset:36864
	ds_read_b128 v[220:223], v145 offset:37888
	ds_read_b128 v[224:227], v145 offset:38912
	ds_read_b128 v[228:231], v145 offset:39936
	global_load_lds_dwordx4 v[236:237], off
	v_lshl_add_u64 v[236:237], s[60:61], 0, v[132:133]
	s_mov_b32 m0, s27
	s_nop 0
	global_load_lds_dwordx4 v[236:237], off
	s_waitcnt vmcnt(8)
	s_waitcnt lgkmcnt(0)
	s_barrier
	s_setprio 1
	s_waitcnt lgkmcnt(0)
	v_mfma_f32_16x16x32_bf16 v[124:127], v[146:149], v[178:181], v[124:127]
	v_mfma_f32_16x16x32_bf16 v[120:123], v[154:157], v[178:181], v[120:123]
	v_mfma_f32_16x16x32_bf16 v[116:119], v[146:149], v[186:189], v[116:119]
	v_mfma_f32_16x16x32_bf16 v[108:111], v[154:157], v[186:189], v[108:111]
	v_mfma_f32_16x16x32_bf16 v[100:103], v[146:149], v[214:217], v[100:103]
	v_mfma_f32_16x16x32_bf16 v[92:95], v[154:157], v[214:217], v[92:95]
	v_mfma_f32_16x16x32_bf16 v[84:87], v[146:149], v[224:227], v[84:87]
	v_mfma_f32_16x16x32_bf16 v[76:79], v[154:157], v[224:227], v[76:79]
	v_mfma_f32_16x16x32_bf16 v[124:127], v[150:153], v[182:185], v[124:127]
	v_mfma_f32_16x16x32_bf16 v[120:123], v[158:161], v[182:185], v[120:123]
	v_mfma_f32_16x16x32_bf16 v[116:119], v[150:153], v[190:193], v[116:119]
	v_mfma_f32_16x16x32_bf16 v[108:111], v[158:161], v[190:193], v[108:111]
	v_mfma_f32_16x16x32_bf16 v[100:103], v[150:153], v[220:223], v[100:103]
	v_mfma_f32_16x16x32_bf16 v[92:95], v[158:161], v[220:223], v[92:95]
	v_mfma_f32_16x16x32_bf16 v[84:87], v[150:153], v[228:231], v[84:87]
	v_mfma_f32_16x16x32_bf16 v[76:79], v[158:161], v[228:231], v[76:79]
	s_setprio 0
	s_setprio 1
	v_mfma_f32_16x16x32_bf16 v[112:115], v[162:165], v[178:181], v[112:115]
	v_mfma_f32_16x16x32_bf16 v[104:107], v[170:173], v[178:181], v[104:107]
	v_mfma_f32_16x16x32_bf16 v[96:99], v[162:165], v[186:189], v[96:99]
	v_mfma_f32_16x16x32_bf16 v[88:91], v[170:173], v[186:189], v[88:91]
	v_mfma_f32_16x16x32_bf16 v[80:83], v[162:165], v[214:217], v[80:83]
	v_mfma_f32_16x16x32_bf16 v[72:75], v[170:173], v[214:217], v[72:75]
	v_mfma_f32_16x16x32_bf16 v[68:71], v[162:165], v[224:227], v[68:71]
	v_mfma_f32_16x16x32_bf16 v[64:67], v[170:173], v[224:227], v[64:67]
	v_mfma_f32_16x16x32_bf16 v[112:115], v[166:169], v[182:185], v[112:115]
	v_mfma_f32_16x16x32_bf16 v[104:107], v[174:177], v[182:185], v[104:107]
	v_mfma_f32_16x16x32_bf16 v[96:99], v[166:169], v[190:193], v[96:99]
	v_mfma_f32_16x16x32_bf16 v[88:91], v[174:177], v[190:193], v[88:91]
	v_mfma_f32_16x16x32_bf16 v[80:83], v[166:169], v[220:223], v[80:83]
	v_mfma_f32_16x16x32_bf16 v[72:75], v[174:177], v[220:223], v[72:75]
	v_mfma_f32_16x16x32_bf16 v[68:71], v[166:169], v[228:231], v[68:71]
	v_mfma_f32_16x16x32_bf16 v[64:67], v[174:177], v[228:231], v[64:67]
	s_setprio 0
	s_barrier
; #define PG8_STAGE(bufoff, gbase, voff) do { _Pragma("unroll") for (int _i = 0; _i < 2; ++_i) \
;         __builtin_amdgcn_global_load_lds((const unsigned*)((const char*)(gbase) + (voff)[_i]), (PG8_LAS unsigned*)(lds + (bufoff) + ldsw + _i * 8192), 16, 0, 0); } while (0)
; #define PG8_LDA(dst, b, h) do { _Pragma("unroll") for (int m = 0; m < 4; ++m) _Pragma("unroll") for (int k = 0; k < 2; ++k) dst[m][k] = *(const PG8_LAS bf16x8*)(lds + PG8_SA(b, h) + aoff + m * 2048 + k * 1024); } while (0)
; #define PG8_MMA(ai, bj, At, Bt) do { __builtin_amdgcn_s_setprio(1); _Pragma("unroll") for (int m = 0; m < 4; ++m) _Pragma("unroll") for (int n = 0; n < 2; ++n) _Pragma("unroll") for (int k = 0; k < 2; ++k) \
;         acc[ai][bj][m][n] = __builtin_amdgcn_mfma_f32_16x16x32_bf16(Bt[n][k], At[m][k], acc[ai][bj][m][n], 0, 0, 0); __builtin_amdgcn_s_setprio(0); } while (0)
; #define PG8_WAIT_V(n) asm volatile("s_waitcnt vmcnt(" #n ")" ::: "memory")
; #define PG8_WAIT_L(n) asm volatile("s_waitcnt lgkmcnt(" #n ")" ::: "memory")
; #define PG8_BAR __builtin_amdgcn_s_barrier()
; #define PG8_SCHED __builtin_amdgcn_sched_barrier(0)
; template <class Epi, class Sched, bool ALIGN_EPI = false, bool SP2 = false>
; __device__ __forceinline__ void gemm_phase(PG8_LAS unsigned char* lds, const Gemm g, const Sched& S, const Epi& E) {
;     ...
;             PG8_LDA(At, 1, 1); PG8_STAGE(PG8_SB(1, 0), b3, voffB); PG8_STAGE(PG8_SB(1, 1), b3 + hstep, voffB); PG8_STAGE(PG8_SA(1, 0), a3, voffA);
;             PG8_WAIT_V(8); PG8_WAIT_L(0); PG8_BAR; PG8_MMA(1, 0, At, B0); PG8_MMA(1, 1, At, B1); PG8_BAR; PG8_SCHED;
	s_add_i32 s7, s7, s2
	v_lshl_add_u64 v[140:141], v[140:141], 0, s[20:21]
	s_mov_b32 m0, s7
	ds_read_b128 v[178:181], v145 offset:49152
	ds_read_b128 v[182:185], v145 offset:50176
	ds_read_b128 v[186:189], v145 offset:51200
	ds_read_b128 v[190:193], v145 offset:52224
	ds_read_b128 v[214:217], v145 offset:53248
	ds_read_b128 v[220:223], v145 offset:54272
	ds_read_b128 v[224:227], v145 offset:55296
	ds_read_b128 v[228:231], v145 offset:56320
	global_load_lds_dwordx4 v[140:141], off
	s_add_i32 m0, s7, 0x2000
	s_add_u32 s58, s58, 0x200080
	v_lshl_add_u64 v[140:141], v[206:207], 0, s[20:21]
	s_addc_u32 s59, s59, 0
	s_add_i32 s7, s62, s2
	global_load_lds_dwordx4 v[140:141], off
	v_lshl_add_u64 v[140:141], s[58:59], 0, v[128:129]
	s_mov_b32 m0, s7
	s_nop 0
	global_load_lds_dwordx4 v[140:141], off
	v_lshl_add_u64 v[140:141], s[58:59], 0, v[130:131]
	s_add_i32 m0, s7, 0x2000
	s_nop 0
	global_load_lds_dwordx4 v[140:141], off
	v_lshl_add_u64 v[140:141], v[232:233], 0, s[20:21]
	s_mov_b32 m0, s28
	s_nop 0
	global_load_lds_dwordx4 v[140:141], off
	v_lshl_add_u64 v[140:141], v[234:235], 0, s[20:21]
	s_mov_b32 m0, s29
	s_nop 0
	global_load_lds_dwordx4 v[140:141], off
	s_waitcnt vmcnt(8)
	s_waitcnt lgkmcnt(0)
	s_barrier
	s_setprio 1
	s_waitcnt lgkmcnt(0)
	v_mfma_f32_16x16x32_bf16 v[60:63], v[146:149], v[178:181], v[60:63]
	v_mfma_f32_16x16x32_bf16 v[56:59], v[154:157], v[178:181], v[56:59]
	v_mfma_f32_16x16x32_bf16 v[52:55], v[146:149], v[186:189], v[52:55]
	v_mfma_f32_16x16x32_bf16 v[44:47], v[154:157], v[186:189], v[44:47]
	v_mfma_f32_16x16x32_bf16 v[36:39], v[146:149], v[214:217], v[36:39]
	v_mfma_f32_16x16x32_bf16 v[28:31], v[154:157], v[214:217], v[28:31]
	v_mfma_f32_16x16x32_bf16 v[20:23], v[146:149], v[224:227], v[20:23]
	v_mfma_f32_16x16x32_bf16 v[12:15], v[154:157], v[224:227], v[12:15]
	v_mfma_f32_16x16x32_bf16 v[60:63], v[150:153], v[182:185], v[60:63]
	v_mfma_f32_16x16x32_bf16 v[56:59], v[158:161], v[182:185], v[56:59]
	v_mfma_f32_16x16x32_bf16 v[52:55], v[150:153], v[190:193], v[52:55]
	v_mfma_f32_16x16x32_bf16 v[44:47], v[158:161], v[190:193], v[44:47]
	v_mfma_f32_16x16x32_bf16 v[36:39], v[150:153], v[220:223], v[36:39]
	v_mfma_f32_16x16x32_bf16 v[28:31], v[158:161], v[220:223], v[28:31]
	v_mfma_f32_16x16x32_bf16 v[20:23], v[150:153], v[228:231], v[20:23]
	v_mfma_f32_16x16x32_bf16 v[12:15], v[158:161], v[228:231], v[12:15]
	s_setprio 0
	s_setprio 1
	v_mfma_f32_16x16x32_bf16 v[48:51], v[162:165], v[178:181], v[48:51]
	v_mfma_f32_16x16x32_bf16 v[40:43], v[170:173], v[178:181], v[40:43]
	v_mfma_f32_16x16x32_bf16 v[32:35], v[162:165], v[186:189], v[32:35]
	v_mfma_f32_16x16x32_bf16 v[24:27], v[170:173], v[186:189], v[24:27]
	v_mfma_f32_16x16x32_bf16 v[16:19], v[162:165], v[214:217], v[16:19]
	v_mfma_f32_16x16x32_bf16 v[8:11], v[170:173], v[214:217], v[8:11]
	v_mfma_f32_16x16x32_bf16 v[4:7], v[162:165], v[224:227], v[4:7]
	v_mfma_f32_16x16x32_bf16 v[0:3], v[170:173], v[224:227], v[0:3]
	v_mfma_f32_16x16x32_bf16 v[48:51], v[166:169], v[182:185], v[48:51]
	v_mfma_f32_16x16x32_bf16 v[40:43], v[174:177], v[182:185], v[40:43]
	v_mfma_f32_16x16x32_bf16 v[32:35], v[166:169], v[190:193], v[32:35]
	v_mfma_f32_16x16x32_bf16 v[24:27], v[174:177], v[190:193], v[24:27]
	v_mfma_f32_16x16x32_bf16 v[16:19], v[166:169], v[220:223], v[16:19]
	v_mfma_f32_16x16x32_bf16 v[8:11], v[174:177], v[220:223], v[8:11]
	v_mfma_f32_16x16x32_bf16 v[4:7], v[166:169], v[228:231], v[4:7]
	v_mfma_f32_16x16x32_bf16 v[0:3], v[174:177], v[228:231], v[0:3]
	s_setprio 0
	s_barrier
	s_add_i32 s51, s51, 2
	s_add_u32 s56, s56, 0x100
	s_addc_u32 s57, s57, 0
	s_add_u32 s47, s47, 0x100
	s_addc_u32 s49, s49, 0
	s_cmpk_gt_u32 s51, 0x7d
	s_cbranch_scc0 .LBB0_37
	s_and_b64 vcc, exec, s[42:43]
	s_cbranch_vccz .LBB0_40
	s_barrier

; #define PG8_STAGE(bufoff, gbase, voff) do { _Pragma("unroll") for (int _i = 0; _i < 2; ++_i) \
;         __builtin_amdgcn_global_load_lds((const unsigned*)((const char*)(gbase) + (voff)[_i]), (PG8_LAS unsigned*)(lds + (bufoff) + ldsw + _i * 8192), 16, 0, 0); } while (0)
; #define PG8_LDA(dst, b, h) do { _Pragma("unroll") for (int m = 0; m < 4; ++m) _Pragma("unroll") for (int k = 0; k < 2; ++k) dst[m][k] = *(const PG8_LAS bf16x8*)(lds + PG8_SA(b, h) + aoff + m * 2048 + k * 1024); } while (0)
; #define PG8_LDB(dst, b, h) do { _Pragma("unroll") for (int n = 0; n < 2; ++n) _Pragma("unroll") for (int k = 0; k < 2; ++k) dst[n][k] = *(const PG8_LAS bf16x8*)(lds + PG8_SB(b, h) + boff + n * 2048 + k * 1024); } while (0)
; #define PG8_MMA(ai, bj, At, Bt) do { __builtin_amdgcn_s_setprio(1); _Pragma("unroll") for (int m = 0; m < 4; ++m) _Pragma("unroll") for (int n = 0; n < 2; ++n) _Pragma("unroll") for (int k = 0; k < 2; ++k) \
;         acc[ai][bj][m][n] = __builtin_amdgcn_mfma_f32_16x16x32_bf16(Bt[n][k], At[m][k], acc[ai][bj][m][n], 0, 0, 0); __builtin_amdgcn_s_setprio(0); } while (0)
; #define PG8_WAIT_V(n) asm volatile("s_waitcnt vmcnt(" #n ")" ::: "memory")
; #define PG8_WAIT_L(n) asm volatile("s_waitcnt lgkmcnt(" #n ")" ::: "memory")
; #define PG8_BAR __builtin_amdgcn_s_barrier()
; #define PG8_SCHED __builtin_amdgcn_sched_barrier(0)
; template <class Epi, class Sched, bool ALIGN_EPI = false, bool SP2 = false>
; __device__ __forceinline__ void gemm_phase(PG8_LAS unsigned char* lds, const Gemm g, const Sched& S, const Epi& E) {
;     ...
;             const bool last = (t == nt - 2);
;             const char* a1 = cA + (size_t)(t + 1) * kstep;
;             const char* a2 = last ? nA : cA + (size_t)(t + 2) * kstep; const char* b2 = last ? nB : cB + (size_t)(t + 2) * kstep;
;             const char* a3 = a2 + kstep; const char* b3 = b2 + kstep;
;             if (last && has_next) S.a_ready(nxt);
;             if constexpr (SP2) {
;             PG8_LDB(B0, 0, 0); PG8_LDB(B1, 0, 1); PG8_SCHED; PG8_LDA(At, 0, 0); PG8_STAGE(PG8_SA(1, 1), a1 + hstep, voffA);
;             PG8_WAIT_V(8); PG8_WAIT_L(0); PG8_BAR; PG8_MMA(0, 0, At, B0); PG8_MMA(0, 1, At, B1); PG8_BAR; PG8_SCHED;
.LBB0_59:
	s_add_u32 s7, s56, 0xfff80080
	s_addc_u32 s58, s57, -1
	s_add_i32 s62, 0, 0x10000
	s_cmp_eq_u32 s55, 28
	s_cselect_b32 s61, s34, s58
	s_cselect_b32 s60, s35, s7
	v_add_u32_e32 v140, s62, v143
	s_cselect_b32 s59, s37, s53
	s_cselect_b32 s58, s45, s47
	s_add_i32 s7, 0, 0x14000
	ds_read_b128 v[146:149], v140
	ds_read_b128 v[150:153], v140 offset:1024
	ds_read_b128 v[154:157], v140 offset:2048
	ds_read_b128 v[158:161], v140 offset:3072
	v_add_u32_e32 v140, s7, v143
	ds_read_b128 v[162:165], v140
	ds_read_b128 v[166:169], v140 offset:1024
	ds_read_b128 v[170:173], v140 offset:2048
	ds_read_b128 v[174:177], v140 offset:3072
	v_lshl_add_u64 v[140:141], s[56:57], 0, v[136:137]
	s_add_i32 m0, s10, 0xc000
	ds_read_b128 v[178:181], v145
	ds_read_b128 v[182:185], v145 offset:1024
	ds_read_b128 v[186:189], v145 offset:2048
	ds_read_b128 v[190:193], v145 offset:3072
	ds_read_b128 v[214:217], v145 offset:4096
	ds_read_b128 v[220:223], v145 offset:5120
	ds_read_b128 v[224:227], v145 offset:6144
	ds_read_b128 v[228:231], v145 offset:7168
	global_load_lds_dwordx4 v[140:141], off
	v_lshl_add_u64 v[140:141], s[56:57], 0, v[138:139]
	s_add_i32 m0, s10, 0xe000
	s_nop 0
	global_load_lds_dwordx4 v[140:141], off
	s_cmp_lt_i32 s55, 0
	s_cbranch_scc0 .Lrx18_0_norm
	s_cmp_lt_u32 s33, 2
	s_cbranch_scc1 .Lrx18_0_norm
	s_waitcnt vmcnt(24)
	s_branch .Lrx18_0_join

; #define PG8_STAGE(bufoff, gbase, voff) do { _Pragma("unroll") for (int _i = 0; _i < 2; ++_i) \
;         __builtin_amdgcn_global_load_lds((const unsigned*)((const char*)(gbase) + (voff)[_i]), (PG8_LAS unsigned*)(lds + (bufoff) + ldsw + _i * 8192), 16, 0, 0); } while (0)
; #define PG8_LDA(dst, b, h) do { _Pragma("unroll") for (int m = 0; m < 4; ++m) _Pragma("unroll") for (int k = 0; k < 2; ++k) dst[m][k] = *(const PG8_LAS bf16x8*)(lds + PG8_SA(b, h) + aoff + m * 2048 + k * 1024); } while (0)
; #define PG8_MMA(ai, bj, At, Bt) do { __builtin_amdgcn_s_setprio(1); _Pragma("unroll") for (int m = 0; m < 4; ++m) _Pragma("unroll") for (int n = 0; n < 2; ++n) _Pragma("unroll") for (int k = 0; k < 2; ++k) \
;         acc[ai][bj][m][n] = __builtin_amdgcn_mfma_f32_16x16x32_bf16(Bt[n][k], At[m][k], acc[ai][bj][m][n], 0, 0, 0); __builtin_amdgcn_s_setprio(0); } while (0)
; #define PG8_WAIT_V(n) asm volatile("s_waitcnt vmcnt(" #n ")" ::: "memory")
; #define PG8_WAIT_L(n) asm volatile("s_waitcnt lgkmcnt(" #n ")" ::: "memory")
; #define PG8_BAR __builtin_amdgcn_s_barrier()
; #define PG8_SCHED __builtin_amdgcn_sched_barrier(0)
; template <class Epi, class Sched, bool ALIGN_EPI = false, bool SP2 = false>
; __device__ __forceinline__ void gemm_phase(PG8_LAS unsigned char* lds, const Gemm g, const Sched& S, const Epi& E) {
;     ...
;             PG8_WAIT_V(8); PG8_WAIT_L(0); PG8_BAR; PG8_MMA(0, 0, At, B0); PG8_MMA(0, 1, At, B1); PG8_BAR; PG8_SCHED;
;             PG8_LDA(At, 0, 1); PG8_STAGE(PG8_SB(0, 0), b2, voffB); PG8_STAGE(PG8_SB(0, 1), b2 + hstep, voffB); PG8_STAGE(PG8_SA(0, 0), a2, voffA);
.Lrx18_0_join:
	s_waitcnt lgkmcnt(0)
	s_barrier
	s_setprio 1
	s_waitcnt lgkmcnt(0)
	v_mfma_f32_16x16x32_bf16 v[124:127], v[146:149], v[178:181], v[124:127]
	v_mfma_f32_16x16x32_bf16 v[120:123], v[154:157], v[178:181], v[120:123]
	v_mfma_f32_16x16x32_bf16 v[108:111], v[146:149], v[186:189], v[108:111]
	v_mfma_f32_16x16x32_bf16 v[104:107], v[154:157], v[186:189], v[104:107]
	v_mfma_f32_16x16x32_bf16 v[92:95], v[146:149], v[214:217], v[92:95]
	v_mfma_f32_16x16x32_bf16 v[88:91], v[154:157], v[214:217], v[88:91]
	v_mfma_f32_16x16x32_bf16 v[76:79], v[146:149], v[224:227], v[76:79]
	v_mfma_f32_16x16x32_bf16 v[72:75], v[154:157], v[224:227], v[72:75]
	v_mfma_f32_16x16x32_bf16 v[124:127], v[150:153], v[182:185], v[124:127]
	v_mfma_f32_16x16x32_bf16 v[120:123], v[158:161], v[182:185], v[120:123]
	v_mfma_f32_16x16x32_bf16 v[108:111], v[150:153], v[190:193], v[108:111]
	v_mfma_f32_16x16x32_bf16 v[104:107], v[158:161], v[190:193], v[104:107]
	v_mfma_f32_16x16x32_bf16 v[92:95], v[150:153], v[220:223], v[92:95]
	v_mfma_f32_16x16x32_bf16 v[88:91], v[158:161], v[220:223], v[88:91]
	v_mfma_f32_16x16x32_bf16 v[76:79], v[150:153], v[228:231], v[76:79]
	v_mfma_f32_16x16x32_bf16 v[72:75], v[158:161], v[228:231], v[72:75]
	s_setprio 0
	s_setprio 1
	v_mfma_f32_16x16x32_bf16 v[116:119], v[162:165], v[178:181], v[116:119]
	v_mfma_f32_16x16x32_bf16 v[112:115], v[170:173], v[178:181], v[112:115]
	v_mfma_f32_16x16x32_bf16 v[100:103], v[162:165], v[186:189], v[100:103]
	v_mfma_f32_16x16x32_bf16 v[96:99], v[170:173], v[186:189], v[96:99]
	v_mfma_f32_16x16x32_bf16 v[84:87], v[162:165], v[214:217], v[84:87]
	v_mfma_f32_16x16x32_bf16 v[80:83], v[170:173], v[214:217], v[80:83]
	v_mfma_f32_16x16x32_bf16 v[68:71], v[162:165], v[224:227], v[68:71]
	v_mfma_f32_16x16x32_bf16 v[64:67], v[170:173], v[224:227], v[64:67]
	v_mfma_f32_16x16x32_bf16 v[116:119], v[166:169], v[182:185], v[116:119]
	v_mfma_f32_16x16x32_bf16 v[112:115], v[174:177], v[182:185], v[112:115]
	v_mfma_f32_16x16x32_bf16 v[100:103], v[166:169], v[190:193], v[100:103]
	v_mfma_f32_16x16x32_bf16 v[96:99], v[174:177], v[190:193], v[96:99]
	v_mfma_f32_16x16x32_bf16 v[84:87], v[166:169], v[220:223], v[84:87]
	v_mfma_f32_16x16x32_bf16 v[80:83], v[174:177], v[220:223], v[80:83]
	v_mfma_f32_16x16x32_bf16 v[68:71], v[166:169], v[228:231], v[68:71]
	v_mfma_f32_16x16x32_bf16 v[64:67], v[174:177], v[228:231], v[64:67]
	s_setprio 0
	s_barrier
	s_add_i32 s62, s62, s2
	v_lshl_add_u64 v[140:141], s[58:59], 0, v[128:129]
	s_mov_b32 m0, s62
	ds_read_b128 v[178:181], v145 offset:16384
	ds_read_b128 v[182:185], v145 offset:17408
	ds_read_b128 v[186:189], v145 offset:18432
	ds_read_b128 v[190:193], v145 offset:19456
	ds_read_b128 v[214:217], v145 offset:20480
	ds_read_b128 v[220:223], v145 offset:21504
	ds_read_b128 v[224:227], v145 offset:22528
	ds_read_b128 v[228:231], v145 offset:23552
	global_load_lds_dwordx4 v[140:141], off
	s_add_i32 m0, s62, 0x2000
	s_add_u32 s62, s58, 0x20000
	v_lshl_add_u64 v[206:207], s[58:59], 0, v[130:131]
	s_addc_u32 s63, s59, 0
	s_add_i32 s7, s7, s2
	global_load_lds_dwordx4 v[206:207], off
	v_lshl_add_u64 v[232:233], s[62:63], 0, v[128:129]
	s_mov_b32 m0, s7
	v_lshl_add_u64 v[234:235], s[60:61], 0, v[132:133]
	global_load_lds_dwordx4 v[232:233], off
	v_lshl_add_u64 v[232:233], s[62:63], 0, v[130:131]
	s_add_i32 m0, s7, 0x2000
	s_nop 0
	global_load_lds_dwordx4 v[232:233], off
	v_lshl_add_u64 v[232:233], s[60:61], 0, v[134:135]
	s_mov_b32 m0, s10
	s_nop 0
	global_load_lds_dwordx4 v[232:233], off
	s_mov_b32 m0, s17
	s_nop 0
	global_load_lds_dwordx4 v[234:235], off
	s_cmp_lt_i32 s55, 0
	s_cbranch_scc0 .Lrx18_1_norm
	s_cmp_lt_u32 s33, 2
	s_cbranch_scc1 .Lrx18_1_norm
	s_waitcnt vmcnt(24)
	s_branch .Lrx18_1_join

; #define PG8_STAGE(bufoff, gbase, voff) do { _Pragma("unroll") for (int _i = 0; _i < 2; ++_i) \
;         __builtin_amdgcn_global_load_lds((const unsigned*)((const char*)(gbase) + (voff)[_i]), (PG8_LAS unsigned*)(lds + (bufoff) + ldsw + _i * 8192), 16, 0, 0); } while (0)
; #define PG8_LDA(dst, b, h) do { _Pragma("unroll") for (int m = 0; m < 4; ++m) _Pragma("unroll") for (int k = 0; k < 2; ++k) dst[m][k] = *(const PG8_LAS bf16x8*)(lds + PG8_SA(b, h) + aoff + m * 2048 + k * 1024); } while (0)
; #define PG8_LDB(dst, b, h) do { _Pragma("unroll") for (int n = 0; n < 2; ++n) _Pragma("unroll") for (int k = 0; k < 2; ++k) dst[n][k] = *(const PG8_LAS bf16x8*)(lds + PG8_SB(b, h) + boff + n * 2048 + k * 1024); } while (0)
; #define PG8_MMA(ai, bj, At, Bt) do { __builtin_amdgcn_s_setprio(1); _Pragma("unroll") for (int m = 0; m < 4; ++m) _Pragma("unroll") for (int n = 0; n < 2; ++n) _Pragma("unroll") for (int k = 0; k < 2; ++k) \
;         acc[ai][bj][m][n] = __builtin_amdgcn_mfma_f32_16x16x32_bf16(Bt[n][k], At[m][k], acc[ai][bj][m][n], 0, 0, 0); __builtin_amdgcn_s_setprio(0); } while (0)
; #define PG8_WAIT_V(n) asm volatile("s_waitcnt vmcnt(" #n ")" ::: "memory")
; #define PG8_WAIT_L(n) asm volatile("s_waitcnt lgkmcnt(" #n ")" ::: "memory")
; #define PG8_BAR __builtin_amdgcn_s_barrier()
; #define PG8_SCHED __builtin_amdgcn_sched_barrier(0)
; template <class Epi, class Sched, bool ALIGN_EPI = false, bool SP2 = false>
; __device__ __forceinline__ void gemm_phase(PG8_LAS unsigned char* lds, const Gemm g, const Sched& S, const Epi& E) {
;     ...
;             PG8_WAIT_V(8); PG8_WAIT_L(0); PG8_BAR; PG8_MMA(1, 0, At, B0); PG8_MMA(1, 1, At, B1); PG8_BAR; PG8_SCHED;
;             PG8_LDB(B0, 1, 0); PG8_LDB(B1, 1, 1); PG8_SCHED; PG8_LDA(At, 1, 0); PG8_STAGE(PG8_SA(0, 1), a2 + hstep, voffA);
;             PG8_WAIT_V(8); PG8_WAIT_L(0); PG8_BAR; PG8_MMA(0, 0, At, B0); PG8_MMA(0, 1, At, B1); PG8_BAR; PG8_SCHED;
.Lrx18_1_join:
	s_waitcnt lgkmcnt(0)
	s_barrier
	s_setprio 1
	s_waitcnt lgkmcnt(0)
	v_mfma_f32_16x16x32_bf16 v[60:63], v[146:149], v[178:181], v[60:63]
	v_mfma_f32_16x16x32_bf16 v[56:59], v[154:157], v[178:181], v[56:59]
	v_mfma_f32_16x16x32_bf16 v[44:47], v[146:149], v[186:189], v[44:47]
	v_mfma_f32_16x16x32_bf16 v[40:43], v[154:157], v[186:189], v[40:43]
	v_mfma_f32_16x16x32_bf16 v[28:31], v[146:149], v[214:217], v[28:31]
	v_mfma_f32_16x16x32_bf16 v[24:27], v[154:157], v[214:217], v[24:27]
	v_mfma_f32_16x16x32_bf16 v[12:15], v[146:149], v[224:227], v[12:15]
	v_mfma_f32_16x16x32_bf16 v[8:11], v[154:157], v[224:227], v[8:11]
	v_mfma_f32_16x16x32_bf16 v[60:63], v[150:153], v[182:185], v[60:63]
	v_mfma_f32_16x16x32_bf16 v[56:59], v[158:161], v[182:185], v[56:59]
	v_mfma_f32_16x16x32_bf16 v[44:47], v[150:153], v[190:193], v[44:47]
	v_mfma_f32_16x16x32_bf16 v[40:43], v[158:161], v[190:193], v[40:43]
	v_mfma_f32_16x16x32_bf16 v[28:31], v[150:153], v[220:223], v[28:31]
	v_mfma_f32_16x16x32_bf16 v[24:27], v[158:161], v[220:223], v[24:27]
	v_mfma_f32_16x16x32_bf16 v[12:15], v[150:153], v[228:231], v[12:15]
	v_mfma_f32_16x16x32_bf16 v[8:11], v[158:161], v[228:231], v[8:11]
	s_setprio 0
	s_setprio 1
	v_mfma_f32_16x16x32_bf16 v[52:55], v[162:165], v[178:181], v[52:55]
	v_mfma_f32_16x16x32_bf16 v[48:51], v[170:173], v[178:181], v[48:51]
	v_mfma_f32_16x16x32_bf16 v[36:39], v[162:165], v[186:189], v[36:39]
	v_mfma_f32_16x16x32_bf16 v[32:35], v[170:173], v[186:189], v[32:35]
	v_mfma_f32_16x16x32_bf16 v[20:23], v[162:165], v[214:217], v[20:23]
	v_mfma_f32_16x16x32_bf16 v[16:19], v[170:173], v[214:217], v[16:19]
	v_mfma_f32_16x16x32_bf16 v[4:7], v[162:165], v[224:227], v[4:7]
	v_mfma_f32_16x16x32_bf16 v[0:3], v[170:173], v[224:227], v[0:3]
	v_mfma_f32_16x16x32_bf16 v[52:55], v[166:169], v[182:185], v[52:55]
	v_mfma_f32_16x16x32_bf16 v[48:51], v[174:177], v[182:185], v[48:51]
	v_mfma_f32_16x16x32_bf16 v[36:39], v[166:169], v[190:193], v[36:39]
	v_mfma_f32_16x16x32_bf16 v[32:35], v[174:177], v[190:193], v[32:35]
	v_mfma_f32_16x16x32_bf16 v[20:23], v[166:169], v[220:223], v[20:23]
	v_mfma_f32_16x16x32_bf16 v[16:19], v[174:177], v[220:223], v[16:19]
	v_mfma_f32_16x16x32_bf16 v[4:7], v[166:169], v[228:231], v[4:7]
	v_mfma_f32_16x16x32_bf16 v[0:3], v[174:177], v[228:231], v[0:3]
	s_setprio 0
	s_barrier
	s_add_i32 s7, 0, 0x18000
	s_add_i32 s62, 0, 0x1c000
	v_add_u32_e32 v158, s7, v143
	v_add_u32_e32 v174, s62, v143
	ds_read_b128 v[146:149], v158
	ds_read_b128 v[150:153], v158 offset:1024
	ds_read_b128 v[154:157], v158 offset:2048
	ds_read_b128 v[158:161], v158 offset:3072
	ds_read_b128 v[162:165], v174
	ds_read_b128 v[166:169], v174 offset:1024
	ds_read_b128 v[170:173], v174 offset:2048
	ds_read_b128 v[174:177], v174 offset:3072
	s_add_u32 s60, s60, 0x80000
	s_addc_u32 s61, s61, 0
	s_mov_b32 m0, s26
	v_lshl_add_u64 v[236:237], s[60:61], 0, v[134:135]
	ds_read_b128 v[178:181], v145 offset:32768
	ds_read_b128 v[182:185], v145 offset:33792
	ds_read_b128 v[186:189], v145 offset:34816
	ds_read_b128 v[190:193], v145 offset:35840
	ds_read_b128 v[214:217], v145 offset:36864
	ds_read_b128 v[220:223], v145 offset:37888
	ds_read_b128 v[224:227], v145 offset:38912
	ds_read_b128 v[228:231], v145 offset:39936
	global_load_lds_dwordx4 v[236:237], off
	v_lshl_add_u64 v[236:237], s[60:61], 0, v[132:133]
	s_mov_b32 m0, s27
	s_nop 0
	global_load_lds_dwordx4 v[236:237], off
	s_waitcnt vmcnt(8)
	s_waitcnt lgkmcnt(0)
	s_barrier
	s_setprio 1
	s_waitcnt lgkmcnt(0)
	v_mfma_f32_16x16x32_bf16 v[124:127], v[146:149], v[178:181], v[124:127]
	v_mfma_f32_16x16x32_bf16 v[120:123], v[154:157], v[178:181], v[120:123]
	v_mfma_f32_16x16x32_bf16 v[108:111], v[146:149], v[186:189], v[108:111]
	v_mfma_f32_16x16x32_bf16 v[104:107], v[154:157], v[186:189], v[104:107]
	v_mfma_f32_16x16x32_bf16 v[92:95], v[146:149], v[214:217], v[92:95]
	v_mfma_f32_16x16x32_bf16 v[88:91], v[154:157], v[214:217], v[88:91]
	v_mfma_f32_16x16x32_bf16 v[76:79], v[146:149], v[224:227], v[76:79]
	v_mfma_f32_16x16x32_bf16 v[72:75], v[154:157], v[224:227], v[72:75]
	v_mfma_f32_16x16x32_bf16 v[124:127], v[150:153], v[182:185], v[124:127]
	v_mfma_f32_16x16x32_bf16 v[120:123], v[158:161], v[182:185], v[120:123]
	v_mfma_f32_16x16x32_bf16 v[108:111], v[150:153], v[190:193], v[108:111]
	v_mfma_f32_16x16x32_bf16 v[104:107], v[158:161], v[190:193], v[104:107]
	v_mfma_f32_16x16x32_bf16 v[92:95], v[150:153], v[220:223], v[92:95]
	v_mfma_f32_16x16x32_bf16 v[88:91], v[158:161], v[220:223], v[88:91]
	v_mfma_f32_16x16x32_bf16 v[76:79], v[150:153], v[228:231], v[76:79]
	v_mfma_f32_16x16x32_bf16 v[72:75], v[158:161], v[228:231], v[72:75]
	s_setprio 0
	s_setprio 1
	v_mfma_f32_16x16x32_bf16 v[116:119], v[162:165], v[178:181], v[116:119]
	v_mfma_f32_16x16x32_bf16 v[112:115], v[170:173], v[178:181], v[112:115]
	v_mfma_f32_16x16x32_bf16 v[100:103], v[162:165], v[186:189], v[100:103]
	v_mfma_f32_16x16x32_bf16 v[96:99], v[170:173], v[186:189], v[96:99]
	v_mfma_f32_16x16x32_bf16 v[84:87], v[162:165], v[214:217], v[84:87]
	v_mfma_f32_16x16x32_bf16 v[80:83], v[170:173], v[214:217], v[80:83]
	v_mfma_f32_16x16x32_bf16 v[68:71], v[162:165], v[224:227], v[68:71]
	v_mfma_f32_16x16x32_bf16 v[64:67], v[170:173], v[224:227], v[64:67]
	v_mfma_f32_16x16x32_bf16 v[116:119], v[166:169], v[182:185], v[116:119]
	v_mfma_f32_16x16x32_bf16 v[112:115], v[174:177], v[182:185], v[112:115]
	v_mfma_f32_16x16x32_bf16 v[100:103], v[166:169], v[190:193], v[100:103]
	v_mfma_f32_16x16x32_bf16 v[96:99], v[174:177], v[190:193], v[96:99]
	v_mfma_f32_16x16x32_bf16 v[84:87], v[166:169], v[220:223], v[84:87]
	v_mfma_f32_16x16x32_bf16 v[80:83], v[174:177], v[220:223], v[80:83]
	v_mfma_f32_16x16x32_bf16 v[68:71], v[166:169], v[228:231], v[68:71]
	v_mfma_f32_16x16x32_bf16 v[64:67], v[174:177], v[228:231], v[64:67]
	s_setprio 0
	s_barrier
; #define PG8_STAGE(bufoff, gbase, voff) do { _Pragma("unroll") for (int _i = 0; _i < 2; ++_i) \
;         __builtin_amdgcn_global_load_lds((const unsigned*)((const char*)(gbase) + (voff)[_i]), (PG8_LAS unsigned*)(lds + (bufoff) + ldsw + _i * 8192), 16, 0, 0); } while (0)
; #define PG8_LDA(dst, b, h) do { _Pragma("unroll") for (int m = 0; m < 4; ++m) _Pragma("unroll") for (int k = 0; k < 2; ++k) dst[m][k] = *(const PG8_LAS bf16x8*)(lds + PG8_SA(b, h) + aoff + m * 2048 + k * 1024); } while (0)
; #define PG8_MMA(ai, bj, At, Bt) do { __builtin_amdgcn_s_setprio(1); _Pragma("unroll") for (int m = 0; m < 4; ++m) _Pragma("unroll") for (int n = 0; n < 2; ++n) _Pragma("unroll") for (int k = 0; k < 2; ++k) \
;         acc[ai][bj][m][n] = __builtin_amdgcn_mfma_f32_16x16x32_bf16(Bt[n][k], At[m][k], acc[ai][bj][m][n], 0, 0, 0); __builtin_amdgcn_s_setprio(0); } while (0)
; #define PG8_WAIT_V(n) asm volatile("s_waitcnt vmcnt(" #n ")" ::: "memory")
; #define PG8_WAIT_L(n) asm volatile("s_waitcnt lgkmcnt(" #n ")" ::: "memory")
; #define PG8_BAR __builtin_amdgcn_s_barrier()
; #define PG8_SCHED __builtin_amdgcn_sched_barrier(0)
; template <class Epi, class Sched, bool ALIGN_EPI = false, bool SP2 = false>
; __device__ __forceinline__ void gemm_phase(PG8_LAS unsigned char* lds, const Gemm g, const Sched& S, const Epi& E) {
;     ...
;             PG8_LDA(At, 1, 1); PG8_STAGE(PG8_SB(1, 0), b3, voffB); PG8_STAGE(PG8_SB(1, 1), b3 + hstep, voffB); PG8_STAGE(PG8_SA(1, 0), a3, voffA);
;             PG8_WAIT_V(8); PG8_WAIT_L(0); PG8_BAR; PG8_MMA(1, 0, At, B0); PG8_MMA(1, 1, At, B1); PG8_BAR; PG8_SCHED;
	s_add_i32 s7, s7, s2
	v_lshl_add_u64 v[140:141], v[140:141], 0, s[20:21]
	s_mov_b32 m0, s7
	ds_read_b128 v[178:181], v145 offset:49152
	ds_read_b128 v[182:185], v145 offset:50176
	ds_read_b128 v[186:189], v145 offset:51200
	ds_read_b128 v[190:193], v145 offset:52224
	ds_read_b128 v[214:217], v145 offset:53248
	ds_read_b128 v[220:223], v145 offset:54272
	ds_read_b128 v[224:227], v145 offset:55296
	ds_read_b128 v[228:231], v145 offset:56320
	global_load_lds_dwordx4 v[140:141], off
	s_add_i32 m0, s7, 0x2000
	s_add_u32 s58, s58, 0x20080
	v_lshl_add_u64 v[140:141], v[206:207], 0, s[20:21]
	s_addc_u32 s59, s59, 0
	s_add_i32 s7, s62, s2
	global_load_lds_dwordx4 v[140:141], off
	v_lshl_add_u64 v[140:141], s[58:59], 0, v[128:129]
	s_mov_b32 m0, s7
	s_nop 0
	global_load_lds_dwordx4 v[140:141], off
	v_lshl_add_u64 v[140:141], s[58:59], 0, v[130:131]
	s_add_i32 m0, s7, 0x2000
	s_nop 0
	global_load_lds_dwordx4 v[140:141], off
	v_lshl_add_u64 v[140:141], v[232:233], 0, s[20:21]
	s_mov_b32 m0, s28
	s_nop 0
	global_load_lds_dwordx4 v[140:141], off
	v_lshl_add_u64 v[140:141], v[234:235], 0, s[20:21]
	s_mov_b32 m0, s29
	s_nop 0
	global_load_lds_dwordx4 v[140:141], off
	s_waitcnt vmcnt(8)
	s_waitcnt lgkmcnt(0)
	s_barrier
	s_setprio 1
	s_waitcnt lgkmcnt(0)
	v_mfma_f32_16x16x32_bf16 v[60:63], v[146:149], v[178:181], v[60:63]
	v_mfma_f32_16x16x32_bf16 v[56:59], v[154:157], v[178:181], v[56:59]
	v_mfma_f32_16x16x32_bf16 v[44:47], v[146:149], v[186:189], v[44:47]
	v_mfma_f32_16x16x32_bf16 v[40:43], v[154:157], v[186:189], v[40:43]
	v_mfma_f32_16x16x32_bf16 v[28:31], v[146:149], v[214:217], v[28:31]
	v_mfma_f32_16x16x32_bf16 v[24:27], v[154:157], v[214:217], v[24:27]
	v_mfma_f32_16x16x32_bf16 v[12:15], v[146:149], v[224:227], v[12:15]
	v_mfma_f32_16x16x32_bf16 v[8:11], v[154:157], v[224:227], v[8:11]
	v_mfma_f32_16x16x32_bf16 v[60:63], v[150:153], v[182:185], v[60:63]
	v_mfma_f32_16x16x32_bf16 v[56:59], v[158:161], v[182:185], v[56:59]
	v_mfma_f32_16x16x32_bf16 v[44:47], v[150:153], v[190:193], v[44:47]
	v_mfma_f32_16x16x32_bf16 v[40:43], v[158:161], v[190:193], v[40:43]
	v_mfma_f32_16x16x32_bf16 v[28:31], v[150:153], v[220:223], v[28:31]
	v_mfma_f32_16x16x32_bf16 v[24:27], v[158:161], v[220:223], v[24:27]
	v_mfma_f32_16x16x32_bf16 v[12:15], v[150:153], v[228:231], v[12:15]
	v_mfma_f32_16x16x32_bf16 v[8:11], v[158:161], v[228:231], v[8:11]
	s_setprio 0
	s_setprio 1
	v_mfma_f32_16x16x32_bf16 v[52:55], v[162:165], v[178:181], v[52:55]
	v_mfma_f32_16x16x32_bf16 v[48:51], v[170:173], v[178:181], v[48:51]
	v_mfma_f32_16x16x32_bf16 v[36:39], v[162:165], v[186:189], v[36:39]
	v_mfma_f32_16x16x32_bf16 v[32:35], v[170:173], v[186:189], v[32:35]
	v_mfma_f32_16x16x32_bf16 v[20:23], v[162:165], v[214:217], v[20:23]
	v_mfma_f32_16x16x32_bf16 v[16:19], v[170:173], v[214:217], v[16:19]
	v_mfma_f32_16x16x32_bf16 v[4:7], v[162:165], v[224:227], v[4:7]
	v_mfma_f32_16x16x32_bf16 v[0:3], v[170:173], v[224:227], v[0:3]
	v_mfma_f32_16x16x32_bf16 v[52:55], v[166:169], v[182:185], v[52:55]
	v_mfma_f32_16x16x32_bf16 v[48:51], v[174:177], v[182:185], v[48:51]
	v_mfma_f32_16x16x32_bf16 v[36:39], v[166:169], v[190:193], v[36:39]
	v_mfma_f32_16x16x32_bf16 v[32:35], v[174:177], v[190:193], v[32:35]
	v_mfma_f32_16x16x32_bf16 v[20:23], v[166:169], v[220:223], v[20:23]
	v_mfma_f32_16x16x32_bf16 v[16:19], v[174:177], v[220:223], v[16:19]
	v_mfma_f32_16x16x32_bf16 v[4:7], v[166:169], v[228:231], v[4:7]
	v_mfma_f32_16x16x32_bf16 v[0:3], v[174:177], v[228:231], v[0:3]
	s_setprio 0
	s_barrier
	s_add_i32 s55, s55, 2
	s_add_u32 s56, s56, 0x100
	s_addc_u32 s57, s57, 0
	s_add_u32 s47, s47, 0x100
	s_addc_u32 s53, s53, 0
	s_cmp_gt_u32 s55, 29
	s_cbranch_scc0 .LBB0_59
	s_and_b64 vcc, exec, s[42:43]
	s_cbranch_vccz .LBB0_62
	s_barrier

; #define PG8_STAGE(bufoff, gbase, voff) do { _Pragma("unroll") for (int _i = 0; _i < 2; ++_i) \
;         __builtin_amdgcn_global_load_lds((const unsigned*)((const char*)(gbase) + (voff)[_i]), (PG8_LAS unsigned*)(lds + (bufoff) + ldsw + _i * 8192), 16, 0, 0); } while (0)
; #define PG8_LDA(dst, b, h) do { _Pragma("unroll") for (int m = 0; m < 4; ++m) _Pragma("unroll") for (int k = 0; k < 2; ++k) dst[m][k] = *(const PG8_LAS bf16x8*)(lds + PG8_SA(b, h) + aoff + m * 2048 + k * 1024); } while (0)
; #define PG8_LDB(dst, b, h) do { _Pragma("unroll") for (int n = 0; n < 2; ++n) _Pragma("unroll") for (int k = 0; k < 2; ++k) dst[n][k] = *(const PG8_LAS bf16x8*)(lds + PG8_SB(b, h) + boff + n * 2048 + k * 1024); } while (0)
; #define PG8_MMA(ai, bj, At, Bt) do { __builtin_amdgcn_s_setprio(1); _Pragma("unroll") for (int m = 0; m < 4; ++m) _Pragma("unroll") for (int n = 0; n < 2; ++n) _Pragma("unroll") for (int k = 0; k < 2; ++k) \
;         acc[ai][bj][m][n] = __builtin_amdgcn_mfma_f32_16x16x32_bf16(Bt[n][k], At[m][k], acc[ai][bj][m][n], 0, 0, 0); __builtin_amdgcn_s_setprio(0); } while (0)
; #define PG8_WAIT_V(n) asm volatile("s_waitcnt vmcnt(" #n ")" ::: "memory")
; #define PG8_WAIT_L(n) asm volatile("s_waitcnt lgkmcnt(" #n ")" ::: "memory")
; #define PG8_BAR __builtin_amdgcn_s_barrier()
; #define PG8_SCHED __builtin_amdgcn_sched_barrier(0)
; template <class Epi, class Sched, bool ALIGN_EPI = false, bool SP2 = false>
; __device__ __forceinline__ void gemm_phase(PG8_LAS unsigned char* lds, const Gemm g, const Sched& S, const Epi& E) {
;     ...
;             const bool last = (t == nt - 2);
;             const char* a1 = cA + (size_t)(t + 1) * kstep;
;             const char* a2 = last ? nA : cA + (size_t)(t + 2) * kstep; const char* b2 = last ? nB : cB + (size_t)(t + 2) * kstep;
;             const char* a3 = a2 + kstep; const char* b3 = b2 + kstep;
;             if (last && has_next) S.a_ready(nxt);
;             if constexpr (SP2) {
;             PG8_LDB(B0, 0, 0); PG8_LDB(B1, 0, 1); PG8_SCHED; PG8_LDA(At, 0, 0); PG8_STAGE(PG8_SA(1, 1), a1 + hstep, voffA);
;             PG8_WAIT_V(8); PG8_WAIT_L(0); PG8_BAR; PG8_MMA(0, 0, At, B0); PG8_MMA(0, 1, At, B1); PG8_BAR; PG8_SCHED;
.LBB0_96:
	s_add_u32 s7, s54, 0xfff80080
	s_addc_u32 s56, s55, -1
	s_add_i32 s60, 0, 0x10000
	s_cmp_eq_u32 s49, 28
	s_cselect_b32 s59, s34, s56
	s_cselect_b32 s58, s35, s7
	v_add_u32_e32 v140, s60, v143
	s_cselect_b32 s57, s37, s47
	s_cselect_b32 s56, s43, s45
	s_add_i32 s7, 0, 0x14000
	ds_read_b128 v[146:149], v140
	ds_read_b128 v[150:153], v140 offset:1024
	ds_read_b128 v[154:157], v140 offset:2048
	ds_read_b128 v[158:161], v140 offset:3072
	v_add_u32_e32 v140, s7, v143
	ds_read_b128 v[162:165], v140
	ds_read_b128 v[166:169], v140 offset:1024
	ds_read_b128 v[170:173], v140 offset:2048
	ds_read_b128 v[174:177], v140 offset:3072
	v_lshl_add_u64 v[140:141], s[54:55], 0, v[136:137]
	s_add_i32 m0, s10, 0xc000
	ds_read_b128 v[178:181], v145
	ds_read_b128 v[182:185], v145 offset:1024
	ds_read_b128 v[186:189], v145 offset:2048
	ds_read_b128 v[190:193], v145 offset:3072
	ds_read_b128 v[214:217], v145 offset:4096
	ds_read_b128 v[220:223], v145 offset:5120
	ds_read_b128 v[224:227], v145 offset:6144
	ds_read_b128 v[228:231], v145 offset:7168
	global_load_lds_dwordx4 v[140:141], off
	v_lshl_add_u64 v[140:141], s[54:55], 0, v[138:139]
	s_add_i32 m0, s10, 0xe000
	s_nop 0
	global_load_lds_dwordx4 v[140:141], off
	s_cmp_lt_i32 s49, 0
	s_cbranch_scc0 .Lrx16_0_norm
	s_cmp_lt_u32 s33, 2
	s_cbranch_scc1 .Lrx16_0_norm
	s_waitcnt vmcnt(24)
	s_branch .Lrx16_0_join

; #define PG8_STAGE(bufoff, gbase, voff) do { _Pragma("unroll") for (int _i = 0; _i < 2; ++_i) \
;         __builtin_amdgcn_global_load_lds((const unsigned*)((const char*)(gbase) + (voff)[_i]), (PG8_LAS unsigned*)(lds + (bufoff) + ldsw + _i * 8192), 16, 0, 0); } while (0)
; #define PG8_LDA(dst, b, h) do { _Pragma("unroll") for (int m = 0; m < 4; ++m) _Pragma("unroll") for (int k = 0; k < 2; ++k) dst[m][k] = *(const PG8_LAS bf16x8*)(lds + PG8_SA(b, h) + aoff + m * 2048 + k * 1024); } while (0)
; #define PG8_MMA(ai, bj, At, Bt) do { __builtin_amdgcn_s_setprio(1); _Pragma("unroll") for (int m = 0; m < 4; ++m) _Pragma("unroll") for (int n = 0; n < 2; ++n) _Pragma("unroll") for (int k = 0; k < 2; ++k) \
;         acc[ai][bj][m][n] = __builtin_amdgcn_mfma_f32_16x16x32_bf16(Bt[n][k], At[m][k], acc[ai][bj][m][n], 0, 0, 0); __builtin_amdgcn_s_setprio(0); } while (0)
; #define PG8_WAIT_V(n) asm volatile("s_waitcnt vmcnt(" #n ")" ::: "memory")
; #define PG8_WAIT_L(n) asm volatile("s_waitcnt lgkmcnt(" #n ")" ::: "memory")
; #define PG8_BAR __builtin_amdgcn_s_barrier()
; #define PG8_SCHED __builtin_amdgcn_sched_barrier(0)
; template <class Epi, class Sched, bool ALIGN_EPI = false, bool SP2 = false>
; __device__ __forceinline__ void gemm_phase(PG8_LAS unsigned char* lds, const Gemm g, const Sched& S, const Epi& E) {
;     ...
;             PG8_WAIT_V(8); PG8_WAIT_L(0); PG8_BAR; PG8_MMA(0, 0, At, B0); PG8_MMA(0, 1, At, B1); PG8_BAR; PG8_SCHED;
;             PG8_LDA(At, 0, 1); PG8_STAGE(PG8_SB(0, 0), b2, voffB); PG8_STAGE(PG8_SB(0, 1), b2 + hstep, voffB); PG8_STAGE(PG8_SA(0, 0), a2, voffA);
.Lrx16_0_join:
	s_waitcnt lgkmcnt(0)
	s_barrier
	s_setprio 1
	s_waitcnt lgkmcnt(0)
	v_mfma_f32_16x16x32_bf16 v[124:127], v[146:149], v[178:181], v[124:127]
	v_mfma_f32_16x16x32_bf16 v[120:123], v[154:157], v[178:181], v[120:123]
	v_mfma_f32_16x16x32_bf16 v[116:119], v[146:149], v[186:189], v[116:119]
	v_mfma_f32_16x16x32_bf16 v[108:111], v[154:157], v[186:189], v[108:111]
	v_mfma_f32_16x16x32_bf16 v[100:103], v[146:149], v[214:217], v[100:103]
	v_mfma_f32_16x16x32_bf16 v[92:95], v[154:157], v[214:217], v[92:95]
	v_mfma_f32_16x16x32_bf16 v[84:87], v[146:149], v[224:227], v[84:87]
	v_mfma_f32_16x16x32_bf16 v[76:79], v[154:157], v[224:227], v[76:79]
	v_mfma_f32_16x16x32_bf16 v[124:127], v[150:153], v[182:185], v[124:127]
	v_mfma_f32_16x16x32_bf16 v[120:123], v[158:161], v[182:185], v[120:123]
	v_mfma_f32_16x16x32_bf16 v[116:119], v[150:153], v[190:193], v[116:119]
	v_mfma_f32_16x16x32_bf16 v[108:111], v[158:161], v[190:193], v[108:111]
	v_mfma_f32_16x16x32_bf16 v[100:103], v[150:153], v[220:223], v[100:103]
	v_mfma_f32_16x16x32_bf16 v[92:95], v[158:161], v[220:223], v[92:95]
	v_mfma_f32_16x16x32_bf16 v[84:87], v[150:153], v[228:231], v[84:87]
	v_mfma_f32_16x16x32_bf16 v[76:79], v[158:161], v[228:231], v[76:79]
	s_setprio 0
	s_setprio 1
	v_mfma_f32_16x16x32_bf16 v[112:115], v[162:165], v[178:181], v[112:115]
	v_mfma_f32_16x16x32_bf16 v[104:107], v[170:173], v[178:181], v[104:107]
	v_mfma_f32_16x16x32_bf16 v[96:99], v[162:165], v[186:189], v[96:99]
	v_mfma_f32_16x16x32_bf16 v[88:91], v[170:173], v[186:189], v[88:91]
	v_mfma_f32_16x16x32_bf16 v[80:83], v[162:165], v[214:217], v[80:83]
	v_mfma_f32_16x16x32_bf16 v[72:75], v[170:173], v[214:217], v[72:75]
	v_mfma_f32_16x16x32_bf16 v[68:71], v[162:165], v[224:227], v[68:71]
	v_mfma_f32_16x16x32_bf16 v[64:67], v[170:173], v[224:227], v[64:67]
	v_mfma_f32_16x16x32_bf16 v[112:115], v[166:169], v[182:185], v[112:115]
	v_mfma_f32_16x16x32_bf16 v[104:107], v[174:177], v[182:185], v[104:107]
	v_mfma_f32_16x16x32_bf16 v[96:99], v[166:169], v[190:193], v[96:99]
	v_mfma_f32_16x16x32_bf16 v[88:91], v[174:177], v[190:193], v[88:91]
	v_mfma_f32_16x16x32_bf16 v[80:83], v[166:169], v[220:223], v[80:83]
	v_mfma_f32_16x16x32_bf16 v[72:75], v[174:177], v[220:223], v[72:75]
	v_mfma_f32_16x16x32_bf16 v[68:71], v[166:169], v[228:231], v[68:71]
	v_mfma_f32_16x16x32_bf16 v[64:67], v[174:177], v[228:231], v[64:67]
	s_setprio 0
	s_barrier
	s_add_i32 s60, s60, s2
	v_lshl_add_u64 v[140:141], s[56:57], 0, v[128:129]
	s_mov_b32 m0, s60
	ds_read_b128 v[178:181], v145 offset:16384
	ds_read_b128 v[182:185], v145 offset:17408
	ds_read_b128 v[186:189], v145 offset:18432
	ds_read_b128 v[190:193], v145 offset:19456
	ds_read_b128 v[214:217], v145 offset:20480
	ds_read_b128 v[220:223], v145 offset:21504
	ds_read_b128 v[224:227], v145 offset:22528
	ds_read_b128 v[228:231], v145 offset:23552
	global_load_lds_dwordx4 v[140:141], off
	s_add_i32 m0, s60, 0x2000
	s_add_u32 s60, s56, 0x80000
	v_lshl_add_u64 v[206:207], s[56:57], 0, v[130:131]
	s_addc_u32 s61, s57, 0
	s_add_i32 s7, s7, s2
	global_load_lds_dwordx4 v[206:207], off
	v_lshl_add_u64 v[232:233], s[60:61], 0, v[128:129]
	s_mov_b32 m0, s7
	v_lshl_add_u64 v[234:235], s[58:59], 0, v[132:133]
	global_load_lds_dwordx4 v[232:233], off
	v_lshl_add_u64 v[232:233], s[60:61], 0, v[130:131]
	s_add_i32 m0, s7, 0x2000
	s_nop 0
	global_load_lds_dwordx4 v[232:233], off
	v_lshl_add_u64 v[232:233], s[58:59], 0, v[134:135]
	s_mov_b32 m0, s10
	s_nop 0
	global_load_lds_dwordx4 v[232:233], off
	s_mov_b32 m0, s17
	s_nop 0
	global_load_lds_dwordx4 v[234:235], off
	s_cmp_lt_i32 s49, 0
	s_cbranch_scc0 .Lrx16_1_norm
	s_cmp_lt_u32 s33, 2
	s_cbranch_scc1 .Lrx16_1_norm
	s_waitcnt vmcnt(24)
	s_branch .Lrx16_1_join

; #define PG8_STAGE(bufoff, gbase, voff) do { _Pragma("unroll") for (int _i = 0; _i < 2; ++_i) \
;         __builtin_amdgcn_global_load_lds((const unsigned*)((const char*)(gbase) + (voff)[_i]), (PG8_LAS unsigned*)(lds + (bufoff) + ldsw + _i * 8192), 16, 0, 0); } while (0)
; #define PG8_LDA(dst, b, h) do { _Pragma("unroll") for (int m = 0; m < 4; ++m) _Pragma("unroll") for (int k = 0; k < 2; ++k) dst[m][k] = *(const PG8_LAS bf16x8*)(lds + PG8_SA(b, h) + aoff + m * 2048 + k * 1024); } while (0)
; #define PG8_LDB(dst, b, h) do { _Pragma("unroll") for (int n = 0; n < 2; ++n) _Pragma("unroll") for (int k = 0; k < 2; ++k) dst[n][k] = *(const PG8_LAS bf16x8*)(lds + PG8_SB(b, h) + boff + n * 2048 + k * 1024); } while (0)
; #define PG8_MMA(ai, bj, At, Bt) do { __builtin_amdgcn_s_setprio(1); _Pragma("unroll") for (int m = 0; m < 4; ++m) _Pragma("unroll") for (int n = 0; n < 2; ++n) _Pragma("unroll") for (int k = 0; k < 2; ++k) \
;         acc[ai][bj][m][n] = __builtin_amdgcn_mfma_f32_16x16x32_bf16(Bt[n][k], At[m][k], acc[ai][bj][m][n], 0, 0, 0); __builtin_amdgcn_s_setprio(0); } while (0)
; #define PG8_WAIT_V(n) asm volatile("s_waitcnt vmcnt(" #n ")" ::: "memory")
; #define PG8_WAIT_L(n) asm volatile("s_waitcnt lgkmcnt(" #n ")" ::: "memory")
; #define PG8_BAR __builtin_amdgcn_s_barrier()
; #define PG8_SCHED __builtin_amdgcn_sched_barrier(0)
; template <class Epi, class Sched, bool ALIGN_EPI = false, bool SP2 = false>
; __device__ __forceinline__ void gemm_phase(PG8_LAS unsigned char* lds, const Gemm g, const Sched& S, const Epi& E) {
;     ...
;             PG8_WAIT_V(8); PG8_WAIT_L(0); PG8_BAR; PG8_MMA(1, 0, At, B0); PG8_MMA(1, 1, At, B1); PG8_BAR; PG8_SCHED;
;             PG8_LDB(B0, 1, 0); PG8_LDB(B1, 1, 1); PG8_SCHED; PG8_LDA(At, 1, 0); PG8_STAGE(PG8_SA(0, 1), a2 + hstep, voffA);
;             PG8_WAIT_V(8); PG8_WAIT_L(0); PG8_BAR; PG8_MMA(0, 0, At, B0); PG8_MMA(0, 1, At, B1); PG8_BAR; PG8_SCHED;
.Lrx16_1_join:
	s_waitcnt lgkmcnt(0)
	s_barrier
	s_setprio 1
	s_waitcnt lgkmcnt(0)
	v_mfma_f32_16x16x32_bf16 v[60:63], v[146:149], v[178:181], v[60:63]
	v_mfma_f32_16x16x32_bf16 v[56:59], v[154:157], v[178:181], v[56:59]
	v_mfma_f32_16x16x32_bf16 v[52:55], v[146:149], v[186:189], v[52:55]
	v_mfma_f32_16x16x32_bf16 v[44:47], v[154:157], v[186:189], v[44:47]
	v_mfma_f32_16x16x32_bf16 v[36:39], v[146:149], v[214:217], v[36:39]
	v_mfma_f32_16x16x32_bf16 v[28:31], v[154:157], v[214:217], v[28:31]
	v_mfma_f32_16x16x32_bf16 v[20:23], v[146:149], v[224:227], v[20:23]
	v_mfma_f32_16x16x32_bf16 v[12:15], v[154:157], v[224:227], v[12:15]
	v_mfma_f32_16x16x32_bf16 v[60:63], v[150:153], v[182:185], v[60:63]
	v_mfma_f32_16x16x32_bf16 v[56:59], v[158:161], v[182:185], v[56:59]
	v_mfma_f32_16x16x32_bf16 v[52:55], v[150:153], v[190:193], v[52:55]
	v_mfma_f32_16x16x32_bf16 v[44:47], v[158:161], v[190:193], v[44:47]
	v_mfma_f32_16x16x32_bf16 v[36:39], v[150:153], v[220:223], v[36:39]
	v_mfma_f32_16x16x32_bf16 v[28:31], v[158:161], v[220:223], v[28:31]
	v_mfma_f32_16x16x32_bf16 v[20:23], v[150:153], v[228:231], v[20:23]
	v_mfma_f32_16x16x32_bf16 v[12:15], v[158:161], v[228:231], v[12:15]
	s_setprio 0
	s_setprio 1
	v_mfma_f32_16x16x32_bf16 v[48:51], v[162:165], v[178:181], v[48:51]
	v_mfma_f32_16x16x32_bf16 v[40:43], v[170:173], v[178:181], v[40:43]
	v_mfma_f32_16x16x32_bf16 v[32:35], v[162:165], v[186:189], v[32:35]
	v_mfma_f32_16x16x32_bf16 v[24:27], v[170:173], v[186:189], v[24:27]
	v_mfma_f32_16x16x32_bf16 v[16:19], v[162:165], v[214:217], v[16:19]
	v_mfma_f32_16x16x32_bf16 v[8:11], v[170:173], v[214:217], v[8:11]
	v_mfma_f32_16x16x32_bf16 v[4:7], v[162:165], v[224:227], v[4:7]
	v_mfma_f32_16x16x32_bf16 v[0:3], v[170:173], v[224:227], v[0:3]
	v_mfma_f32_16x16x32_bf16 v[48:51], v[166:169], v[182:185], v[48:51]
	v_mfma_f32_16x16x32_bf16 v[40:43], v[174:177], v[182:185], v[40:43]
	v_mfma_f32_16x16x32_bf16 v[32:35], v[166:169], v[190:193], v[32:35]
	v_mfma_f32_16x16x32_bf16 v[24:27], v[174:177], v[190:193], v[24:27]
	v_mfma_f32_16x16x32_bf16 v[16:19], v[166:169], v[220:223], v[16:19]
	v_mfma_f32_16x16x32_bf16 v[8:11], v[174:177], v[220:223], v[8:11]
	v_mfma_f32_16x16x32_bf16 v[4:7], v[166:169], v[228:231], v[4:7]
	v_mfma_f32_16x16x32_bf16 v[0:3], v[174:177], v[228:231], v[0:3]
	s_setprio 0
	s_barrier
	s_add_i32 s7, 0, 0x18000
	s_add_i32 s60, 0, 0x1c000
	v_add_u32_e32 v158, s7, v143
	v_add_u32_e32 v174, s60, v143
	ds_read_b128 v[146:149], v158
	ds_read_b128 v[150:153], v158 offset:1024
	ds_read_b128 v[154:157], v158 offset:2048
	ds_read_b128 v[158:161], v158 offset:3072
	ds_read_b128 v[162:165], v174
	ds_read_b128 v[166:169], v174 offset:1024
	ds_read_b128 v[170:173], v174 offset:2048
	ds_read_b128 v[174:177], v174 offset:3072
	s_add_u32 s58, s58, 0x80000
	s_addc_u32 s59, s59, 0
	s_mov_b32 m0, s26
	v_lshl_add_u64 v[236:237], s[58:59], 0, v[134:135]
	ds_read_b128 v[178:181], v145 offset:32768
	ds_read_b128 v[182:185], v145 offset:33792
	ds_read_b128 v[186:189], v145 offset:34816
	ds_read_b128 v[190:193], v145 offset:35840
	ds_read_b128 v[214:217], v145 offset:36864
	ds_read_b128 v[220:223], v145 offset:37888
	ds_read_b128 v[224:227], v145 offset:38912
	ds_read_b128 v[228:231], v145 offset:39936
	global_load_lds_dwordx4 v[236:237], off
	v_lshl_add_u64 v[236:237], s[58:59], 0, v[132:133]
	s_mov_b32 m0, s27
	s_nop 0
	global_load_lds_dwordx4 v[236:237], off
	s_waitcnt vmcnt(8)
	s_waitcnt lgkmcnt(0)
	s_barrier
	s_setprio 1
	s_waitcnt lgkmcnt(0)
	v_mfma_f32_16x16x32_bf16 v[124:127], v[146:149], v[178:181], v[124:127]
	v_mfma_f32_16x16x32_bf16 v[120:123], v[154:157], v[178:181], v[120:123]
	v_mfma_f32_16x16x32_bf16 v[116:119], v[146:149], v[186:189], v[116:119]
	v_mfma_f32_16x16x32_bf16 v[108:111], v[154:157], v[186:189], v[108:111]
	v_mfma_f32_16x16x32_bf16 v[100:103], v[146:149], v[214:217], v[100:103]
	v_mfma_f32_16x16x32_bf16 v[92:95], v[154:157], v[214:217], v[92:95]
	v_mfma_f32_16x16x32_bf16 v[84:87], v[146:149], v[224:227], v[84:87]
	v_mfma_f32_16x16x32_bf16 v[76:79], v[154:157], v[224:227], v[76:79]
	v_mfma_f32_16x16x32_bf16 v[124:127], v[150:153], v[182:185], v[124:127]
	v_mfma_f32_16x16x32_bf16 v[120:123], v[158:161], v[182:185], v[120:123]
	v_mfma_f32_16x16x32_bf16 v[116:119], v[150:153], v[190:193], v[116:119]
	v_mfma_f32_16x16x32_bf16 v[108:111], v[158:161], v[190:193], v[108:111]
	v_mfma_f32_16x16x32_bf16 v[100:103], v[150:153], v[220:223], v[100:103]
	v_mfma_f32_16x16x32_bf16 v[92:95], v[158:161], v[220:223], v[92:95]
	v_mfma_f32_16x16x32_bf16 v[84:87], v[150:153], v[228:231], v[84:87]
	v_mfma_f32_16x16x32_bf16 v[76:79], v[158:161], v[228:231], v[76:79]
	s_setprio 0
	s_setprio 1
	v_mfma_f32_16x16x32_bf16 v[112:115], v[162:165], v[178:181], v[112:115]
	v_mfma_f32_16x16x32_bf16 v[104:107], v[170:173], v[178:181], v[104:107]
	v_mfma_f32_16x16x32_bf16 v[96:99], v[162:165], v[186:189], v[96:99]
	v_mfma_f32_16x16x32_bf16 v[88:91], v[170:173], v[186:189], v[88:91]
	v_mfma_f32_16x16x32_bf16 v[80:83], v[162:165], v[214:217], v[80:83]
	v_mfma_f32_16x16x32_bf16 v[72:75], v[170:173], v[214:217], v[72:75]
	v_mfma_f32_16x16x32_bf16 v[68:71], v[162:165], v[224:227], v[68:71]
	v_mfma_f32_16x16x32_bf16 v[64:67], v[170:173], v[224:227], v[64:67]
	v_mfma_f32_16x16x32_bf16 v[112:115], v[166:169], v[182:185], v[112:115]
	v_mfma_f32_16x16x32_bf16 v[104:107], v[174:177], v[182:185], v[104:107]
	v_mfma_f32_16x16x32_bf16 v[96:99], v[166:169], v[190:193], v[96:99]
	v_mfma_f32_16x16x32_bf16 v[88:91], v[174:177], v[190:193], v[88:91]
	v_mfma_f32_16x16x32_bf16 v[80:83], v[166:169], v[220:223], v[80:83]
	v_mfma_f32_16x16x32_bf16 v[72:75], v[174:177], v[220:223], v[72:75]
	v_mfma_f32_16x16x32_bf16 v[68:71], v[166:169], v[228:231], v[68:71]
	v_mfma_f32_16x16x32_bf16 v[64:67], v[174:177], v[228:231], v[64:67]
	s_setprio 0
	s_barrier
; #define PG8_STAGE(bufoff, gbase, voff) do { _Pragma("unroll") for (int _i = 0; _i < 2; ++_i) \
;         __builtin_amdgcn_global_load_lds((const unsigned*)((const char*)(gbase) + (voff)[_i]), (PG8_LAS unsigned*)(lds + (bufoff) + ldsw + _i * 8192), 16, 0, 0); } while (0)
; #define PG8_LDA(dst, b, h) do { _Pragma("unroll") for (int m = 0; m < 4; ++m) _Pragma("unroll") for (int k = 0; k < 2; ++k) dst[m][k] = *(const PG8_LAS bf16x8*)(lds + PG8_SA(b, h) + aoff + m * 2048 + k * 1024); } while (0)
; #define PG8_MMA(ai, bj, At, Bt) do { __builtin_amdgcn_s_setprio(1); _Pragma("unroll") for (int m = 0; m < 4; ++m) _Pragma("unroll") for (int n = 0; n < 2; ++n) _Pragma("unroll") for (int k = 0; k < 2; ++k) \
;         acc[ai][bj][m][n] = __builtin_amdgcn_mfma_f32_16x16x32_bf16(Bt[n][k], At[m][k], acc[ai][bj][m][n], 0, 0, 0); __builtin_amdgcn_s_setprio(0); } while (0)
; #define PG8_WAIT_V(n) asm volatile("s_waitcnt vmcnt(" #n ")" ::: "memory")
; #define PG8_WAIT_L(n) asm volatile("s_waitcnt lgkmcnt(" #n ")" ::: "memory")
; #define PG8_BAR __builtin_amdgcn_s_barrier()
; #define PG8_SCHED __builtin_amdgcn_sched_barrier(0)
; template <class Epi, class Sched, bool ALIGN_EPI = false, bool SP2 = false>
; __device__ __forceinline__ void gemm_phase(PG8_LAS unsigned char* lds, const Gemm g, const Sched& S, const Epi& E) {
;     ...
;             PG8_LDA(At, 1, 1); PG8_STAGE(PG8_SB(1, 0), b3, voffB); PG8_STAGE(PG8_SB(1, 1), b3 + hstep, voffB); PG8_STAGE(PG8_SA(1, 0), a3, voffA);
;             PG8_WAIT_V(8); PG8_WAIT_L(0); PG8_BAR; PG8_MMA(1, 0, At, B0); PG8_MMA(1, 1, At, B1); PG8_BAR; PG8_SCHED;
	s_add_i32 s7, s7, s2
	v_lshl_add_u64 v[140:141], v[140:141], 0, s[20:21]
	s_mov_b32 m0, s7
	ds_read_b128 v[178:181], v145 offset:49152
	ds_read_b128 v[182:185], v145 offset:50176
	ds_read_b128 v[186:189], v145 offset:51200
	ds_read_b128 v[190:193], v145 offset:52224
	ds_read_b128 v[214:217], v145 offset:53248
	ds_read_b128 v[220:223], v145 offset:54272
	ds_read_b128 v[224:227], v145 offset:55296
	ds_read_b128 v[228:231], v145 offset:56320
	global_load_lds_dwordx4 v[140:141], off
	s_add_i32 m0, s7, 0x2000
	s_add_u32 s56, s56, 0x80080
	v_lshl_add_u64 v[140:141], v[206:207], 0, s[20:21]
	s_addc_u32 s57, s57, 0
	s_add_i32 s7, s60, s2
	global_load_lds_dwordx4 v[140:141], off
	v_lshl_add_u64 v[140:141], s[56:57], 0, v[128:129]
	s_mov_b32 m0, s7
	s_nop 0
	global_load_lds_dwordx4 v[140:141], off
	v_lshl_add_u64 v[140:141], s[56:57], 0, v[130:131]
	s_add_i32 m0, s7, 0x2000
	s_nop 0
	global_load_lds_dwordx4 v[140:141], off
	v_lshl_add_u64 v[140:141], v[232:233], 0, s[20:21]
	s_mov_b32 m0, s28
	s_nop 0
	global_load_lds_dwordx4 v[140:141], off
	v_lshl_add_u64 v[140:141], v[234:235], 0, s[20:21]
	s_mov_b32 m0, s29
	s_nop 0
	global_load_lds_dwordx4 v[140:141], off
	s_waitcnt vmcnt(8)
	s_waitcnt lgkmcnt(0)
	s_barrier
	s_setprio 1
	s_waitcnt lgkmcnt(0)
	v_mfma_f32_16x16x32_bf16 v[60:63], v[146:149], v[178:181], v[60:63]
	v_mfma_f32_16x16x32_bf16 v[56:59], v[154:157], v[178:181], v[56:59]
	v_mfma_f32_16x16x32_bf16 v[52:55], v[146:149], v[186:189], v[52:55]
	v_mfma_f32_16x16x32_bf16 v[44:47], v[154:157], v[186:189], v[44:47]
	v_mfma_f32_16x16x32_bf16 v[36:39], v[146:149], v[214:217], v[36:39]
	v_mfma_f32_16x16x32_bf16 v[28:31], v[154:157], v[214:217], v[28:31]
	v_mfma_f32_16x16x32_bf16 v[20:23], v[146:149], v[224:227], v[20:23]
	v_mfma_f32_16x16x32_bf16 v[12:15], v[154:157], v[224:227], v[12:15]
	v_mfma_f32_16x16x32_bf16 v[60:63], v[150:153], v[182:185], v[60:63]
	v_mfma_f32_16x16x32_bf16 v[56:59], v[158:161], v[182:185], v[56:59]
	v_mfma_f32_16x16x32_bf16 v[52:55], v[150:153], v[190:193], v[52:55]
	v_mfma_f32_16x16x32_bf16 v[44:47], v[158:161], v[190:193], v[44:47]
	v_mfma_f32_16x16x32_bf16 v[36:39], v[150:153], v[220:223], v[36:39]
	v_mfma_f32_16x16x32_bf16 v[28:31], v[158:161], v[220:223], v[28:31]
	v_mfma_f32_16x16x32_bf16 v[20:23], v[150:153], v[228:231], v[20:23]
	v_mfma_f32_16x16x32_bf16 v[12:15], v[158:161], v[228:231], v[12:15]
	s_setprio 0
	s_setprio 1
	v_mfma_f32_16x16x32_bf16 v[48:51], v[162:165], v[178:181], v[48:51]
	v_mfma_f32_16x16x32_bf16 v[40:43], v[170:173], v[178:181], v[40:43]
	v_mfma_f32_16x16x32_bf16 v[32:35], v[162:165], v[186:189], v[32:35]
	v_mfma_f32_16x16x32_bf16 v[24:27], v[170:173], v[186:189], v[24:27]
	v_mfma_f32_16x16x32_bf16 v[16:19], v[162:165], v[214:217], v[16:19]
	v_mfma_f32_16x16x32_bf16 v[8:11], v[170:173], v[214:217], v[8:11]
	v_mfma_f32_16x16x32_bf16 v[4:7], v[162:165], v[224:227], v[4:7]
	v_mfma_f32_16x16x32_bf16 v[0:3], v[170:173], v[224:227], v[0:3]
	v_mfma_f32_16x16x32_bf16 v[48:51], v[166:169], v[182:185], v[48:51]
	v_mfma_f32_16x16x32_bf16 v[40:43], v[174:177], v[182:185], v[40:43]
	v_mfma_f32_16x16x32_bf16 v[32:35], v[166:169], v[190:193], v[32:35]
	v_mfma_f32_16x16x32_bf16 v[24:27], v[174:177], v[190:193], v[24:27]
	v_mfma_f32_16x16x32_bf16 v[16:19], v[166:169], v[220:223], v[16:19]
	v_mfma_f32_16x16x32_bf16 v[8:11], v[174:177], v[220:223], v[8:11]
	v_mfma_f32_16x16x32_bf16 v[4:7], v[166:169], v[228:231], v[4:7]
	v_mfma_f32_16x16x32_bf16 v[0:3], v[174:177], v[228:231], v[0:3]
	s_setprio 0
	s_barrier
	s_add_i32 s49, s49, 2
	s_add_u32 s54, s54, 0x100
	s_addc_u32 s55, s55, 0
	s_add_u32 s45, s45, 0x100
	s_addc_u32 s47, s47, 0
	s_cmp_gt_u32 s49, 29
	s_cbranch_scc0 .LBB0_96
	s_and_b64 vcc, exec, s[30:31]
	s_cbranch_vccz .LBB0_99
	s_barrier

; #define PG8_STAGE(bufoff, gbase, voff) do { _Pragma("unroll") for (int _i = 0; _i < 2; ++_i) \
;         __builtin_amdgcn_global_load_lds((const unsigned*)((const char*)(gbase) + (voff)[_i]), (PG8_LAS unsigned*)(lds + (bufoff) + ldsw + _i * 8192), 16, 0, 0); } while (0)
; #define PG8_LDA(dst, b, h) do { _Pragma("unroll") for (int m = 0; m < 4; ++m) _Pragma("unroll") for (int k = 0; k < 2; ++k) dst[m][k] = *(const PG8_LAS bf16x8*)(lds + PG8_SA(b, h) + aoff + m * 2048 + k * 1024); } while (0)
; #define PG8_LDB(dst, b, h) do { _Pragma("unroll") for (int n = 0; n < 2; ++n) _Pragma("unroll") for (int k = 0; k < 2; ++k) dst[n][k] = *(const PG8_LAS bf16x8*)(lds + PG8_SB(b, h) + boff + n * 2048 + k * 1024); } while (0)
; #define PG8_MMA(ai, bj, At, Bt) do { __builtin_amdgcn_s_setprio(1); _Pragma("unroll") for (int m = 0; m < 4; ++m) _Pragma("unroll") for (int n = 0; n < 2; ++n) _Pragma("unroll") for (int k = 0; k < 2; ++k) \
;         acc[ai][bj][m][n] = __builtin_amdgcn_mfma_f32_16x16x32_bf16(Bt[n][k], At[m][k], acc[ai][bj][m][n], 0, 0, 0); __builtin_amdgcn_s_setprio(0); } while (0)
; #define PG8_WAIT_V(n) asm volatile("s_waitcnt vmcnt(" #n ")" ::: "memory")
; #define PG8_WAIT_L(n) asm volatile("s_waitcnt lgkmcnt(" #n ")" ::: "memory")
; #define PG8_BAR __builtin_amdgcn_s_barrier()
; #define PG8_SCHED __builtin_amdgcn_sched_barrier(0)
; template <class Epi, class Sched, bool ALIGN_EPI = false, bool SP2 = false>
; __device__ __forceinline__ void gemm_phase(PG8_LAS unsigned char* lds, const Gemm g, const Sched& S, const Epi& E) {
;     ...
;             const bool last = (t == nt - 2);
;             const char* a1 = cA + (size_t)(t + 1) * kstep;
;             const char* a2 = last ? nA : cA + (size_t)(t + 2) * kstep; const char* b2 = last ? nB : cB + (size_t)(t + 2) * kstep;
;             const char* a3 = a2 + kstep; const char* b3 = b2 + kstep;
;             if (last && has_next) S.a_ready(nxt);
;             if constexpr (SP2) {
;             PG8_LDB(B0, 0, 0); PG8_LDB(B1, 0, 1); PG8_SCHED; PG8_LDA(At, 0, 0); PG8_STAGE(PG8_SA(1, 1), a1 + hstep, voffA);
;             PG8_WAIT_V(8); PG8_WAIT_L(0); PG8_BAR; PG8_MMA(0, 0, At, B0); PG8_MMA(0, 1, At, B1); PG8_BAR; PG8_SCHED;
.LBB0_305:
	s_add_u32 s52, s50, 0xfff80080
	s_addc_u32 s53, s51, -1
	s_add_i32 s56, 0, 0x10000
	s_cmp_eq_u32 s45, 28
	s_cselect_b32 s55, s19, s53
	s_cselect_b32 s54, s34, s52
	v_add_u32_e32 v140, s56, v143
	s_cselect_b32 s53, s31, s43
	s_cselect_b32 s52, s35, s37
	s_add_i32 s58, 0, 0x14000
	ds_read_b128 v[146:149], v140
	ds_read_b128 v[150:153], v140 offset:1024
	ds_read_b128 v[154:157], v140 offset:2048
	ds_read_b128 v[158:161], v140 offset:3072
	v_add_u32_e32 v140, s58, v143
	ds_read_b128 v[162:165], v140
	ds_read_b128 v[166:169], v140 offset:1024
	ds_read_b128 v[170:173], v140 offset:2048
	ds_read_b128 v[174:177], v140 offset:3072
	v_lshl_add_u64 v[140:141], s[50:51], 0, v[136:137]
	s_add_i32 m0, s10, 0xc000
	ds_read_b128 v[178:181], v145
	ds_read_b128 v[182:185], v145 offset:1024
	ds_read_b128 v[186:189], v145 offset:2048
	ds_read_b128 v[190:193], v145 offset:3072
	ds_read_b128 v[220:223], v145 offset:4096
	ds_read_b128 v[224:227], v145 offset:5120
	ds_read_b128 v[228:231], v145 offset:6144
	ds_read_b128 v[232:235], v145 offset:7168
	global_load_lds_dwordx4 v[140:141], off
	v_lshl_add_u64 v[140:141], s[50:51], 0, v[138:139]
	s_add_i32 m0, s10, 0xe000
	s_nop 0
	global_load_lds_dwordx4 v[140:141], off
	s_cmp_lt_i32 s45, 0
	s_cbranch_scc0 .Lrx11_0_norm
	s_cmp_lt_u32 s33, 2
	s_cbranch_scc1 .Lrx11_0_norm
	s_waitcnt vmcnt(24)
	s_branch .Lrx11_0_join

; #define PG8_STAGE(bufoff, gbase, voff) do { _Pragma("unroll") for (int _i = 0; _i < 2; ++_i) \
;         __builtin_amdgcn_global_load_lds((const unsigned*)((const char*)(gbase) + (voff)[_i]), (PG8_LAS unsigned*)(lds + (bufoff) + ldsw + _i * 8192), 16, 0, 0); } while (0)
; #define PG8_LDA(dst, b, h) do { _Pragma("unroll") for (int m = 0; m < 4; ++m) _Pragma("unroll") for (int k = 0; k < 2; ++k) dst[m][k] = *(const PG8_LAS bf16x8*)(lds + PG8_SA(b, h) + aoff + m * 2048 + k * 1024); } while (0)
; #define PG8_MMA(ai, bj, At, Bt) do { __builtin_amdgcn_s_setprio(1); _Pragma("unroll") for (int m = 0; m < 4; ++m) _Pragma("unroll") for (int n = 0; n < 2; ++n) _Pragma("unroll") for (int k = 0; k < 2; ++k) \
;         acc[ai][bj][m][n] = __builtin_amdgcn_mfma_f32_16x16x32_bf16(Bt[n][k], At[m][k], acc[ai][bj][m][n], 0, 0, 0); __builtin_amdgcn_s_setprio(0); } while (0)
; #define PG8_WAIT_V(n) asm volatile("s_waitcnt vmcnt(" #n ")" ::: "memory")
; #define PG8_WAIT_L(n) asm volatile("s_waitcnt lgkmcnt(" #n ")" ::: "memory")
; #define PG8_BAR __builtin_amdgcn_s_barrier()
; #define PG8_SCHED __builtin_amdgcn_sched_barrier(0)
; template <class Epi, class Sched, bool ALIGN_EPI = false, bool SP2 = false>
; __device__ __forceinline__ void gemm_phase(PG8_LAS unsigned char* lds, const Gemm g, const Sched& S, const Epi& E) {
;     ...
;             PG8_WAIT_V(8); PG8_WAIT_L(0); PG8_BAR; PG8_MMA(0, 0, At, B0); PG8_MMA(0, 1, At, B1); PG8_BAR; PG8_SCHED;
;             PG8_LDA(At, 0, 1); PG8_STAGE(PG8_SB(0, 0), b2, voffB); PG8_STAGE(PG8_SB(0, 1), b2 + hstep, voffB); PG8_STAGE(PG8_SA(0, 0), a2, voffA);
.Lrx11_0_join:
	s_waitcnt lgkmcnt(0)
	s_barrier
	s_setprio 1
	s_waitcnt lgkmcnt(0)
	v_mfma_f32_16x16x32_bf16 v[124:127], v[146:149], v[178:181], v[124:127]
	v_mfma_f32_16x16x32_bf16 v[120:123], v[154:157], v[178:181], v[120:123]
	v_mfma_f32_16x16x32_bf16 v[116:119], v[146:149], v[186:189], v[116:119]
	v_mfma_f32_16x16x32_bf16 v[108:111], v[154:157], v[186:189], v[108:111]
	v_mfma_f32_16x16x32_bf16 v[100:103], v[146:149], v[220:223], v[100:103]
	v_mfma_f32_16x16x32_bf16 v[92:95], v[154:157], v[220:223], v[92:95]
	v_mfma_f32_16x16x32_bf16 v[84:87], v[146:149], v[228:231], v[84:87]
	v_mfma_f32_16x16x32_bf16 v[76:79], v[154:157], v[228:231], v[76:79]
	v_mfma_f32_16x16x32_bf16 v[124:127], v[150:153], v[182:185], v[124:127]
	v_mfma_f32_16x16x32_bf16 v[120:123], v[158:161], v[182:185], v[120:123]
	v_mfma_f32_16x16x32_bf16 v[116:119], v[150:153], v[190:193], v[116:119]
	v_mfma_f32_16x16x32_bf16 v[108:111], v[158:161], v[190:193], v[108:111]
	v_mfma_f32_16x16x32_bf16 v[100:103], v[150:153], v[224:227], v[100:103]
	v_mfma_f32_16x16x32_bf16 v[92:95], v[158:161], v[224:227], v[92:95]
	v_mfma_f32_16x16x32_bf16 v[84:87], v[150:153], v[232:235], v[84:87]
	v_mfma_f32_16x16x32_bf16 v[76:79], v[158:161], v[232:235], v[76:79]
	s_setprio 0
	s_setprio 1
	v_mfma_f32_16x16x32_bf16 v[112:115], v[162:165], v[178:181], v[112:115]
	v_mfma_f32_16x16x32_bf16 v[104:107], v[170:173], v[178:181], v[104:107]
	v_mfma_f32_16x16x32_bf16 v[96:99], v[162:165], v[186:189], v[96:99]
	v_mfma_f32_16x16x32_bf16 v[88:91], v[170:173], v[186:189], v[88:91]
	v_mfma_f32_16x16x32_bf16 v[80:83], v[162:165], v[220:223], v[80:83]
	v_mfma_f32_16x16x32_bf16 v[72:75], v[170:173], v[220:223], v[72:75]
	v_mfma_f32_16x16x32_bf16 v[68:71], v[162:165], v[228:231], v[68:71]
	v_mfma_f32_16x16x32_bf16 v[64:67], v[170:173], v[228:231], v[64:67]
	v_mfma_f32_16x16x32_bf16 v[112:115], v[166:169], v[182:185], v[112:115]
	v_mfma_f32_16x16x32_bf16 v[104:107], v[174:177], v[182:185], v[104:107]
	v_mfma_f32_16x16x32_bf16 v[96:99], v[166:169], v[190:193], v[96:99]
	v_mfma_f32_16x16x32_bf16 v[88:91], v[174:177], v[190:193], v[88:91]
	v_mfma_f32_16x16x32_bf16 v[80:83], v[166:169], v[224:227], v[80:83]
	v_mfma_f32_16x16x32_bf16 v[72:75], v[174:177], v[224:227], v[72:75]
	v_mfma_f32_16x16x32_bf16 v[68:71], v[166:169], v[232:235], v[68:71]
	v_mfma_f32_16x16x32_bf16 v[64:67], v[174:177], v[232:235], v[64:67]
	s_setprio 0
	s_barrier
	s_add_i32 s56, s56, s2
	v_lshl_add_u64 v[140:141], s[52:53], 0, v[128:129]
	s_mov_b32 m0, s56
	ds_read_b128 v[178:181], v145 offset:16384
	ds_read_b128 v[182:185], v145 offset:17408
	ds_read_b128 v[186:189], v145 offset:18432
	ds_read_b128 v[190:193], v145 offset:19456
	ds_read_b128 v[220:223], v145 offset:20480
	ds_read_b128 v[224:227], v145 offset:21504
	ds_read_b128 v[228:231], v145 offset:22528
	ds_read_b128 v[232:235], v145 offset:23552
	global_load_lds_dwordx4 v[140:141], off
	s_add_i32 m0, s56, 0x2000
	s_add_u32 s56, s52, 0x80000
	v_lshl_add_u64 v[206:207], s[52:53], 0, v[130:131]
	s_addc_u32 s57, s53, 0
	s_add_i32 s58, s58, s2
	global_load_lds_dwordx4 v[206:207], off
	v_lshl_add_u64 v[214:215], s[56:57], 0, v[128:129]
	s_mov_b32 m0, s58
	v_lshl_add_u64 v[216:217], s[54:55], 0, v[132:133]
	global_load_lds_dwordx4 v[214:215], off
	v_lshl_add_u64 v[214:215], s[56:57], 0, v[130:131]
	s_add_i32 m0, s58, 0x2000
	s_nop 0
	global_load_lds_dwordx4 v[214:215], off
	v_lshl_add_u64 v[214:215], s[54:55], 0, v[134:135]
	s_mov_b32 m0, s10
	s_nop 0
	global_load_lds_dwordx4 v[214:215], off
	s_mov_b32 m0, s17
	s_nop 0
	global_load_lds_dwordx4 v[216:217], off
	s_cmp_lt_i32 s45, 0
	s_cbranch_scc0 .Lrx11_1_norm
	s_cmp_lt_u32 s33, 2
	s_cbranch_scc1 .Lrx11_1_norm
	s_waitcnt vmcnt(24)
	s_branch .Lrx11_1_join

; #define PG8_STAGE(bufoff, gbase, voff) do { _Pragma("unroll") for (int _i = 0; _i < 2; ++_i) \
;         __builtin_amdgcn_global_load_lds((const unsigned*)((const char*)(gbase) + (voff)[_i]), (PG8_LAS unsigned*)(lds + (bufoff) + ldsw + _i * 8192), 16, 0, 0); } while (0)
; #define PG8_LDA(dst, b, h) do { _Pragma("unroll") for (int m = 0; m < 4; ++m) _Pragma("unroll") for (int k = 0; k < 2; ++k) dst[m][k] = *(const PG8_LAS bf16x8*)(lds + PG8_SA(b, h) + aoff + m * 2048 + k * 1024); } while (0)
; #define PG8_LDB(dst, b, h) do { _Pragma("unroll") for (int n = 0; n < 2; ++n) _Pragma("unroll") for (int k = 0; k < 2; ++k) dst[n][k] = *(const PG8_LAS bf16x8*)(lds + PG8_SB(b, h) + boff + n * 2048 + k * 1024); } while (0)
; #define PG8_MMA(ai, bj, At, Bt) do { __builtin_amdgcn_s_setprio(1); _Pragma("unroll") for (int m = 0; m < 4; ++m) _Pragma("unroll") for (int n = 0; n < 2; ++n) _Pragma("unroll") for (int k = 0; k < 2; ++k) \
;         acc[ai][bj][m][n] = __builtin_amdgcn_mfma_f32_16x16x32_bf16(Bt[n][k], At[m][k], acc[ai][bj][m][n], 0, 0, 0); __builtin_amdgcn_s_setprio(0); } while (0)
; #define PG8_WAIT_V(n) asm volatile("s_waitcnt vmcnt(" #n ")" ::: "memory")
; #define PG8_WAIT_L(n) asm volatile("s_waitcnt lgkmcnt(" #n ")" ::: "memory")
; #define PG8_BAR __builtin_amdgcn_s_barrier()
; #define PG8_SCHED __builtin_amdgcn_sched_barrier(0)
; template <class Epi, class Sched, bool ALIGN_EPI = false, bool SP2 = false>
; __device__ __forceinline__ void gemm_phase(PG8_LAS unsigned char* lds, const Gemm g, const Sched& S, const Epi& E) {
;     ...
;             PG8_WAIT_V(8); PG8_WAIT_L(0); PG8_BAR; PG8_MMA(1, 0, At, B0); PG8_MMA(1, 1, At, B1); PG8_BAR; PG8_SCHED;
;             PG8_LDB(B0, 1, 0); PG8_LDB(B1, 1, 1); PG8_SCHED; PG8_LDA(At, 1, 0); PG8_STAGE(PG8_SA(0, 1), a2 + hstep, voffA);
;             PG8_WAIT_V(8); PG8_WAIT_L(0); PG8_BAR; PG8_MMA(0, 0, At, B0); PG8_MMA(0, 1, At, B1); PG8_BAR; PG8_SCHED;
.Lrx11_1_join:
	s_waitcnt lgkmcnt(0)
	s_barrier
	s_setprio 1
	s_waitcnt lgkmcnt(0)
	v_mfma_f32_16x16x32_bf16 v[60:63], v[146:149], v[178:181], v[60:63]
	v_mfma_f32_16x16x32_bf16 v[56:59], v[154:157], v[178:181], v[56:59]
	v_mfma_f32_16x16x32_bf16 v[52:55], v[146:149], v[186:189], v[52:55]
	v_mfma_f32_16x16x32_bf16 v[44:47], v[154:157], v[186:189], v[44:47]
	v_mfma_f32_16x16x32_bf16 v[36:39], v[146:149], v[220:223], v[36:39]
	v_mfma_f32_16x16x32_bf16 v[28:31], v[154:157], v[220:223], v[28:31]
	v_mfma_f32_16x16x32_bf16 v[20:23], v[146:149], v[228:231], v[20:23]
	v_mfma_f32_16x16x32_bf16 v[12:15], v[154:157], v[228:231], v[12:15]
	v_mfma_f32_16x16x32_bf16 v[60:63], v[150:153], v[182:185], v[60:63]
	v_mfma_f32_16x16x32_bf16 v[56:59], v[158:161], v[182:185], v[56:59]
	v_mfma_f32_16x16x32_bf16 v[52:55], v[150:153], v[190:193], v[52:55]
	v_mfma_f32_16x16x32_bf16 v[44:47], v[158:161], v[190:193], v[44:47]
	v_mfma_f32_16x16x32_bf16 v[36:39], v[150:153], v[224:227], v[36:39]
	v_mfma_f32_16x16x32_bf16 v[28:31], v[158:161], v[224:227], v[28:31]
	v_mfma_f32_16x16x32_bf16 v[20:23], v[150:153], v[232:235], v[20:23]
	v_mfma_f32_16x16x32_bf16 v[12:15], v[158:161], v[232:235], v[12:15]
	s_setprio 0
	s_setprio 1
	v_mfma_f32_16x16x32_bf16 v[48:51], v[162:165], v[178:181], v[48:51]
	v_mfma_f32_16x16x32_bf16 v[40:43], v[170:173], v[178:181], v[40:43]
	v_mfma_f32_16x16x32_bf16 v[32:35], v[162:165], v[186:189], v[32:35]
	v_mfma_f32_16x16x32_bf16 v[24:27], v[170:173], v[186:189], v[24:27]
	v_mfma_f32_16x16x32_bf16 v[16:19], v[162:165], v[220:223], v[16:19]
	v_mfma_f32_16x16x32_bf16 v[8:11], v[170:173], v[220:223], v[8:11]
	v_mfma_f32_16x16x32_bf16 v[4:7], v[162:165], v[228:231], v[4:7]
	v_mfma_f32_16x16x32_bf16 v[0:3], v[170:173], v[228:231], v[0:3]
	v_mfma_f32_16x16x32_bf16 v[48:51], v[166:169], v[182:185], v[48:51]
	v_mfma_f32_16x16x32_bf16 v[40:43], v[174:177], v[182:185], v[40:43]
	v_mfma_f32_16x16x32_bf16 v[32:35], v[166:169], v[190:193], v[32:35]
	v_mfma_f32_16x16x32_bf16 v[24:27], v[174:177], v[190:193], v[24:27]
	v_mfma_f32_16x16x32_bf16 v[16:19], v[166:169], v[224:227], v[16:19]
	v_mfma_f32_16x16x32_bf16 v[8:11], v[174:177], v[224:227], v[8:11]
	v_mfma_f32_16x16x32_bf16 v[4:7], v[166:169], v[232:235], v[4:7]
	v_mfma_f32_16x16x32_bf16 v[0:3], v[174:177], v[232:235], v[0:3]
	s_setprio 0
	s_barrier
	s_add_i32 s56, 0, 0x18000
	s_add_i32 s57, 0, 0x1c000
	v_add_u32_e32 v158, s56, v143
	v_add_u32_e32 v174, s57, v143
	ds_read_b128 v[146:149], v158
	ds_read_b128 v[150:153], v158 offset:1024
	ds_read_b128 v[154:157], v158 offset:2048
	ds_read_b128 v[158:161], v158 offset:3072
	ds_read_b128 v[162:165], v174
	ds_read_b128 v[166:169], v174 offset:1024
	ds_read_b128 v[170:173], v174 offset:2048
	ds_read_b128 v[174:177], v174 offset:3072
	s_add_u32 s54, s54, 0x80000
	s_addc_u32 s55, s55, 0
	s_mov_b32 m0, s26
	v_lshl_add_u64 v[236:237], s[54:55], 0, v[134:135]
	ds_read_b128 v[178:181], v145 offset:32768
	ds_read_b128 v[182:185], v145 offset:33792
	ds_read_b128 v[186:189], v145 offset:34816
	ds_read_b128 v[190:193], v145 offset:35840
	ds_read_b128 v[220:223], v145 offset:36864
	ds_read_b128 v[224:227], v145 offset:37888
	ds_read_b128 v[228:231], v145 offset:38912
	ds_read_b128 v[232:235], v145 offset:39936
	global_load_lds_dwordx4 v[236:237], off
	v_lshl_add_u64 v[236:237], s[54:55], 0, v[132:133]
	s_mov_b32 m0, s27
	s_nop 0
	global_load_lds_dwordx4 v[236:237], off
	s_waitcnt vmcnt(8)
	s_waitcnt lgkmcnt(0)
	s_barrier
	s_setprio 1
	s_waitcnt lgkmcnt(0)
	v_mfma_f32_16x16x32_bf16 v[124:127], v[146:149], v[178:181], v[124:127]
	v_mfma_f32_16x16x32_bf16 v[120:123], v[154:157], v[178:181], v[120:123]
	v_mfma_f32_16x16x32_bf16 v[116:119], v[146:149], v[186:189], v[116:119]
	v_mfma_f32_16x16x32_bf16 v[108:111], v[154:157], v[186:189], v[108:111]
	v_mfma_f32_16x16x32_bf16 v[100:103], v[146:149], v[220:223], v[100:103]
	v_mfma_f32_16x16x32_bf16 v[92:95], v[154:157], v[220:223], v[92:95]
	v_mfma_f32_16x16x32_bf16 v[84:87], v[146:149], v[228:231], v[84:87]
	v_mfma_f32_16x16x32_bf16 v[76:79], v[154:157], v[228:231], v[76:79]
	v_mfma_f32_16x16x32_bf16 v[124:127], v[150:153], v[182:185], v[124:127]
	v_mfma_f32_16x16x32_bf16 v[120:123], v[158:161], v[182:185], v[120:123]
	v_mfma_f32_16x16x32_bf16 v[116:119], v[150:153], v[190:193], v[116:119]
	v_mfma_f32_16x16x32_bf16 v[108:111], v[158:161], v[190:193], v[108:111]
	v_mfma_f32_16x16x32_bf16 v[100:103], v[150:153], v[224:227], v[100:103]
	v_mfma_f32_16x16x32_bf16 v[92:95], v[158:161], v[224:227], v[92:95]
	v_mfma_f32_16x16x32_bf16 v[84:87], v[150:153], v[232:235], v[84:87]
	v_mfma_f32_16x16x32_bf16 v[76:79], v[158:161], v[232:235], v[76:79]
	s_setprio 0
	s_setprio 1
	v_mfma_f32_16x16x32_bf16 v[112:115], v[162:165], v[178:181], v[112:115]
	v_mfma_f32_16x16x32_bf16 v[104:107], v[170:173], v[178:181], v[104:107]
	v_mfma_f32_16x16x32_bf16 v[96:99], v[162:165], v[186:189], v[96:99]
	v_mfma_f32_16x16x32_bf16 v[88:91], v[170:173], v[186:189], v[88:91]
	v_mfma_f32_16x16x32_bf16 v[80:83], v[162:165], v[220:223], v[80:83]
	v_mfma_f32_16x16x32_bf16 v[72:75], v[170:173], v[220:223], v[72:75]
	v_mfma_f32_16x16x32_bf16 v[68:71], v[162:165], v[228:231], v[68:71]
	v_mfma_f32_16x16x32_bf16 v[64:67], v[170:173], v[228:231], v[64:67]
	v_mfma_f32_16x16x32_bf16 v[112:115], v[166:169], v[182:185], v[112:115]
	v_mfma_f32_16x16x32_bf16 v[104:107], v[174:177], v[182:185], v[104:107]
	v_mfma_f32_16x16x32_bf16 v[96:99], v[166:169], v[190:193], v[96:99]
	v_mfma_f32_16x16x32_bf16 v[88:91], v[174:177], v[190:193], v[88:91]
	v_mfma_f32_16x16x32_bf16 v[80:83], v[166:169], v[224:227], v[80:83]
	v_mfma_f32_16x16x32_bf16 v[72:75], v[174:177], v[224:227], v[72:75]
	v_mfma_f32_16x16x32_bf16 v[68:71], v[166:169], v[232:235], v[68:71]
	v_mfma_f32_16x16x32_bf16 v[64:67], v[174:177], v[232:235], v[64:67]
	s_setprio 0
	s_barrier
; #define PG8_STAGE(bufoff, gbase, voff) do { _Pragma("unroll") for (int _i = 0; _i < 2; ++_i) \
;         __builtin_amdgcn_global_load_lds((const unsigned*)((const char*)(gbase) + (voff)[_i]), (PG8_LAS unsigned*)(lds + (bufoff) + ldsw + _i * 8192), 16, 0, 0); } while (0)
; #define PG8_LDA(dst, b, h) do { _Pragma("unroll") for (int m = 0; m < 4; ++m) _Pragma("unroll") for (int k = 0; k < 2; ++k) dst[m][k] = *(const PG8_LAS bf16x8*)(lds + PG8_SA(b, h) + aoff + m * 2048 + k * 1024); } while (0)
; #define PG8_MMA(ai, bj, At, Bt) do { __builtin_amdgcn_s_setprio(1); _Pragma("unroll") for (int m = 0; m < 4; ++m) _Pragma("unroll") for (int n = 0; n < 2; ++n) _Pragma("unroll") for (int k = 0; k < 2; ++k) \
;         acc[ai][bj][m][n] = __builtin_amdgcn_mfma_f32_16x16x32_bf16(Bt[n][k], At[m][k], acc[ai][bj][m][n], 0, 0, 0); __builtin_amdgcn_s_setprio(0); } while (0)
; #define PG8_WAIT_V(n) asm volatile("s_waitcnt vmcnt(" #n ")" ::: "memory")
; #define PG8_WAIT_L(n) asm volatile("s_waitcnt lgkmcnt(" #n ")" ::: "memory")
; #define PG8_BAR __builtin_amdgcn_s_barrier()
; #define PG8_SCHED __builtin_amdgcn_sched_barrier(0)
; template <class Epi, class Sched, bool ALIGN_EPI = false, bool SP2 = false>
; __device__ __forceinline__ void gemm_phase(PG8_LAS unsigned char* lds, const Gemm g, const Sched& S, const Epi& E) {
;     ...
;             PG8_LDA(At, 1, 1); PG8_STAGE(PG8_SB(1, 0), b3, voffB); PG8_STAGE(PG8_SB(1, 1), b3 + hstep, voffB); PG8_STAGE(PG8_SA(1, 0), a3, voffA);
;             PG8_WAIT_V(8); PG8_WAIT_L(0); PG8_BAR; PG8_MMA(1, 0, At, B0); PG8_MMA(1, 1, At, B1); PG8_BAR; PG8_SCHED;
	s_add_i32 s54, s56, s2
	v_lshl_add_u64 v[140:141], v[140:141], 0, s[20:21]
	s_mov_b32 m0, s54
	ds_read_b128 v[178:181], v145 offset:49152
	ds_read_b128 v[182:185], v145 offset:50176
	ds_read_b128 v[186:189], v145 offset:51200
	ds_read_b128 v[190:193], v145 offset:52224
	ds_read_b128 v[220:223], v145 offset:53248
	ds_read_b128 v[224:227], v145 offset:54272
	ds_read_b128 v[228:231], v145 offset:55296
	ds_read_b128 v[232:235], v145 offset:56320
	global_load_lds_dwordx4 v[140:141], off
	s_add_i32 m0, s54, 0x2000
	s_add_u32 s52, s52, 0x80080
	v_lshl_add_u64 v[140:141], v[206:207], 0, s[20:21]
	s_addc_u32 s53, s53, 0
	s_add_i32 s54, s57, s2
	global_load_lds_dwordx4 v[140:141], off
	v_lshl_add_u64 v[140:141], s[52:53], 0, v[128:129]
	s_mov_b32 m0, s54
	s_nop 0
	global_load_lds_dwordx4 v[140:141], off
	v_lshl_add_u64 v[140:141], s[52:53], 0, v[130:131]
	s_add_i32 m0, s54, 0x2000
	s_nop 0
	global_load_lds_dwordx4 v[140:141], off
	v_lshl_add_u64 v[140:141], v[214:215], 0, s[20:21]
	s_mov_b32 m0, s28
	s_nop 0
	global_load_lds_dwordx4 v[140:141], off
	v_lshl_add_u64 v[140:141], v[216:217], 0, s[20:21]
	s_mov_b32 m0, s29
	s_nop 0
	global_load_lds_dwordx4 v[140:141], off
	s_waitcnt vmcnt(8)
	s_waitcnt lgkmcnt(0)
	s_barrier
	s_setprio 1
	s_waitcnt lgkmcnt(0)
	v_mfma_f32_16x16x32_bf16 v[60:63], v[146:149], v[178:181], v[60:63]
	v_mfma_f32_16x16x32_bf16 v[56:59], v[154:157], v[178:181], v[56:59]
	v_mfma_f32_16x16x32_bf16 v[52:55], v[146:149], v[186:189], v[52:55]
	v_mfma_f32_16x16x32_bf16 v[44:47], v[154:157], v[186:189], v[44:47]
	v_mfma_f32_16x16x32_bf16 v[36:39], v[146:149], v[220:223], v[36:39]
	v_mfma_f32_16x16x32_bf16 v[28:31], v[154:157], v[220:223], v[28:31]
	v_mfma_f32_16x16x32_bf16 v[20:23], v[146:149], v[228:231], v[20:23]
	v_mfma_f32_16x16x32_bf16 v[12:15], v[154:157], v[228:231], v[12:15]
	v_mfma_f32_16x16x32_bf16 v[60:63], v[150:153], v[182:185], v[60:63]
	v_mfma_f32_16x16x32_bf16 v[56:59], v[158:161], v[182:185], v[56:59]
	v_mfma_f32_16x16x32_bf16 v[52:55], v[150:153], v[190:193], v[52:55]
	v_mfma_f32_16x16x32_bf16 v[44:47], v[158:161], v[190:193], v[44:47]
	v_mfma_f32_16x16x32_bf16 v[36:39], v[150:153], v[224:227], v[36:39]
	v_mfma_f32_16x16x32_bf16 v[28:31], v[158:161], v[224:227], v[28:31]
	v_mfma_f32_16x16x32_bf16 v[20:23], v[150:153], v[232:235], v[20:23]
	v_mfma_f32_16x16x32_bf16 v[12:15], v[158:161], v[232:235], v[12:15]
	s_setprio 0
	s_setprio 1
	v_mfma_f32_16x16x32_bf16 v[48:51], v[162:165], v[178:181], v[48:51]
	v_mfma_f32_16x16x32_bf16 v[40:43], v[170:173], v[178:181], v[40:43]
	v_mfma_f32_16x16x32_bf16 v[32:35], v[162:165], v[186:189], v[32:35]
	v_mfma_f32_16x16x32_bf16 v[24:27], v[170:173], v[186:189], v[24:27]
	v_mfma_f32_16x16x32_bf16 v[16:19], v[162:165], v[220:223], v[16:19]
	v_mfma_f32_16x16x32_bf16 v[8:11], v[170:173], v[220:223], v[8:11]
	v_mfma_f32_16x16x32_bf16 v[4:7], v[162:165], v[228:231], v[4:7]
	v_mfma_f32_16x16x32_bf16 v[0:3], v[170:173], v[228:231], v[0:3]
	v_mfma_f32_16x16x32_bf16 v[48:51], v[166:169], v[182:185], v[48:51]
	v_mfma_f32_16x16x32_bf16 v[40:43], v[174:177], v[182:185], v[40:43]
	v_mfma_f32_16x16x32_bf16 v[32:35], v[166:169], v[190:193], v[32:35]
	v_mfma_f32_16x16x32_bf16 v[24:27], v[174:177], v[190:193], v[24:27]
	v_mfma_f32_16x16x32_bf16 v[16:19], v[166:169], v[224:227], v[16:19]
	v_mfma_f32_16x16x32_bf16 v[8:11], v[174:177], v[224:227], v[8:11]
	v_mfma_f32_16x16x32_bf16 v[4:7], v[166:169], v[232:235], v[4:7]
	v_mfma_f32_16x16x32_bf16 v[0:3], v[174:177], v[232:235], v[0:3]
	s_setprio 0
	s_barrier
	s_add_i32 s45, s45, 2
	s_add_u32 s50, s50, 0x100
	s_addc_u32 s51, s51, 0
	s_add_u32 s37, s37, 0x100
	s_addc_u32 s43, s43, 0
	s_cmp_gt_u32 s45, 29
	s_cbranch_scc0 .LBB0_305
	s_and_b64 vcc, exec, s[12:13]
	s_cbranch_vccz .LBB0_308
	s_barrier

; #define PG8_STAGE(bufoff, gbase, voff) do { _Pragma("unroll") for (int _i = 0; _i < 2; ++_i) \
;         __builtin_amdgcn_global_load_lds((const unsigned*)((const char*)(gbase) + (voff)[_i]), (PG8_LAS unsigned*)(lds + (bufoff) + ldsw + _i * 8192), 16, 0, 0); } while (0)
; #define PG8_LDA(dst, b, h) do { _Pragma("unroll") for (int m = 0; m < 4; ++m) _Pragma("unroll") for (int k = 0; k < 2; ++k) dst[m][k] = *(const PG8_LAS bf16x8*)(lds + PG8_SA(b, h) + aoff + m * 2048 + k * 1024); } while (0)
; #define PG8_MMA(ai, bj, At, Bt) do { __builtin_amdgcn_s_setprio(1); _Pragma("unroll") for (int m = 0; m < 4; ++m) _Pragma("unroll") for (int n = 0; n < 2; ++n) _Pragma("unroll") for (int k = 0; k < 2; ++k) \
;         acc[ai][bj][m][n] = __builtin_amdgcn_mfma_f32_16x16x32_bf16(Bt[n][k], At[m][k], acc[ai][bj][m][n], 0, 0, 0); __builtin_amdgcn_s_setprio(0); } while (0)
; #define PG8_WAIT_V(n) asm volatile("s_waitcnt vmcnt(" #n ")" ::: "memory")
; #define PG8_WAIT_L(n) asm volatile("s_waitcnt lgkmcnt(" #n ")" ::: "memory")
; #define PG8_BAR __builtin_amdgcn_s_barrier()
; #define PG8_SCHED __builtin_amdgcn_sched_barrier(0)
; template <class Epi, class Sched, bool ALIGN_EPI = false, bool SP2 = false>
; __device__ __forceinline__ void gemm_phase(PG8_LAS unsigned char* lds, const Gemm g, const Sched& S, const Epi& E) {
;     ...
;             PG8_WAIT_V(8); PG8_WAIT_L(0); PG8_BAR; PG8_MMA(0, 0, At, B0); PG8_MMA(0, 1, At, B1); PG8_BAR; PG8_SCHED;
;             PG8_LDA(At, 0, 1); PG8_STAGE(PG8_SB(0, 0), b2, voffB); PG8_STAGE(PG8_SB(0, 1), b2 + hstep, voffB); PG8_STAGE(PG8_SA(0, 0), a2, voffA);
.Lrx10_0_join:
	s_waitcnt lgkmcnt(0)
	s_barrier
	s_setprio 1
	s_waitcnt lgkmcnt(0)
	v_mfma_f32_16x16x32_bf16 v[124:127], v[146:149], v[178:181], v[124:127]
	v_mfma_f32_16x16x32_bf16 v[120:123], v[154:157], v[178:181], v[120:123]
	v_mfma_f32_16x16x32_bf16 v[116:119], v[146:149], v[186:189], v[116:119]
	v_mfma_f32_16x16x32_bf16 v[108:111], v[154:157], v[186:189], v[108:111]
	v_mfma_f32_16x16x32_bf16 v[100:103], v[146:149], v[220:223], v[100:103]
	v_mfma_f32_16x16x32_bf16 v[92:95], v[154:157], v[220:223], v[92:95]
	v_mfma_f32_16x16x32_bf16 v[84:87], v[146:149], v[228:231], v[84:87]
	v_mfma_f32_16x16x32_bf16 v[76:79], v[154:157], v[228:231], v[76:79]
	v_mfma_f32_16x16x32_bf16 v[124:127], v[150:153], v[182:185], v[124:127]
	v_mfma_f32_16x16x32_bf16 v[120:123], v[158:161], v[182:185], v[120:123]
	v_mfma_f32_16x16x32_bf16 v[116:119], v[150:153], v[190:193], v[116:119]
	v_mfma_f32_16x16x32_bf16 v[108:111], v[158:161], v[190:193], v[108:111]
	v_mfma_f32_16x16x32_bf16 v[100:103], v[150:153], v[224:227], v[100:103]
	v_mfma_f32_16x16x32_bf16 v[92:95], v[158:161], v[224:227], v[92:95]
	v_mfma_f32_16x16x32_bf16 v[84:87], v[150:153], v[232:235], v[84:87]
	v_mfma_f32_16x16x32_bf16 v[76:79], v[158:161], v[232:235], v[76:79]
	s_setprio 0
	s_setprio 1
	v_mfma_f32_16x16x32_bf16 v[112:115], v[162:165], v[178:181], v[112:115]
	v_mfma_f32_16x16x32_bf16 v[104:107], v[170:173], v[178:181], v[104:107]
	v_mfma_f32_16x16x32_bf16 v[96:99], v[162:165], v[186:189], v[96:99]
	v_mfma_f32_16x16x32_bf16 v[88:91], v[170:173], v[186:189], v[88:91]
	v_mfma_f32_16x16x32_bf16 v[80:83], v[162:165], v[220:223], v[80:83]
	v_mfma_f32_16x16x32_bf16 v[72:75], v[170:173], v[220:223], v[72:75]
	v_mfma_f32_16x16x32_bf16 v[68:71], v[162:165], v[228:231], v[68:71]
	v_mfma_f32_16x16x32_bf16 v[64:67], v[170:173], v[228:231], v[64:67]
	v_mfma_f32_16x16x32_bf16 v[112:115], v[166:169], v[182:185], v[112:115]
	v_mfma_f32_16x16x32_bf16 v[104:107], v[174:177], v[182:185], v[104:107]
	v_mfma_f32_16x16x32_bf16 v[96:99], v[166:169], v[190:193], v[96:99]
	v_mfma_f32_16x16x32_bf16 v[88:91], v[174:177], v[190:193], v[88:91]
	v_mfma_f32_16x16x32_bf16 v[80:83], v[166:169], v[224:227], v[80:83]
	v_mfma_f32_16x16x32_bf16 v[72:75], v[174:177], v[224:227], v[72:75]
	v_mfma_f32_16x16x32_bf16 v[68:71], v[166:169], v[232:235], v[68:71]
	v_mfma_f32_16x16x32_bf16 v[64:67], v[174:177], v[232:235], v[64:67]
	s_setprio 0
	s_barrier
	s_add_i32 s56, s56, s2
	v_lshl_add_u64 v[140:141], s[52:53], 0, v[128:129]
	s_mov_b32 m0, s56
	ds_read_b128 v[178:181], v145 offset:16384
	ds_read_b128 v[182:185], v145 offset:17408
	ds_read_b128 v[186:189], v145 offset:18432
	ds_read_b128 v[190:193], v145 offset:19456
	ds_read_b128 v[220:223], v145 offset:20480
	ds_read_b128 v[224:227], v145 offset:21504
	ds_read_b128 v[228:231], v145 offset:22528
	ds_read_b128 v[232:235], v145 offset:23552
	global_load_lds_dwordx4 v[140:141], off
	s_add_i32 m0, s56, 0x2000
	s_add_u32 s56, s52, 0x20000
	v_lshl_add_u64 v[206:207], s[52:53], 0, v[130:131]
	s_addc_u32 s57, s53, 0
	s_add_i32 s58, s58, s2
	global_load_lds_dwordx4 v[206:207], off
	v_lshl_add_u64 v[214:215], s[56:57], 0, v[128:129]
	s_mov_b32 m0, s58
	v_lshl_add_u64 v[216:217], s[54:55], 0, v[132:133]
	global_load_lds_dwordx4 v[214:215], off
	v_lshl_add_u64 v[214:215], s[56:57], 0, v[130:131]
	s_add_i32 m0, s58, 0x2000
	s_nop 0
	global_load_lds_dwordx4 v[214:215], off
	v_lshl_add_u64 v[214:215], s[54:55], 0, v[134:135]
	s_mov_b32 m0, s10
	s_nop 0
	global_load_lds_dwordx4 v[214:215], off
	s_mov_b32 m0, s17
	s_nop 0
	global_load_lds_dwordx4 v[216:217], off
	s_cmp_lt_i32 s45, 0
	s_cbranch_scc0 .Lrx10_1_norm
	s_cmp_lt_u32 s33, 2
	s_cbranch_scc1 .Lrx10_1_norm
	s_waitcnt vmcnt(24)
	s_branch .Lrx10_1_join

; #define PG8_STAGE(bufoff, gbase, voff) do { _Pragma("unroll") for (int _i = 0; _i < 2; ++_i) \
;         __builtin_amdgcn_global_load_lds((const unsigned*)((const char*)(gbase) + (voff)[_i]), (PG8_LAS unsigned*)(lds + (bufoff) + ldsw + _i * 8192), 16, 0, 0); } while (0)
; #define PG8_LDA(dst, b, h) do { _Pragma("unroll") for (int m = 0; m < 4; ++m) _Pragma("unroll") for (int k = 0; k < 2; ++k) dst[m][k] = *(const PG8_LAS bf16x8*)(lds + PG8_SA(b, h) + aoff + m * 2048 + k * 1024); } while (0)
; #define PG8_LDB(dst, b, h) do { _Pragma("unroll") for (int n = 0; n < 2; ++n) _Pragma("unroll") for (int k = 0; k < 2; ++k) dst[n][k] = *(const PG8_LAS bf16x8*)(lds + PG8_SB(b, h) + boff + n * 2048 + k * 1024); } while (0)
; #define PG8_MMA(ai, bj, At, Bt) do { __builtin_amdgcn_s_setprio(1); _Pragma("unroll") for (int m = 0; m < 4; ++m) _Pragma("unroll") for (int n = 0; n < 2; ++n) _Pragma("unroll") for (int k = 0; k < 2; ++k) \
;         acc[ai][bj][m][n] = __builtin_amdgcn_mfma_f32_16x16x32_bf16(Bt[n][k], At[m][k], acc[ai][bj][m][n], 0, 0, 0); __builtin_amdgcn_s_setprio(0); } while (0)
; #define PG8_WAIT_V(n) asm volatile("s_waitcnt vmcnt(" #n ")" ::: "memory")
; #define PG8_WAIT_L(n) asm volatile("s_waitcnt lgkmcnt(" #n ")" ::: "memory")
; #define PG8_BAR __builtin_amdgcn_s_barrier()
; #define PG8_SCHED __builtin_amdgcn_sched_barrier(0)
; template <class Epi, class Sched, bool ALIGN_EPI = false, bool SP2 = false>
; __device__ __forceinline__ void gemm_phase(PG8_LAS unsigned char* lds, const Gemm g, const Sched& S, const Epi& E) {
;     ...
;             PG8_WAIT_V(8); PG8_WAIT_L(0); PG8_BAR; PG8_MMA(1, 0, At, B0); PG8_MMA(1, 1, At, B1); PG8_BAR; PG8_SCHED;
;             PG8_LDB(B0, 1, 0); PG8_LDB(B1, 1, 1); PG8_SCHED; PG8_LDA(At, 1, 0); PG8_STAGE(PG8_SA(0, 1), a2 + hstep, voffA);
;             PG8_WAIT_V(8); PG8_WAIT_L(0); PG8_BAR; PG8_MMA(0, 0, At, B0); PG8_MMA(0, 1, At, B1); PG8_BAR; PG8_SCHED;
.Lrx10_1_join:
	s_waitcnt lgkmcnt(0)
	s_barrier
	s_setprio 1
	s_waitcnt lgkmcnt(0)
	v_mfma_f32_16x16x32_bf16 v[60:63], v[146:149], v[178:181], v[60:63]
	v_mfma_f32_16x16x32_bf16 v[56:59], v[154:157], v[178:181], v[56:59]
	v_mfma_f32_16x16x32_bf16 v[52:55], v[146:149], v[186:189], v[52:55]
	v_mfma_f32_16x16x32_bf16 v[44:47], v[154:157], v[186:189], v[44:47]
	v_mfma_f32_16x16x32_bf16 v[36:39], v[146:149], v[220:223], v[36:39]
	v_mfma_f32_16x16x32_bf16 v[28:31], v[154:157], v[220:223], v[28:31]
	v_mfma_f32_16x16x32_bf16 v[20:23], v[146:149], v[228:231], v[20:23]
	v_mfma_f32_16x16x32_bf16 v[12:15], v[154:157], v[228:231], v[12:15]
	v_mfma_f32_16x16x32_bf16 v[60:63], v[150:153], v[182:185], v[60:63]
	v_mfma_f32_16x16x32_bf16 v[56:59], v[158:161], v[182:185], v[56:59]
	v_mfma_f32_16x16x32_bf16 v[52:55], v[150:153], v[190:193], v[52:55]
	v_mfma_f32_16x16x32_bf16 v[44:47], v[158:161], v[190:193], v[44:47]
	v_mfma_f32_16x16x32_bf16 v[36:39], v[150:153], v[224:227], v[36:39]
	v_mfma_f32_16x16x32_bf16 v[28:31], v[158:161], v[224:227], v[28:31]
	v_mfma_f32_16x16x32_bf16 v[20:23], v[150:153], v[232:235], v[20:23]
	v_mfma_f32_16x16x32_bf16 v[12:15], v[158:161], v[232:235], v[12:15]
	s_setprio 0
	s_setprio 1
	v_mfma_f32_16x16x32_bf16 v[48:51], v[162:165], v[178:181], v[48:51]
	v_mfma_f32_16x16x32_bf16 v[40:43], v[170:173], v[178:181], v[40:43]
	v_mfma_f32_16x16x32_bf16 v[32:35], v[162:165], v[186:189], v[32:35]
	v_mfma_f32_16x16x32_bf16 v[24:27], v[170:173], v[186:189], v[24:27]
	v_mfma_f32_16x16x32_bf16 v[16:19], v[162:165], v[220:223], v[16:19]
	v_mfma_f32_16x16x32_bf16 v[8:11], v[170:173], v[220:223], v[8:11]
	v_mfma_f32_16x16x32_bf16 v[4:7], v[162:165], v[228:231], v[4:7]
	v_mfma_f32_16x16x32_bf16 v[0:3], v[170:173], v[228:231], v[0:3]
	v_mfma_f32_16x16x32_bf16 v[48:51], v[166:169], v[182:185], v[48:51]
	v_mfma_f32_16x16x32_bf16 v[40:43], v[174:177], v[182:185], v[40:43]
	v_mfma_f32_16x16x32_bf16 v[32:35], v[166:169], v[190:193], v[32:35]
	v_mfma_f32_16x16x32_bf16 v[24:27], v[174:177], v[190:193], v[24:27]
	v_mfma_f32_16x16x32_bf16 v[16:19], v[166:169], v[224:227], v[16:19]
	v_mfma_f32_16x16x32_bf16 v[8:11], v[174:177], v[224:227], v[8:11]
	v_mfma_f32_16x16x32_bf16 v[4:7], v[166:169], v[232:235], v[4:7]
	v_mfma_f32_16x16x32_bf16 v[0:3], v[174:177], v[232:235], v[0:3]
	s_setprio 0
	s_barrier
	s_add_i32 s56, 0, 0x18000
	s_add_i32 s57, 0, 0x1c000
	v_add_u32_e32 v158, s56, v143
	v_add_u32_e32 v174, s57, v143
	ds_read_b128 v[146:149], v158
	ds_read_b128 v[150:153], v158 offset:1024
	ds_read_b128 v[154:157], v158 offset:2048
	ds_read_b128 v[158:161], v158 offset:3072
	ds_read_b128 v[162:165], v174
	ds_read_b128 v[166:169], v174 offset:1024
	ds_read_b128 v[170:173], v174 offset:2048
	ds_read_b128 v[174:177], v174 offset:3072
	s_add_u32 s54, s54, 0x80000
	s_addc_u32 s55, s55, 0
	s_mov_b32 m0, s26
	v_lshl_add_u64 v[236:237], s[54:55], 0, v[134:135]
	ds_read_b128 v[178:181], v145 offset:32768
	ds_read_b128 v[182:185], v145 offset:33792
	ds_read_b128 v[186:189], v145 offset:34816
	ds_read_b128 v[190:193], v145 offset:35840
	ds_read_b128 v[220:223], v145 offset:36864
	ds_read_b128 v[224:227], v145 offset:37888
	ds_read_b128 v[228:231], v145 offset:38912
	ds_read_b128 v[232:235], v145 offset:39936
	global_load_lds_dwordx4 v[236:237], off
	v_lshl_add_u64 v[236:237], s[54:55], 0, v[132:133]
	s_mov_b32 m0, s27
	s_nop 0
	global_load_lds_dwordx4 v[236:237], off
	s_waitcnt vmcnt(8)
	s_waitcnt lgkmcnt(0)
	s_barrier
	s_setprio 1
	s_waitcnt lgkmcnt(0)
	v_mfma_f32_16x16x32_bf16 v[124:127], v[146:149], v[178:181], v[124:127]
	v_mfma_f32_16x16x32_bf16 v[120:123], v[154:157], v[178:181], v[120:123]
	v_mfma_f32_16x16x32_bf16 v[116:119], v[146:149], v[186:189], v[116:119]
	v_mfma_f32_16x16x32_bf16 v[108:111], v[154:157], v[186:189], v[108:111]
	v_mfma_f32_16x16x32_bf16 v[100:103], v[146:149], v[220:223], v[100:103]
	v_mfma_f32_16x16x32_bf16 v[92:95], v[154:157], v[220:223], v[92:95]
	v_mfma_f32_16x16x32_bf16 v[84:87], v[146:149], v[228:231], v[84:87]
	v_mfma_f32_16x16x32_bf16 v[76:79], v[154:157], v[228:231], v[76:79]
	v_mfma_f32_16x16x32_bf16 v[124:127], v[150:153], v[182:185], v[124:127]
	v_mfma_f32_16x16x32_bf16 v[120:123], v[158:161], v[182:185], v[120:123]
	v_mfma_f32_16x16x32_bf16 v[116:119], v[150:153], v[190:193], v[116:119]
	v_mfma_f32_16x16x32_bf16 v[108:111], v[158:161], v[190:193], v[108:111]
	v_mfma_f32_16x16x32_bf16 v[100:103], v[150:153], v[224:227], v[100:103]
	v_mfma_f32_16x16x32_bf16 v[92:95], v[158:161], v[224:227], v[92:95]
	v_mfma_f32_16x16x32_bf16 v[84:87], v[150:153], v[232:235], v[84:87]
	v_mfma_f32_16x16x32_bf16 v[76:79], v[158:161], v[232:235], v[76:79]
	s_setprio 0
	s_setprio 1
	v_mfma_f32_16x16x32_bf16 v[112:115], v[162:165], v[178:181], v[112:115]
	v_mfma_f32_16x16x32_bf16 v[104:107], v[170:173], v[178:181], v[104:107]
	v_mfma_f32_16x16x32_bf16 v[96:99], v[162:165], v[186:189], v[96:99]
	v_mfma_f32_16x16x32_bf16 v[88:91], v[170:173], v[186:189], v[88:91]
	v_mfma_f32_16x16x32_bf16 v[80:83], v[162:165], v[220:223], v[80:83]
	v_mfma_f32_16x16x32_bf16 v[72:75], v[170:173], v[220:223], v[72:75]
	v_mfma_f32_16x16x32_bf16 v[68:71], v[162:165], v[228:231], v[68:71]
	v_mfma_f32_16x16x32_bf16 v[64:67], v[170:173], v[228:231], v[64:67]
	v_mfma_f32_16x16x32_bf16 v[112:115], v[166:169], v[182:185], v[112:115]
	v_mfma_f32_16x16x32_bf16 v[104:107], v[174:177], v[182:185], v[104:107]
	v_mfma_f32_16x16x32_bf16 v[96:99], v[166:169], v[190:193], v[96:99]
	v_mfma_f32_16x16x32_bf16 v[88:91], v[174:177], v[190:193], v[88:91]
	v_mfma_f32_16x16x32_bf16 v[80:83], v[166:169], v[224:227], v[80:83]
	v_mfma_f32_16x16x32_bf16 v[72:75], v[174:177], v[224:227], v[72:75]
	v_mfma_f32_16x16x32_bf16 v[68:71], v[166:169], v[232:235], v[68:71]
	v_mfma_f32_16x16x32_bf16 v[64:67], v[174:177], v[232:235], v[64:67]
	s_setprio 0
	s_barrier
; #define PG8_STAGE(bufoff, gbase, voff) do { _Pragma("unroll") for (int _i = 0; _i < 2; ++_i) \
;         __builtin_amdgcn_global_load_lds((const unsigned*)((const char*)(gbase) + (voff)[_i]), (PG8_LAS unsigned*)(lds + (bufoff) + ldsw + _i * 8192), 16, 0, 0); } while (0)
; #define PG8_LDA(dst, b, h) do { _Pragma("unroll") for (int m = 0; m < 4; ++m) _Pragma("unroll") for (int k = 0; k < 2; ++k) dst[m][k] = *(const PG8_LAS bf16x8*)(lds + PG8_SA(b, h) + aoff + m * 2048 + k * 1024); } while (0)
; #define PG8_LDB(dst, b, h) do { _Pragma("unroll") for (int n = 0; n < 2; ++n) _Pragma("unroll") for (int k = 0; k < 2; ++k) dst[n][k] = *(const PG8_LAS bf16x8*)(lds + PG8_SB(b, h) + boff + n * 2048 + k * 1024); } while (0)
; #define PG8_MMA(ai, bj, At, Bt) do { __builtin_amdgcn_s_setprio(1); _Pragma("unroll") for (int m = 0; m < 4; ++m) _Pragma("unroll") for (int n = 0; n < 2; ++n) _Pragma("unroll") for (int k = 0; k < 2; ++k) \
;         acc[ai][bj][m][n] = __builtin_amdgcn_mfma_f32_16x16x32_bf16(Bt[n][k], At[m][k], acc[ai][bj][m][n], 0, 0, 0); __builtin_amdgcn_s_setprio(0); } while (0)
; #define PG8_WAIT_V(n) asm volatile("s_waitcnt vmcnt(" #n ")" ::: "memory")
; #define PG8_WAIT_L(n) asm volatile("s_waitcnt lgkmcnt(" #n ")" ::: "memory")
; #define PG8_BAR __builtin_amdgcn_s_barrier()
; #define PG8_SCHED __builtin_amdgcn_sched_barrier(0)
; template <class Epi, class Sched, bool ALIGN_EPI = false, bool SP2 = false>
; __device__ __forceinline__ void gemm_phase(PG8_LAS unsigned char* lds, const Gemm g, const Sched& S, const Epi& E) {
;     ...
;             PG8_LDA(At, 0, 1); PG8_STAGE(PG8_SB(0, 0), b2, voffB); PG8_STAGE(PG8_SB(0, 1), b2 + hstep, voffB); PG8_STAGE(PG8_SA(0, 0), a2, voffA);
;             PG8_WAIT_V(8); PG8_WAIT_L(0); PG8_BAR; PG8_MMA(1, 0, At, B0); PG8_MMA(1, 1, At, B1); PG8_BAR; PG8_SCHED;
;             PG8_LDB(B0, 1, 0); PG8_LDB(B1, 1, 1); PG8_SCHED; PG8_LDA(At, 1, 0); PG8_STAGE(PG8_SA(0, 1), a2 + hstep, voffA);
;             PG8_WAIT_V(8); PG8_WAIT_L(0); PG8_BAR; PG8_MMA(0, 0, At, B0); PG8_MMA(0, 1, At, B1); PG8_BAR; PG8_SCHED;
;             PG8_LDA(At, 1, 1); PG8_STAGE(PG8_SB(1, 0), b3, voffB); PG8_STAGE(PG8_SB(1, 1), b3 + hstep, voffB); PG8_STAGE(PG8_SA(1, 0), a3, voffA);
;             PG8_WAIT_V(8); PG8_WAIT_L(0); PG8_BAR; PG8_MMA(1, 0, At, B0); PG8_MMA(1, 1, At, B1); PG8_BAR; PG8_SCHED;
	s_add_i32 s54, s56, s2
	v_lshl_add_u64 v[140:141], v[140:141], 0, s[20:21]
	s_mov_b32 m0, s54
	ds_read_b128 v[178:181], v145 offset:49152
	ds_read_b128 v[182:185], v145 offset:50176
	ds_read_b128 v[186:189], v145 offset:51200
	ds_read_b128 v[190:193], v145 offset:52224
	ds_read_b128 v[220:223], v145 offset:53248
	ds_read_b128 v[224:227], v145 offset:54272
	ds_read_b128 v[228:231], v145 offset:55296
	ds_read_b128 v[232:235], v145 offset:56320
	global_load_lds_dwordx4 v[140:141], off
	s_add_i32 m0, s54, 0x2000
	s_add_u32 s52, s52, 0x20080
	v_lshl_add_u64 v[140:141], v[206:207], 0, s[20:21]
	s_addc_u32 s53, s53, 0
	s_add_i32 s54, s57, s2
	global_load_lds_dwordx4 v[140:141], off
	v_lshl_add_u64 v[140:141], s[52:53], 0, v[128:129]
	s_mov_b32 m0, s54
	s_nop 0
	global_load_lds_dwordx4 v[140:141], off
	v_lshl_add_u64 v[140:141], s[52:53], 0, v[130:131]
	s_add_i32 m0, s54, 0x2000
	s_nop 0
	global_load_lds_dwordx4 v[140:141], off
	v_lshl_add_u64 v[140:141], v[214:215], 0, s[20:21]
	s_mov_b32 m0, s28
	s_nop 0
	global_load_lds_dwordx4 v[140:141], off
	v_lshl_add_u64 v[140:141], v[216:217], 0, s[20:21]
	s_mov_b32 m0, s29
	s_nop 0
	global_load_lds_dwordx4 v[140:141], off
	s_waitcnt vmcnt(8)
	s_waitcnt lgkmcnt(0)
	s_barrier
	s_setprio 1
	s_waitcnt lgkmcnt(0)
	v_mfma_f32_16x16x32_bf16 v[60:63], v[146:149], v[178:181], v[60:63]
	v_mfma_f32_16x16x32_bf16 v[56:59], v[154:157], v[178:181], v[56:59]
	v_mfma_f32_16x16x32_bf16 v[52:55], v[146:149], v[186:189], v[52:55]
	v_mfma_f32_16x16x32_bf16 v[44:47], v[154:157], v[186:189], v[44:47]
	v_mfma_f32_16x16x32_bf16 v[36:39], v[146:149], v[220:223], v[36:39]
	v_mfma_f32_16x16x32_bf16 v[28:31], v[154:157], v[220:223], v[28:31]
	v_mfma_f32_16x16x32_bf16 v[20:23], v[146:149], v[228:231], v[20:23]
	v_mfma_f32_16x16x32_bf16 v[12:15], v[154:157], v[228:231], v[12:15]
	v_mfma_f32_16x16x32_bf16 v[60:63], v[150:153], v[182:185], v[60:63]
	v_mfma_f32_16x16x32_bf16 v[56:59], v[158:161], v[182:185], v[56:59]
	v_mfma_f32_16x16x32_bf16 v[52:55], v[150:153], v[190:193], v[52:55]
	v_mfma_f32_16x16x32_bf16 v[44:47], v[158:161], v[190:193], v[44:47]
	v_mfma_f32_16x16x32_bf16 v[36:39], v[150:153], v[224:227], v[36:39]
	v_mfma_f32_16x16x32_bf16 v[28:31], v[158:161], v[224:227], v[28:31]
	v_mfma_f32_16x16x32_bf16 v[20:23], v[150:153], v[232:235], v[20:23]
	v_mfma_f32_16x16x32_bf16 v[12:15], v[158:161], v[232:235], v[12:15]
	s_setprio 0
	s_setprio 1
	v_mfma_f32_16x16x32_bf16 v[48:51], v[162:165], v[178:181], v[48:51]
	v_mfma_f32_16x16x32_bf16 v[40:43], v[170:173], v[178:181], v[40:43]
	v_mfma_f32_16x16x32_bf16 v[32:35], v[162:165], v[186:189], v[32:35]
	v_mfma_f32_16x16x32_bf16 v[24:27], v[170:173], v[186:189], v[24:27]
	v_mfma_f32_16x16x32_bf16 v[16:19], v[162:165], v[220:223], v[16:19]
	v_mfma_f32_16x16x32_bf16 v[8:11], v[170:173], v[220:223], v[8:11]
	v_mfma_f32_16x16x32_bf16 v[4:7], v[162:165], v[228:231], v[4:7]
	v_mfma_f32_16x16x32_bf16 v[0:3], v[170:173], v[228:231], v[0:3]
	v_mfma_f32_16x16x32_bf16 v[48:51], v[166:169], v[182:185], v[48:51]
	v_mfma_f32_16x16x32_bf16 v[40:43], v[174:177], v[182:185], v[40:43]
	v_mfma_f32_16x16x32_bf16 v[32:35], v[166:169], v[190:193], v[32:35]
	v_mfma_f32_16x16x32_bf16 v[24:27], v[174:177], v[190:193], v[24:27]
	v_mfma_f32_16x16x32_bf16 v[16:19], v[166:169], v[224:227], v[16:19]
	v_mfma_f32_16x16x32_bf16 v[8:11], v[174:177], v[224:227], v[8:11]
	v_mfma_f32_16x16x32_bf16 v[4:7], v[166:169], v[232:235], v[4:7]
	v_mfma_f32_16x16x32_bf16 v[0:3], v[174:177], v[232:235], v[0:3]
	s_setprio 0
	s_barrier
	s_add_i32 s45, s45, 2
	s_add_u32 s50, s50, 0x100
	s_addc_u32 s51, s51, 0
	s_add_u32 s37, s37, 0x100
	s_addc_u32 s43, s43, 0
	s_cmp_gt_u32 s45, 29
	s_cbranch_scc0 .LBB0_327
	s_and_b64 vcc, exec, s[12:13]
	s_cbranch_vccz .LBB0_330
	s_barrier

; #define PG8_STAGE(bufoff, gbase, voff) do { _Pragma("unroll") for (int _i = 0; _i < 2; ++_i) \
;         __builtin_amdgcn_global_load_lds((const unsigned*)((const char*)(gbase) + (voff)[_i]), (PG8_LAS unsigned*)(lds + (bufoff) + ldsw + _i * 8192), 16, 0, 0); } while (0)
; #define PG8_LDA(dst, b, h) do { _Pragma("unroll") for (int m = 0; m < 4; ++m) _Pragma("unroll") for (int k = 0; k < 2; ++k) dst[m][k] = *(const PG8_LAS bf16x8*)(lds + PG8_SA(b, h) + aoff + m * 2048 + k * 1024); } while (0)
; #define PG8_LDB(dst, b, h) do { _Pragma("unroll") for (int n = 0; n < 2; ++n) _Pragma("unroll") for (int k = 0; k < 2; ++k) dst[n][k] = *(const PG8_LAS bf16x8*)(lds + PG8_SB(b, h) + boff + n * 2048 + k * 1024); } while (0)
; #define PG8_MMA(ai, bj, At, Bt) do { __builtin_amdgcn_s_setprio(1); _Pragma("unroll") for (int m = 0; m < 4; ++m) _Pragma("unroll") for (int n = 0; n < 2; ++n) _Pragma("unroll") for (int k = 0; k < 2; ++k) \
;         acc[ai][bj][m][n] = __builtin_amdgcn_mfma_f32_16x16x32_bf16(Bt[n][k], At[m][k], acc[ai][bj][m][n], 0, 0, 0); __builtin_amdgcn_s_setprio(0); } while (0)
; #define PG8_WAIT_V(n) asm volatile("s_waitcnt vmcnt(" #n ")" ::: "memory")
; #define PG8_WAIT_L(n) asm volatile("s_waitcnt lgkmcnt(" #n ")" ::: "memory")
; #define PG8_BAR __builtin_amdgcn_s_barrier()
; #define PG8_SCHED __builtin_amdgcn_sched_barrier(0)
; template <class Epi, class Sched, bool ALIGN_EPI = false, bool SP2 = false>
; __device__ __forceinline__ void gemm_phase(PG8_LAS unsigned char* lds, const Gemm g, const Sched& S, const Epi& E) {
;     ...
;         for (int t = 0; t < nt; t += 2) {
;             const bool last = (t == nt - 2);
;             const char* a1 = cA + (size_t)(t + 1) * kstep;
;             const char* a2 = last ? nA : cA + (size_t)(t + 2) * kstep; const char* b2 = last ? nB : cB + (size_t)(t + 2) * kstep;
;             const char* a3 = a2 + kstep; const char* b3 = b2 + kstep;
;             if (last && has_next) S.a_ready(nxt);
;             if constexpr (SP2) {
;             PG8_LDB(B0, 0, 0); PG8_LDB(B1, 0, 1); PG8_SCHED; PG8_LDA(At, 0, 0); PG8_STAGE(PG8_SA(1, 1), a1 + hstep, voffA);
;             PG8_WAIT_V(8); PG8_WAIT_L(0); PG8_BAR; PG8_MMA(0, 0, At, B0); PG8_MMA(0, 1, At, B1); PG8_BAR; PG8_SCHED;
.LBB0_432:
	s_add_u32 s49, s66, 0xffe00080
	s_addc_u32 s52, s67, -1
	s_add_i32 s53, 0, 0x10000
	s_cmpk_eq_i32 s45, 0x7c
	s_cselect_b32 s71, s19, s52
	s_cselect_b32 s70, s34, s49
	v_add_u32_e32 v140, s53, v143
	s_cselect_b32 s69, s31, s43
	s_cselect_b32 s68, s35, s37
	s_add_i32 s49, 0, 0x14000
	ds_read_b128 v[146:149], v140
	ds_read_b128 v[150:153], v140 offset:1024
	ds_read_b128 v[154:157], v140 offset:2048
	ds_read_b128 v[158:161], v140 offset:3072
	v_add_u32_e32 v140, s49, v143
	ds_read_b128 v[162:165], v140
	ds_read_b128 v[166:169], v140 offset:1024
	ds_read_b128 v[170:173], v140 offset:2048
	ds_read_b128 v[174:177], v140 offset:3072
	v_lshl_add_u64 v[140:141], s[66:67], 0, v[136:137]
	s_add_i32 m0, s10, 0xc000
	ds_read_b128 v[178:181], v145
	ds_read_b128 v[182:185], v145 offset:1024
	ds_read_b128 v[186:189], v145 offset:2048
	ds_read_b128 v[190:193], v145 offset:3072
	ds_read_b128 v[220:223], v145 offset:4096
	ds_read_b128 v[224:227], v145 offset:5120
	ds_read_b128 v[228:231], v145 offset:6144
	ds_read_b128 v[232:235], v145 offset:7168
	global_load_lds_dwordx4 v[140:141], off
	v_lshl_add_u64 v[140:141], s[66:67], 0, v[138:139]
	s_add_i32 m0, s10, 0xe000
	s_nop 0
	global_load_lds_dwordx4 v[140:141], off
	s_cmp_lt_i32 s45, 0
	s_cbranch_scc0 .Lrx7_0_norm
	s_cmp_lt_u32 s33, 2
	s_cbranch_scc1 .Lrx7_0_norm
	s_waitcnt vmcnt(24)
	s_branch .Lrx7_0_join

; #define PG8_STAGE(bufoff, gbase, voff) do { _Pragma("unroll") for (int _i = 0; _i < 2; ++_i) \
;         __builtin_amdgcn_global_load_lds((const unsigned*)((const char*)(gbase) + (voff)[_i]), (PG8_LAS unsigned*)(lds + (bufoff) + ldsw + _i * 8192), 16, 0, 0); } while (0)
; #define PG8_LDA(dst, b, h) do { _Pragma("unroll") for (int m = 0; m < 4; ++m) _Pragma("unroll") for (int k = 0; k < 2; ++k) dst[m][k] = *(const PG8_LAS bf16x8*)(lds + PG8_SA(b, h) + aoff + m * 2048 + k * 1024); } while (0)
; #define PG8_MMA(ai, bj, At, Bt) do { __builtin_amdgcn_s_setprio(1); _Pragma("unroll") for (int m = 0; m < 4; ++m) _Pragma("unroll") for (int n = 0; n < 2; ++n) _Pragma("unroll") for (int k = 0; k < 2; ++k) \
;         acc[ai][bj][m][n] = __builtin_amdgcn_mfma_f32_16x16x32_bf16(Bt[n][k], At[m][k], acc[ai][bj][m][n], 0, 0, 0); __builtin_amdgcn_s_setprio(0); } while (0)
; #define PG8_WAIT_V(n) asm volatile("s_waitcnt vmcnt(" #n ")" ::: "memory")
; #define PG8_WAIT_L(n) asm volatile("s_waitcnt lgkmcnt(" #n ")" ::: "memory")
; #define PG8_BAR __builtin_amdgcn_s_barrier()
; #define PG8_SCHED __builtin_amdgcn_sched_barrier(0)
; template <class Epi, class Sched, bool ALIGN_EPI = false, bool SP2 = false>
; __device__ __forceinline__ void gemm_phase(PG8_LAS unsigned char* lds, const Gemm g, const Sched& S, const Epi& E) {
;     ...
;             PG8_WAIT_V(8); PG8_WAIT_L(0); PG8_BAR; PG8_MMA(0, 0, At, B0); PG8_MMA(0, 1, At, B1); PG8_BAR; PG8_SCHED;
;             PG8_LDA(At, 0, 1); PG8_STAGE(PG8_SB(0, 0), b2, voffB); PG8_STAGE(PG8_SB(0, 1), b2 + hstep, voffB); PG8_STAGE(PG8_SA(0, 0), a2, voffA);
;             PG8_WAIT_V(8); PG8_WAIT_L(0); PG8_BAR; PG8_MMA(1, 0, At, B0); PG8_MMA(1, 1, At, B1); PG8_BAR; PG8_SCHED;
.Lrx7_0_join:
	s_waitcnt lgkmcnt(0)
	s_barrier
	s_setprio 1
	s_waitcnt lgkmcnt(0)
	v_mfma_f32_16x16x32_bf16 v[124:127], v[146:149], v[178:181], v[124:127]
	v_mfma_f32_16x16x32_bf16 v[120:123], v[154:157], v[178:181], v[120:123]
	v_mfma_f32_16x16x32_bf16 v[116:119], v[146:149], v[186:189], v[116:119]
	v_mfma_f32_16x16x32_bf16 v[108:111], v[154:157], v[186:189], v[108:111]
	v_mfma_f32_16x16x32_bf16 v[100:103], v[146:149], v[220:223], v[100:103]
	v_mfma_f32_16x16x32_bf16 v[92:95], v[154:157], v[220:223], v[92:95]
	v_mfma_f32_16x16x32_bf16 v[84:87], v[146:149], v[228:231], v[84:87]
	v_mfma_f32_16x16x32_bf16 v[76:79], v[154:157], v[228:231], v[76:79]
	v_mfma_f32_16x16x32_bf16 v[124:127], v[150:153], v[182:185], v[124:127]
	v_mfma_f32_16x16x32_bf16 v[120:123], v[158:161], v[182:185], v[120:123]
	v_mfma_f32_16x16x32_bf16 v[116:119], v[150:153], v[190:193], v[116:119]
	v_mfma_f32_16x16x32_bf16 v[108:111], v[158:161], v[190:193], v[108:111]
	v_mfma_f32_16x16x32_bf16 v[100:103], v[150:153], v[224:227], v[100:103]
	v_mfma_f32_16x16x32_bf16 v[92:95], v[158:161], v[224:227], v[92:95]
	v_mfma_f32_16x16x32_bf16 v[84:87], v[150:153], v[232:235], v[84:87]
	v_mfma_f32_16x16x32_bf16 v[76:79], v[158:161], v[232:235], v[76:79]
	s_setprio 0
	s_setprio 1
	v_mfma_f32_16x16x32_bf16 v[112:115], v[162:165], v[178:181], v[112:115]
	v_mfma_f32_16x16x32_bf16 v[104:107], v[170:173], v[178:181], v[104:107]
	v_mfma_f32_16x16x32_bf16 v[96:99], v[162:165], v[186:189], v[96:99]
	v_mfma_f32_16x16x32_bf16 v[88:91], v[170:173], v[186:189], v[88:91]
	v_mfma_f32_16x16x32_bf16 v[80:83], v[162:165], v[220:223], v[80:83]
	v_mfma_f32_16x16x32_bf16 v[72:75], v[170:173], v[220:223], v[72:75]
	v_mfma_f32_16x16x32_bf16 v[68:71], v[162:165], v[228:231], v[68:71]
	v_mfma_f32_16x16x32_bf16 v[64:67], v[170:173], v[228:231], v[64:67]
	v_mfma_f32_16x16x32_bf16 v[112:115], v[166:169], v[182:185], v[112:115]
	v_mfma_f32_16x16x32_bf16 v[104:107], v[174:177], v[182:185], v[104:107]
	v_mfma_f32_16x16x32_bf16 v[96:99], v[166:169], v[190:193], v[96:99]
	v_mfma_f32_16x16x32_bf16 v[88:91], v[174:177], v[190:193], v[88:91]
	v_mfma_f32_16x16x32_bf16 v[80:83], v[166:169], v[224:227], v[80:83]
	v_mfma_f32_16x16x32_bf16 v[72:75], v[174:177], v[224:227], v[72:75]
	v_mfma_f32_16x16x32_bf16 v[68:71], v[166:169], v[232:235], v[68:71]
	v_mfma_f32_16x16x32_bf16 v[64:67], v[174:177], v[232:235], v[64:67]
	s_setprio 0
	s_barrier
	s_add_i32 s52, s53, s2
	v_lshl_add_u64 v[140:141], s[68:69], 0, v[128:129]
	s_mov_b32 m0, s52
	ds_read_b128 v[178:181], v145 offset:16384
	ds_read_b128 v[182:185], v145 offset:17408
	ds_read_b128 v[186:189], v145 offset:18432
	ds_read_b128 v[190:193], v145 offset:19456
	ds_read_b128 v[220:223], v145 offset:20480
	ds_read_b128 v[224:227], v145 offset:21504
	ds_read_b128 v[228:231], v145 offset:22528
	ds_read_b128 v[232:235], v145 offset:23552
	global_load_lds_dwordx4 v[140:141], off
	s_add_i32 m0, s52, 0x2000
	s_add_u32 s52, s68, 0x200000
	v_lshl_add_u64 v[206:207], s[68:69], 0, v[130:131]
	s_addc_u32 s53, s69, 0
	s_add_i32 s49, s49, s2
	global_load_lds_dwordx4 v[206:207], off
	v_lshl_add_u64 v[214:215], s[52:53], 0, v[128:129]
	s_mov_b32 m0, s49
	v_lshl_add_u64 v[216:217], s[70:71], 0, v[132:133]
	global_load_lds_dwordx4 v[214:215], off
	v_lshl_add_u64 v[214:215], s[52:53], 0, v[130:131]
	s_add_i32 m0, s49, 0x2000
	s_nop 0
	global_load_lds_dwordx4 v[214:215], off
	v_lshl_add_u64 v[214:215], s[70:71], 0, v[134:135]
	s_mov_b32 m0, s10
	s_nop 0
	global_load_lds_dwordx4 v[214:215], off
	s_mov_b32 m0, s17
	s_nop 0
	global_load_lds_dwordx4 v[216:217], off
	s_cmp_lt_i32 s45, 0
	s_cbranch_scc0 .Lrx7_1_norm
	s_cmp_lt_u32 s33, 2
	s_cbranch_scc1 .Lrx7_1_norm
	s_waitcnt vmcnt(24)
	s_branch .Lrx7_1_join

; #define PG8_STAGE(bufoff, gbase, voff) do { _Pragma("unroll") for (int _i = 0; _i < 2; ++_i) \
;         __builtin_amdgcn_global_load_lds((const unsigned*)((const char*)(gbase) + (voff)[_i]), (PG8_LAS unsigned*)(lds + (bufoff) + ldsw + _i * 8192), 16, 0, 0); } while (0)
; #define PG8_LDA(dst, b, h) do { _Pragma("unroll") for (int m = 0; m < 4; ++m) _Pragma("unroll") for (int k = 0; k < 2; ++k) dst[m][k] = *(const PG8_LAS bf16x8*)(lds + PG8_SA(b, h) + aoff + m * 2048 + k * 1024); } while (0)
; #define PG8_LDB(dst, b, h) do { _Pragma("unroll") for (int n = 0; n < 2; ++n) _Pragma("unroll") for (int k = 0; k < 2; ++k) dst[n][k] = *(const PG8_LAS bf16x8*)(lds + PG8_SB(b, h) + boff + n * 2048 + k * 1024); } while (0)
; #define PG8_MMA(ai, bj, At, Bt) do { __builtin_amdgcn_s_setprio(1); _Pragma("unroll") for (int m = 0; m < 4; ++m) _Pragma("unroll") for (int n = 0; n < 2; ++n) _Pragma("unroll") for (int k = 0; k < 2; ++k) \
;         acc[ai][bj][m][n] = __builtin_amdgcn_mfma_f32_16x16x32_bf16(Bt[n][k], At[m][k], acc[ai][bj][m][n], 0, 0, 0); __builtin_amdgcn_s_setprio(0); } while (0)
; #define PG8_WAIT_V(n) asm volatile("s_waitcnt vmcnt(" #n ")" ::: "memory")
; #define PG8_WAIT_L(n) asm volatile("s_waitcnt lgkmcnt(" #n ")" ::: "memory")
; #define PG8_BAR __builtin_amdgcn_s_barrier()
; #define PG8_SCHED __builtin_amdgcn_sched_barrier(0)
; template <class Epi, class Sched, bool ALIGN_EPI = false, bool SP2 = false>
; __device__ __forceinline__ void gemm_phase(PG8_LAS unsigned char* lds, const Gemm g, const Sched& S, const Epi& E) {
;     ...
;             PG8_WAIT_V(8); PG8_WAIT_L(0); PG8_BAR; PG8_MMA(1, 0, At, B0); PG8_MMA(1, 1, At, B1); PG8_BAR; PG8_SCHED;
;             PG8_LDB(B0, 1, 0); PG8_LDB(B1, 1, 1); PG8_SCHED; PG8_LDA(At, 1, 0); PG8_STAGE(PG8_SA(0, 1), a2 + hstep, voffA);
;             PG8_WAIT_V(8); PG8_WAIT_L(0); PG8_BAR; PG8_MMA(0, 0, At, B0); PG8_MMA(0, 1, At, B1); PG8_BAR; PG8_SCHED;
.Lrx7_1_join:
	s_waitcnt lgkmcnt(0)
	s_barrier
	s_setprio 1
	s_waitcnt lgkmcnt(0)
	v_mfma_f32_16x16x32_bf16 v[60:63], v[146:149], v[178:181], v[60:63]
	v_mfma_f32_16x16x32_bf16 v[56:59], v[154:157], v[178:181], v[56:59]
	v_mfma_f32_16x16x32_bf16 v[52:55], v[146:149], v[186:189], v[52:55]
	v_mfma_f32_16x16x32_bf16 v[44:47], v[154:157], v[186:189], v[44:47]
	v_mfma_f32_16x16x32_bf16 v[36:39], v[146:149], v[220:223], v[36:39]
	v_mfma_f32_16x16x32_bf16 v[28:31], v[154:157], v[220:223], v[28:31]
	v_mfma_f32_16x16x32_bf16 v[20:23], v[146:149], v[228:231], v[20:23]
	v_mfma_f32_16x16x32_bf16 v[12:15], v[154:157], v[228:231], v[12:15]
	v_mfma_f32_16x16x32_bf16 v[60:63], v[150:153], v[182:185], v[60:63]
	v_mfma_f32_16x16x32_bf16 v[56:59], v[158:161], v[182:185], v[56:59]
	v_mfma_f32_16x16x32_bf16 v[52:55], v[150:153], v[190:193], v[52:55]
	v_mfma_f32_16x16x32_bf16 v[44:47], v[158:161], v[190:193], v[44:47]
	v_mfma_f32_16x16x32_bf16 v[36:39], v[150:153], v[224:227], v[36:39]
	v_mfma_f32_16x16x32_bf16 v[28:31], v[158:161], v[224:227], v[28:31]
	v_mfma_f32_16x16x32_bf16 v[20:23], v[150:153], v[232:235], v[20:23]
	v_mfma_f32_16x16x32_bf16 v[12:15], v[158:161], v[232:235], v[12:15]
	s_setprio 0
	s_setprio 1
	v_mfma_f32_16x16x32_bf16 v[48:51], v[162:165], v[178:181], v[48:51]
	v_mfma_f32_16x16x32_bf16 v[40:43], v[170:173], v[178:181], v[40:43]
	v_mfma_f32_16x16x32_bf16 v[32:35], v[162:165], v[186:189], v[32:35]
	v_mfma_f32_16x16x32_bf16 v[24:27], v[170:173], v[186:189], v[24:27]
	v_mfma_f32_16x16x32_bf16 v[16:19], v[162:165], v[220:223], v[16:19]
	v_mfma_f32_16x16x32_bf16 v[8:11], v[170:173], v[220:223], v[8:11]
	v_mfma_f32_16x16x32_bf16 v[4:7], v[162:165], v[228:231], v[4:7]
	v_mfma_f32_16x16x32_bf16 v[0:3], v[170:173], v[228:231], v[0:3]
	v_mfma_f32_16x16x32_bf16 v[48:51], v[166:169], v[182:185], v[48:51]
	v_mfma_f32_16x16x32_bf16 v[40:43], v[174:177], v[182:185], v[40:43]
	v_mfma_f32_16x16x32_bf16 v[32:35], v[166:169], v[190:193], v[32:35]
	v_mfma_f32_16x16x32_bf16 v[24:27], v[174:177], v[190:193], v[24:27]
	v_mfma_f32_16x16x32_bf16 v[16:19], v[166:169], v[224:227], v[16:19]
	v_mfma_f32_16x16x32_bf16 v[8:11], v[174:177], v[224:227], v[8:11]
	v_mfma_f32_16x16x32_bf16 v[4:7], v[166:169], v[232:235], v[4:7]
	v_mfma_f32_16x16x32_bf16 v[0:3], v[174:177], v[232:235], v[0:3]
	s_setprio 0
	s_barrier
	s_add_i32 s49, 0, 0x18000
	s_add_i32 s83, 0, 0x1c000
	v_add_u32_e32 v158, s49, v143
	v_add_u32_e32 v174, s83, v143
	ds_read_b128 v[146:149], v158
	ds_read_b128 v[150:153], v158 offset:1024
	ds_read_b128 v[154:157], v158 offset:2048
	ds_read_b128 v[158:161], v158 offset:3072
	ds_read_b128 v[162:165], v174
	ds_read_b128 v[166:169], v174 offset:1024
	ds_read_b128 v[170:173], v174 offset:2048
	ds_read_b128 v[174:177], v174 offset:3072
	s_add_u32 s52, s70, 0x200000
	s_addc_u32 s53, s71, 0
	s_mov_b32 m0, s26
	v_lshl_add_u64 v[236:237], s[52:53], 0, v[134:135]
	ds_read_b128 v[178:181], v145 offset:32768
	ds_read_b128 v[182:185], v145 offset:33792
	ds_read_b128 v[186:189], v145 offset:34816
	ds_read_b128 v[190:193], v145 offset:35840
	ds_read_b128 v[220:223], v145 offset:36864
	ds_read_b128 v[224:227], v145 offset:37888
	ds_read_b128 v[228:231], v145 offset:38912
	ds_read_b128 v[232:235], v145 offset:39936
	global_load_lds_dwordx4 v[236:237], off
	v_lshl_add_u64 v[236:237], s[52:53], 0, v[132:133]
	s_mov_b32 m0, s27
	s_nop 0
	global_load_lds_dwordx4 v[236:237], off
	s_waitcnt vmcnt(8)
	s_waitcnt lgkmcnt(0)
	s_barrier
	s_setprio 1
	s_waitcnt lgkmcnt(0)
	v_mfma_f32_16x16x32_bf16 v[124:127], v[146:149], v[178:181], v[124:127]
	v_mfma_f32_16x16x32_bf16 v[120:123], v[154:157], v[178:181], v[120:123]
	v_mfma_f32_16x16x32_bf16 v[116:119], v[146:149], v[186:189], v[116:119]
	v_mfma_f32_16x16x32_bf16 v[108:111], v[154:157], v[186:189], v[108:111]
	v_mfma_f32_16x16x32_bf16 v[100:103], v[146:149], v[220:223], v[100:103]
	v_mfma_f32_16x16x32_bf16 v[92:95], v[154:157], v[220:223], v[92:95]
	v_mfma_f32_16x16x32_bf16 v[84:87], v[146:149], v[228:231], v[84:87]
	v_mfma_f32_16x16x32_bf16 v[76:79], v[154:157], v[228:231], v[76:79]
	v_mfma_f32_16x16x32_bf16 v[124:127], v[150:153], v[182:185], v[124:127]
	v_mfma_f32_16x16x32_bf16 v[120:123], v[158:161], v[182:185], v[120:123]
	v_mfma_f32_16x16x32_bf16 v[116:119], v[150:153], v[190:193], v[116:119]
	v_mfma_f32_16x16x32_bf16 v[108:111], v[158:161], v[190:193], v[108:111]
	v_mfma_f32_16x16x32_bf16 v[100:103], v[150:153], v[224:227], v[100:103]
	v_mfma_f32_16x16x32_bf16 v[92:95], v[158:161], v[224:227], v[92:95]
	v_mfma_f32_16x16x32_bf16 v[84:87], v[150:153], v[232:235], v[84:87]
	v_mfma_f32_16x16x32_bf16 v[76:79], v[158:161], v[232:235], v[76:79]
	s_setprio 0
	s_setprio 1
	v_mfma_f32_16x16x32_bf16 v[112:115], v[162:165], v[178:181], v[112:115]
	v_mfma_f32_16x16x32_bf16 v[104:107], v[170:173], v[178:181], v[104:107]
	v_mfma_f32_16x16x32_bf16 v[96:99], v[162:165], v[186:189], v[96:99]
	v_mfma_f32_16x16x32_bf16 v[88:91], v[170:173], v[186:189], v[88:91]
	v_mfma_f32_16x16x32_bf16 v[80:83], v[162:165], v[220:223], v[80:83]
	v_mfma_f32_16x16x32_bf16 v[72:75], v[170:173], v[220:223], v[72:75]
	v_mfma_f32_16x16x32_bf16 v[68:71], v[162:165], v[228:231], v[68:71]
	v_mfma_f32_16x16x32_bf16 v[64:67], v[170:173], v[228:231], v[64:67]
	v_mfma_f32_16x16x32_bf16 v[112:115], v[166:169], v[182:185], v[112:115]
	v_mfma_f32_16x16x32_bf16 v[104:107], v[174:177], v[182:185], v[104:107]
	v_mfma_f32_16x16x32_bf16 v[96:99], v[166:169], v[190:193], v[96:99]
	v_mfma_f32_16x16x32_bf16 v[88:91], v[174:177], v[190:193], v[88:91]
	v_mfma_f32_16x16x32_bf16 v[80:83], v[166:169], v[224:227], v[80:83]
	v_mfma_f32_16x16x32_bf16 v[72:75], v[174:177], v[224:227], v[72:75]
	v_mfma_f32_16x16x32_bf16 v[68:71], v[166:169], v[232:235], v[68:71]
	v_mfma_f32_16x16x32_bf16 v[64:67], v[174:177], v[232:235], v[64:67]
	s_setprio 0
	s_barrier
; #define PG8_STAGE(bufoff, gbase, voff) do { _Pragma("unroll") for (int _i = 0; _i < 2; ++_i) \
;         __builtin_amdgcn_global_load_lds((const unsigned*)((const char*)(gbase) + (voff)[_i]), (PG8_LAS unsigned*)(lds + (bufoff) + ldsw + _i * 8192), 16, 0, 0); } while (0)
; #define PG8_LDA(dst, b, h) do { _Pragma("unroll") for (int m = 0; m < 4; ++m) _Pragma("unroll") for (int k = 0; k < 2; ++k) dst[m][k] = *(const PG8_LAS bf16x8*)(lds + PG8_SA(b, h) + aoff + m * 2048 + k * 1024); } while (0)
; #define PG8_LDB(dst, b, h) do { _Pragma("unroll") for (int n = 0; n < 2; ++n) _Pragma("unroll") for (int k = 0; k < 2; ++k) dst[n][k] = *(const PG8_LAS bf16x8*)(lds + PG8_SB(b, h) + boff + n * 2048 + k * 1024); } while (0)
; #define PG8_MMA(ai, bj, At, Bt) do { __builtin_amdgcn_s_setprio(1); _Pragma("unroll") for (int m = 0; m < 4; ++m) _Pragma("unroll") for (int n = 0; n < 2; ++n) _Pragma("unroll") for (int k = 0; k < 2; ++k) \
;         acc[ai][bj][m][n] = __builtin_amdgcn_mfma_f32_16x16x32_bf16(Bt[n][k], At[m][k], acc[ai][bj][m][n], 0, 0, 0); __builtin_amdgcn_s_setprio(0); } while (0)
; #define PG8_WAIT_V(n) asm volatile("s_waitcnt vmcnt(" #n ")" ::: "memory")
; #define PG8_WAIT_L(n) asm volatile("s_waitcnt lgkmcnt(" #n ")" ::: "memory")
; #define PG8_BAR __builtin_amdgcn_s_barrier()
; #define PG8_SCHED __builtin_amdgcn_sched_barrier(0)
; template <class Epi, class Sched, bool ALIGN_EPI = false, bool SP2 = false>
; __device__ __forceinline__ void gemm_phase(PG8_LAS unsigned char* lds, const Gemm g, const Sched& S, const Epi& E) {
;     ...
;             PG8_LDA(At, 0, 1); PG8_STAGE(PG8_SB(0, 0), b2, voffB); PG8_STAGE(PG8_SB(0, 1), b2 + hstep, voffB); PG8_STAGE(PG8_SA(0, 0), a2, voffA);
;             PG8_WAIT_V(8); PG8_WAIT_L(0); PG8_BAR; PG8_MMA(1, 0, At, B0); PG8_MMA(1, 1, At, B1); PG8_BAR; PG8_SCHED;
;             PG8_LDB(B0, 1, 0); PG8_LDB(B1, 1, 1); PG8_SCHED; PG8_LDA(At, 1, 0); PG8_STAGE(PG8_SA(0, 1), a2 + hstep, voffA);
;             PG8_WAIT_V(8); PG8_WAIT_L(0); PG8_BAR; PG8_MMA(0, 0, At, B0); PG8_MMA(0, 1, At, B1); PG8_BAR; PG8_SCHED;
;             PG8_LDA(At, 1, 1); PG8_STAGE(PG8_SB(1, 0), b3, voffB); PG8_STAGE(PG8_SB(1, 1), b3 + hstep, voffB); PG8_STAGE(PG8_SA(1, 0), a3, voffA);
;             PG8_WAIT_V(8); PG8_WAIT_L(0); PG8_BAR; PG8_MMA(1, 0, At, B0); PG8_MMA(1, 1, At, B1); PG8_BAR; PG8_SCHED;
	s_add_i32 s49, s49, s2
	v_lshl_add_u64 v[140:141], v[140:141], 0, s[20:21]
	s_mov_b32 m0, s49
	ds_read_b128 v[178:181], v145 offset:49152
	ds_read_b128 v[182:185], v145 offset:50176
	ds_read_b128 v[186:189], v145 offset:51200
	ds_read_b128 v[190:193], v145 offset:52224
	ds_read_b128 v[220:223], v145 offset:53248
	ds_read_b128 v[224:227], v145 offset:54272
	ds_read_b128 v[228:231], v145 offset:55296
	ds_read_b128 v[232:235], v145 offset:56320
	global_load_lds_dwordx4 v[140:141], off
	s_add_i32 m0, s49, 0x2000
	s_add_u32 s52, s68, 0x200080
	v_lshl_add_u64 v[140:141], v[206:207], 0, s[20:21]
	s_addc_u32 s53, s69, 0
	s_add_i32 s49, s83, s2
	global_load_lds_dwordx4 v[140:141], off
	v_lshl_add_u64 v[140:141], s[52:53], 0, v[128:129]
	s_mov_b32 m0, s49
	s_nop 0
	global_load_lds_dwordx4 v[140:141], off
	v_lshl_add_u64 v[140:141], s[52:53], 0, v[130:131]
	s_add_i32 m0, s49, 0x2000
	s_nop 0
	global_load_lds_dwordx4 v[140:141], off
	v_lshl_add_u64 v[140:141], v[214:215], 0, s[20:21]
	s_mov_b32 m0, s28
	s_nop 0
	global_load_lds_dwordx4 v[140:141], off
	v_lshl_add_u64 v[140:141], v[216:217], 0, s[20:21]
	s_mov_b32 m0, s29
	s_nop 0
	global_load_lds_dwordx4 v[140:141], off
	s_waitcnt vmcnt(8)
	s_waitcnt lgkmcnt(0)
	s_barrier
	s_setprio 1
	s_waitcnt lgkmcnt(0)
	v_mfma_f32_16x16x32_bf16 v[60:63], v[146:149], v[178:181], v[60:63]
	v_mfma_f32_16x16x32_bf16 v[56:59], v[154:157], v[178:181], v[56:59]
	v_mfma_f32_16x16x32_bf16 v[52:55], v[146:149], v[186:189], v[52:55]
	v_mfma_f32_16x16x32_bf16 v[44:47], v[154:157], v[186:189], v[44:47]
	v_mfma_f32_16x16x32_bf16 v[36:39], v[146:149], v[220:223], v[36:39]
	v_mfma_f32_16x16x32_bf16 v[28:31], v[154:157], v[220:223], v[28:31]
	v_mfma_f32_16x16x32_bf16 v[20:23], v[146:149], v[228:231], v[20:23]
	v_mfma_f32_16x16x32_bf16 v[12:15], v[154:157], v[228:231], v[12:15]
	v_mfma_f32_16x16x32_bf16 v[60:63], v[150:153], v[182:185], v[60:63]
	v_mfma_f32_16x16x32_bf16 v[56:59], v[158:161], v[182:185], v[56:59]
	v_mfma_f32_16x16x32_bf16 v[52:55], v[150:153], v[190:193], v[52:55]
	v_mfma_f32_16x16x32_bf16 v[44:47], v[158:161], v[190:193], v[44:47]
	v_mfma_f32_16x16x32_bf16 v[36:39], v[150:153], v[224:227], v[36:39]
	v_mfma_f32_16x16x32_bf16 v[28:31], v[158:161], v[224:227], v[28:31]
	v_mfma_f32_16x16x32_bf16 v[20:23], v[150:153], v[232:235], v[20:23]
	v_mfma_f32_16x16x32_bf16 v[12:15], v[158:161], v[232:235], v[12:15]
	s_setprio 0
	s_setprio 1
	v_mfma_f32_16x16x32_bf16 v[48:51], v[162:165], v[178:181], v[48:51]
	v_mfma_f32_16x16x32_bf16 v[40:43], v[170:173], v[178:181], v[40:43]
	v_mfma_f32_16x16x32_bf16 v[32:35], v[162:165], v[186:189], v[32:35]
	v_mfma_f32_16x16x32_bf16 v[24:27], v[170:173], v[186:189], v[24:27]
	v_mfma_f32_16x16x32_bf16 v[16:19], v[162:165], v[220:223], v[16:19]
	v_mfma_f32_16x16x32_bf16 v[8:11], v[170:173], v[220:223], v[8:11]
	v_mfma_f32_16x16x32_bf16 v[4:7], v[162:165], v[228:231], v[4:7]
	v_mfma_f32_16x16x32_bf16 v[0:3], v[170:173], v[228:231], v[0:3]
	v_mfma_f32_16x16x32_bf16 v[48:51], v[166:169], v[182:185], v[48:51]
	v_mfma_f32_16x16x32_bf16 v[40:43], v[174:177], v[182:185], v[40:43]
	v_mfma_f32_16x16x32_bf16 v[32:35], v[166:169], v[190:193], v[32:35]
	v_mfma_f32_16x16x32_bf16 v[24:27], v[174:177], v[190:193], v[24:27]
	v_mfma_f32_16x16x32_bf16 v[16:19], v[166:169], v[224:227], v[16:19]
	v_mfma_f32_16x16x32_bf16 v[8:11], v[174:177], v[224:227], v[8:11]
	v_mfma_f32_16x16x32_bf16 v[4:7], v[166:169], v[232:235], v[4:7]
	v_mfma_f32_16x16x32_bf16 v[0:3], v[174:177], v[232:235], v[0:3]
	s_setprio 0
	s_barrier
	s_add_i32 s45, s45, 2
	s_add_u32 s66, s66, 0x100
	s_addc_u32 s67, s67, 0
	s_add_u32 s37, s37, 0x100
	s_addc_u32 s43, s43, 0
	s_cmpk_gt_u32 s45, 0x7d
	s_cbranch_scc0 .LBB0_432
	s_and_b64 vcc, exec, s[12:13]
	s_cbranch_vccz .LBB0_435
	s_barrier

; #define PG8_STAGE(bufoff, gbase, voff) do { _Pragma("unroll") for (int _i = 0; _i < 2; ++_i) \
;         __builtin_amdgcn_global_load_lds((const unsigned*)((const char*)(gbase) + (voff)[_i]), (PG8_LAS unsigned*)(lds + (bufoff) + ldsw + _i * 8192), 16, 0, 0); } while (0)
; #define PG8_LDA(dst, b, h) do { _Pragma("unroll") for (int m = 0; m < 4; ++m) _Pragma("unroll") for (int k = 0; k < 2; ++k) dst[m][k] = *(const PG8_LAS bf16x8*)(lds + PG8_SA(b, h) + aoff + m * 2048 + k * 1024); } while (0)
; #define PG8_LDB(dst, b, h) do { _Pragma("unroll") for (int n = 0; n < 2; ++n) _Pragma("unroll") for (int k = 0; k < 2; ++k) dst[n][k] = *(const PG8_LAS bf16x8*)(lds + PG8_SB(b, h) + boff + n * 2048 + k * 1024); } while (0)
; #define PG8_MMA(ai, bj, At, Bt) do { __builtin_amdgcn_s_setprio(1); _Pragma("unroll") for (int m = 0; m < 4; ++m) _Pragma("unroll") for (int n = 0; n < 2; ++n) _Pragma("unroll") for (int k = 0; k < 2; ++k) \
;         acc[ai][bj][m][n] = __builtin_amdgcn_mfma_f32_16x16x32_bf16(Bt[n][k], At[m][k], acc[ai][bj][m][n], 0, 0, 0); __builtin_amdgcn_s_setprio(0); } while (0)
; #define PG8_WAIT_V(n) asm volatile("s_waitcnt vmcnt(" #n ")" ::: "memory")
; #define PG8_WAIT_L(n) asm volatile("s_waitcnt lgkmcnt(" #n ")" ::: "memory")
; #define PG8_BAR __builtin_amdgcn_s_barrier()
; #define PG8_SCHED __builtin_amdgcn_sched_barrier(0)
; template <class Epi, class Sched, bool ALIGN_EPI = false, bool SP2 = false>
; __device__ __forceinline__ void gemm_phase(PG8_LAS unsigned char* lds, const Gemm g, const Sched& S, const Epi& E) {
;     ...
;         for (int t = 0; t < nt; t += 2) {
;             const bool last = (t == nt - 2);
;             const char* a1 = cA + (size_t)(t + 1) * kstep;
;             const char* a2 = last ? nA : cA + (size_t)(t + 2) * kstep; const char* b2 = last ? nB : cB + (size_t)(t + 2) * kstep;
;             const char* a3 = a2 + kstep; const char* b3 = b2 + kstep;
;             if (last && has_next) S.a_ready(nxt);
;             if constexpr (SP2) {
;             PG8_LDB(B0, 0, 0); PG8_LDB(B1, 0, 1); PG8_SCHED; PG8_LDA(At, 0, 0); PG8_STAGE(PG8_SA(1, 1), a1 + hstep, voffA);
;             PG8_WAIT_V(8); PG8_WAIT_L(0); PG8_BAR; PG8_MMA(0, 0, At, B0); PG8_MMA(0, 1, At, B1); PG8_BAR; PG8_SCHED;
.LBB0_455:
	s_add_u32 s49, s66, 0xfff80080
	s_addc_u32 s52, s67, -1
	s_add_i32 s53, 0, 0x10000
	s_cmp_eq_u32 s47, 28
	s_cselect_b32 s71, s19, s52
	s_cselect_b32 s70, s33, s49
	v_add_u32_e32 v140, s53, v143
	s_cselect_b32 s69, s31, s37
	s_cselect_b32 s68, s34, s35
	s_add_i32 s49, 0, 0x14000
	ds_read_b128 v[146:149], v140
	ds_read_b128 v[150:153], v140 offset:1024
	ds_read_b128 v[154:157], v140 offset:2048
	ds_read_b128 v[158:161], v140 offset:3072
	v_add_u32_e32 v140, s49, v143
	ds_read_b128 v[162:165], v140
	ds_read_b128 v[166:169], v140 offset:1024
	ds_read_b128 v[170:173], v140 offset:2048
	ds_read_b128 v[174:177], v140 offset:3072
	v_lshl_add_u64 v[140:141], s[66:67], 0, v[136:137]
	s_add_i32 m0, s7, 0xc000
	ds_read_b128 v[178:181], v145
	ds_read_b128 v[182:185], v145 offset:1024
	ds_read_b128 v[186:189], v145 offset:2048
	ds_read_b128 v[190:193], v145 offset:3072
	ds_read_b128 v[220:223], v145 offset:4096
	ds_read_b128 v[224:227], v145 offset:5120
	ds_read_b128 v[228:231], v145 offset:6144
	ds_read_b128 v[232:235], v145 offset:7168
	global_load_lds_dwordx4 v[140:141], off
	v_lshl_add_u64 v[140:141], s[66:67], 0, v[138:139]
	s_add_i32 m0, s7, 0xe000
	s_nop 0
	global_load_lds_dwordx4 v[140:141], off
	s_cmp_lt_i32 s47, 0
	s_cbranch_scc0 .Lrx6_0_norm
	s_cmp_lt_u32 s29, 2
	s_cbranch_scc1 .Lrx6_0_norm
	s_waitcnt vmcnt(24)
	s_branch .Lrx6_0_join

; #define PG8_STAGE(bufoff, gbase, voff) do { _Pragma("unroll") for (int _i = 0; _i < 2; ++_i) \
;         __builtin_amdgcn_global_load_lds((const unsigned*)((const char*)(gbase) + (voff)[_i]), (PG8_LAS unsigned*)(lds + (bufoff) + ldsw + _i * 8192), 16, 0, 0); } while (0)
; #define PG8_LDA(dst, b, h) do { _Pragma("unroll") for (int m = 0; m < 4; ++m) _Pragma("unroll") for (int k = 0; k < 2; ++k) dst[m][k] = *(const PG8_LAS bf16x8*)(lds + PG8_SA(b, h) + aoff + m * 2048 + k * 1024); } while (0)
; #define PG8_MMA(ai, bj, At, Bt) do { __builtin_amdgcn_s_setprio(1); _Pragma("unroll") for (int m = 0; m < 4; ++m) _Pragma("unroll") for (int n = 0; n < 2; ++n) _Pragma("unroll") for (int k = 0; k < 2; ++k) \
;         acc[ai][bj][m][n] = __builtin_amdgcn_mfma_f32_16x16x32_bf16(Bt[n][k], At[m][k], acc[ai][bj][m][n], 0, 0, 0); __builtin_amdgcn_s_setprio(0); } while (0)
; #define PG8_WAIT_V(n) asm volatile("s_waitcnt vmcnt(" #n ")" ::: "memory")
; #define PG8_WAIT_L(n) asm volatile("s_waitcnt lgkmcnt(" #n ")" ::: "memory")
; #define PG8_BAR __builtin_amdgcn_s_barrier()
; #define PG8_SCHED __builtin_amdgcn_sched_barrier(0)
; template <class Epi, class Sched, bool ALIGN_EPI = false, bool SP2 = false>
; __device__ __forceinline__ void gemm_phase(PG8_LAS unsigned char* lds, const Gemm g, const Sched& S, const Epi& E) {
;     ...
;             PG8_WAIT_V(8); PG8_WAIT_L(0); PG8_BAR; PG8_MMA(0, 0, At, B0); PG8_MMA(0, 1, At, B1); PG8_BAR; PG8_SCHED;
;             PG8_LDA(At, 0, 1); PG8_STAGE(PG8_SB(0, 0), b2, voffB); PG8_STAGE(PG8_SB(0, 1), b2 + hstep, voffB); PG8_STAGE(PG8_SA(0, 0), a2, voffA);
;             PG8_WAIT_V(8); PG8_WAIT_L(0); PG8_BAR; PG8_MMA(1, 0, At, B0); PG8_MMA(1, 1, At, B1); PG8_BAR; PG8_SCHED;
.Lrx6_0_join:
	s_waitcnt lgkmcnt(0)
	s_barrier
	s_setprio 1
	s_waitcnt lgkmcnt(0)
	v_mfma_f32_16x16x32_bf16 v[124:127], v[146:149], v[178:181], v[124:127]
	v_mfma_f32_16x16x32_bf16 v[120:123], v[154:157], v[178:181], v[120:123]
	v_mfma_f32_16x16x32_bf16 v[108:111], v[146:149], v[186:189], v[108:111]
	v_mfma_f32_16x16x32_bf16 v[104:107], v[154:157], v[186:189], v[104:107]
	v_mfma_f32_16x16x32_bf16 v[92:95], v[146:149], v[220:223], v[92:95]
	v_mfma_f32_16x16x32_bf16 v[88:91], v[154:157], v[220:223], v[88:91]
	v_mfma_f32_16x16x32_bf16 v[76:79], v[146:149], v[228:231], v[76:79]
	v_mfma_f32_16x16x32_bf16 v[72:75], v[154:157], v[228:231], v[72:75]
	v_mfma_f32_16x16x32_bf16 v[124:127], v[150:153], v[182:185], v[124:127]
	v_mfma_f32_16x16x32_bf16 v[120:123], v[158:161], v[182:185], v[120:123]
	v_mfma_f32_16x16x32_bf16 v[108:111], v[150:153], v[190:193], v[108:111]
	v_mfma_f32_16x16x32_bf16 v[104:107], v[158:161], v[190:193], v[104:107]
	v_mfma_f32_16x16x32_bf16 v[92:95], v[150:153], v[224:227], v[92:95]
	v_mfma_f32_16x16x32_bf16 v[88:91], v[158:161], v[224:227], v[88:91]
	v_mfma_f32_16x16x32_bf16 v[76:79], v[150:153], v[232:235], v[76:79]
	v_mfma_f32_16x16x32_bf16 v[72:75], v[158:161], v[232:235], v[72:75]
	s_setprio 0
	s_setprio 1
	v_mfma_f32_16x16x32_bf16 v[116:119], v[162:165], v[178:181], v[116:119]
	v_mfma_f32_16x16x32_bf16 v[112:115], v[170:173], v[178:181], v[112:115]
	v_mfma_f32_16x16x32_bf16 v[100:103], v[162:165], v[186:189], v[100:103]
	v_mfma_f32_16x16x32_bf16 v[96:99], v[170:173], v[186:189], v[96:99]
	v_mfma_f32_16x16x32_bf16 v[84:87], v[162:165], v[220:223], v[84:87]
	v_mfma_f32_16x16x32_bf16 v[80:83], v[170:173], v[220:223], v[80:83]
	v_mfma_f32_16x16x32_bf16 v[68:71], v[162:165], v[228:231], v[68:71]
	v_mfma_f32_16x16x32_bf16 v[64:67], v[170:173], v[228:231], v[64:67]
	v_mfma_f32_16x16x32_bf16 v[116:119], v[166:169], v[182:185], v[116:119]
	v_mfma_f32_16x16x32_bf16 v[112:115], v[174:177], v[182:185], v[112:115]
	v_mfma_f32_16x16x32_bf16 v[100:103], v[166:169], v[190:193], v[100:103]
	v_mfma_f32_16x16x32_bf16 v[96:99], v[174:177], v[190:193], v[96:99]
	v_mfma_f32_16x16x32_bf16 v[84:87], v[166:169], v[224:227], v[84:87]
	v_mfma_f32_16x16x32_bf16 v[80:83], v[174:177], v[224:227], v[80:83]
	v_mfma_f32_16x16x32_bf16 v[68:71], v[166:169], v[232:235], v[68:71]
	v_mfma_f32_16x16x32_bf16 v[64:67], v[174:177], v[232:235], v[64:67]
	s_setprio 0
	s_barrier
	s_add_i32 s52, s53, s2
	v_lshl_add_u64 v[140:141], s[68:69], 0, v[128:129]
	s_mov_b32 m0, s52
	ds_read_b128 v[178:181], v145 offset:16384
	ds_read_b128 v[182:185], v145 offset:17408
	ds_read_b128 v[186:189], v145 offset:18432
	ds_read_b128 v[190:193], v145 offset:19456
	ds_read_b128 v[220:223], v145 offset:20480
	ds_read_b128 v[224:227], v145 offset:21504
	ds_read_b128 v[228:231], v145 offset:22528
	ds_read_b128 v[232:235], v145 offset:23552
	global_load_lds_dwordx4 v[140:141], off
	s_add_i32 m0, s52, 0x2000
	s_add_u32 s52, s68, 0x20000
	v_lshl_add_u64 v[206:207], s[68:69], 0, v[130:131]
	s_addc_u32 s53, s69, 0
	s_add_i32 s49, s49, s2
	global_load_lds_dwordx4 v[206:207], off
	v_lshl_add_u64 v[214:215], s[52:53], 0, v[128:129]
	s_mov_b32 m0, s49
	v_lshl_add_u64 v[216:217], s[70:71], 0, v[132:133]
	global_load_lds_dwordx4 v[214:215], off
	v_lshl_add_u64 v[214:215], s[52:53], 0, v[130:131]
	s_add_i32 m0, s49, 0x2000
	s_nop 0
	global_load_lds_dwordx4 v[214:215], off
	v_lshl_add_u64 v[214:215], s[70:71], 0, v[134:135]
	s_mov_b32 m0, s7
	s_nop 0
	global_load_lds_dwordx4 v[214:215], off
	s_mov_b32 m0, s10
	s_nop 0
	global_load_lds_dwordx4 v[216:217], off
	s_cmp_lt_i32 s47, 0
	s_cbranch_scc0 .Lrx6_1_norm
	s_cmp_lt_u32 s29, 2
	s_cbranch_scc1 .Lrx6_1_norm
	s_waitcnt vmcnt(24)
	s_branch .Lrx6_1_join

; #define PG8_STAGE(bufoff, gbase, voff) do { _Pragma("unroll") for (int _i = 0; _i < 2; ++_i) \
;         __builtin_amdgcn_global_load_lds((const unsigned*)((const char*)(gbase) + (voff)[_i]), (PG8_LAS unsigned*)(lds + (bufoff) + ldsw + _i * 8192), 16, 0, 0); } while (0)
; #define PG8_LDA(dst, b, h) do { _Pragma("unroll") for (int m = 0; m < 4; ++m) _Pragma("unroll") for (int k = 0; k < 2; ++k) dst[m][k] = *(const PG8_LAS bf16x8*)(lds + PG8_SA(b, h) + aoff + m * 2048 + k * 1024); } while (0)
; #define PG8_LDB(dst, b, h) do { _Pragma("unroll") for (int n = 0; n < 2; ++n) _Pragma("unroll") for (int k = 0; k < 2; ++k) dst[n][k] = *(const PG8_LAS bf16x8*)(lds + PG8_SB(b, h) + boff + n * 2048 + k * 1024); } while (0)
; #define PG8_MMA(ai, bj, At, Bt) do { __builtin_amdgcn_s_setprio(1); _Pragma("unroll") for (int m = 0; m < 4; ++m) _Pragma("unroll") for (int n = 0; n < 2; ++n) _Pragma("unroll") for (int k = 0; k < 2; ++k) \
;         acc[ai][bj][m][n] = __builtin_amdgcn_mfma_f32_16x16x32_bf16(Bt[n][k], At[m][k], acc[ai][bj][m][n], 0, 0, 0); __builtin_amdgcn_s_setprio(0); } while (0)
; #define PG8_WAIT_V(n) asm volatile("s_waitcnt vmcnt(" #n ")" ::: "memory")
; #define PG8_WAIT_L(n) asm volatile("s_waitcnt lgkmcnt(" #n ")" ::: "memory")
; #define PG8_BAR __builtin_amdgcn_s_barrier()
; #define PG8_SCHED __builtin_amdgcn_sched_barrier(0)
; template <class Epi, class Sched, bool ALIGN_EPI = false, bool SP2 = false>
; __device__ __forceinline__ void gemm_phase(PG8_LAS unsigned char* lds, const Gemm g, const Sched& S, const Epi& E) {
;     ...
;             PG8_WAIT_V(8); PG8_WAIT_L(0); PG8_BAR; PG8_MMA(1, 0, At, B0); PG8_MMA(1, 1, At, B1); PG8_BAR; PG8_SCHED;
;             PG8_LDB(B0, 1, 0); PG8_LDB(B1, 1, 1); PG8_SCHED; PG8_LDA(At, 1, 0); PG8_STAGE(PG8_SA(0, 1), a2 + hstep, voffA);
;             PG8_WAIT_V(8); PG8_WAIT_L(0); PG8_BAR; PG8_MMA(0, 0, At, B0); PG8_MMA(0, 1, At, B1); PG8_BAR; PG8_SCHED;
.Lrx6_1_join:
	s_waitcnt lgkmcnt(0)
	s_barrier
	s_setprio 1
	s_waitcnt lgkmcnt(0)
	v_mfma_f32_16x16x32_bf16 v[60:63], v[146:149], v[178:181], v[60:63]
	v_mfma_f32_16x16x32_bf16 v[56:59], v[154:157], v[178:181], v[56:59]
	v_mfma_f32_16x16x32_bf16 v[44:47], v[146:149], v[186:189], v[44:47]
	v_mfma_f32_16x16x32_bf16 v[40:43], v[154:157], v[186:189], v[40:43]
	v_mfma_f32_16x16x32_bf16 v[28:31], v[146:149], v[220:223], v[28:31]
	v_mfma_f32_16x16x32_bf16 v[24:27], v[154:157], v[220:223], v[24:27]
	v_mfma_f32_16x16x32_bf16 v[12:15], v[146:149], v[228:231], v[12:15]
	v_mfma_f32_16x16x32_bf16 v[8:11], v[154:157], v[228:231], v[8:11]
	v_mfma_f32_16x16x32_bf16 v[60:63], v[150:153], v[182:185], v[60:63]
	v_mfma_f32_16x16x32_bf16 v[56:59], v[158:161], v[182:185], v[56:59]
	v_mfma_f32_16x16x32_bf16 v[44:47], v[150:153], v[190:193], v[44:47]
	v_mfma_f32_16x16x32_bf16 v[40:43], v[158:161], v[190:193], v[40:43]
	v_mfma_f32_16x16x32_bf16 v[28:31], v[150:153], v[224:227], v[28:31]
	v_mfma_f32_16x16x32_bf16 v[24:27], v[158:161], v[224:227], v[24:27]
	v_mfma_f32_16x16x32_bf16 v[12:15], v[150:153], v[232:235], v[12:15]
	v_mfma_f32_16x16x32_bf16 v[8:11], v[158:161], v[232:235], v[8:11]
	s_setprio 0
	s_setprio 1
	v_mfma_f32_16x16x32_bf16 v[52:55], v[162:165], v[178:181], v[52:55]
	v_mfma_f32_16x16x32_bf16 v[48:51], v[170:173], v[178:181], v[48:51]
	v_mfma_f32_16x16x32_bf16 v[36:39], v[162:165], v[186:189], v[36:39]
	v_mfma_f32_16x16x32_bf16 v[32:35], v[170:173], v[186:189], v[32:35]
	v_mfma_f32_16x16x32_bf16 v[20:23], v[162:165], v[220:223], v[20:23]
	v_mfma_f32_16x16x32_bf16 v[16:19], v[170:173], v[220:223], v[16:19]
	v_mfma_f32_16x16x32_bf16 v[4:7], v[162:165], v[228:231], v[4:7]
	v_mfma_f32_16x16x32_bf16 v[0:3], v[170:173], v[228:231], v[0:3]
	v_mfma_f32_16x16x32_bf16 v[52:55], v[166:169], v[182:185], v[52:55]
	v_mfma_f32_16x16x32_bf16 v[48:51], v[174:177], v[182:185], v[48:51]
	v_mfma_f32_16x16x32_bf16 v[36:39], v[166:169], v[190:193], v[36:39]
	v_mfma_f32_16x16x32_bf16 v[32:35], v[174:177], v[190:193], v[32:35]
	v_mfma_f32_16x16x32_bf16 v[20:23], v[166:169], v[224:227], v[20:23]
	v_mfma_f32_16x16x32_bf16 v[16:19], v[174:177], v[224:227], v[16:19]
	v_mfma_f32_16x16x32_bf16 v[4:7], v[166:169], v[232:235], v[4:7]
	v_mfma_f32_16x16x32_bf16 v[0:3], v[174:177], v[232:235], v[0:3]
	s_setprio 0
	s_barrier
	s_add_i32 s49, 0, 0x18000
	s_add_i32 s63, 0, 0x1c000
	v_add_u32_e32 v158, s49, v143
	v_add_u32_e32 v174, s63, v143
	ds_read_b128 v[146:149], v158
	ds_read_b128 v[150:153], v158 offset:1024
	ds_read_b128 v[154:157], v158 offset:2048
	ds_read_b128 v[158:161], v158 offset:3072
	ds_read_b128 v[162:165], v174
	ds_read_b128 v[166:169], v174 offset:1024
	ds_read_b128 v[170:173], v174 offset:2048
	ds_read_b128 v[174:177], v174 offset:3072
	s_add_u32 s52, s70, 0x80000
	s_addc_u32 s53, s71, 0
	s_mov_b32 m0, s17
	v_lshl_add_u64 v[236:237], s[52:53], 0, v[134:135]
	ds_read_b128 v[178:181], v145 offset:32768
	ds_read_b128 v[182:185], v145 offset:33792
	ds_read_b128 v[186:189], v145 offset:34816
	ds_read_b128 v[190:193], v145 offset:35840
	ds_read_b128 v[220:223], v145 offset:36864
	ds_read_b128 v[224:227], v145 offset:37888
	ds_read_b128 v[228:231], v145 offset:38912
	ds_read_b128 v[232:235], v145 offset:39936
	global_load_lds_dwordx4 v[236:237], off
	v_lshl_add_u64 v[236:237], s[52:53], 0, v[132:133]
	s_mov_b32 m0, s26
	s_nop 0
	global_load_lds_dwordx4 v[236:237], off
	s_waitcnt vmcnt(8)
	s_waitcnt lgkmcnt(0)
	s_barrier
	s_setprio 1
	s_waitcnt lgkmcnt(0)
	v_mfma_f32_16x16x32_bf16 v[124:127], v[146:149], v[178:181], v[124:127]
	v_mfma_f32_16x16x32_bf16 v[120:123], v[154:157], v[178:181], v[120:123]
	v_mfma_f32_16x16x32_bf16 v[108:111], v[146:149], v[186:189], v[108:111]
	v_mfma_f32_16x16x32_bf16 v[104:107], v[154:157], v[186:189], v[104:107]
	v_mfma_f32_16x16x32_bf16 v[92:95], v[146:149], v[220:223], v[92:95]
	v_mfma_f32_16x16x32_bf16 v[88:91], v[154:157], v[220:223], v[88:91]
	v_mfma_f32_16x16x32_bf16 v[76:79], v[146:149], v[228:231], v[76:79]
	v_mfma_f32_16x16x32_bf16 v[72:75], v[154:157], v[228:231], v[72:75]
	v_mfma_f32_16x16x32_bf16 v[124:127], v[150:153], v[182:185], v[124:127]
	v_mfma_f32_16x16x32_bf16 v[120:123], v[158:161], v[182:185], v[120:123]
	v_mfma_f32_16x16x32_bf16 v[108:111], v[150:153], v[190:193], v[108:111]
	v_mfma_f32_16x16x32_bf16 v[104:107], v[158:161], v[190:193], v[104:107]
	v_mfma_f32_16x16x32_bf16 v[92:95], v[150:153], v[224:227], v[92:95]
	v_mfma_f32_16x16x32_bf16 v[88:91], v[158:161], v[224:227], v[88:91]
	v_mfma_f32_16x16x32_bf16 v[76:79], v[150:153], v[232:235], v[76:79]
	v_mfma_f32_16x16x32_bf16 v[72:75], v[158:161], v[232:235], v[72:75]
	s_setprio 0
	s_setprio 1
	v_mfma_f32_16x16x32_bf16 v[116:119], v[162:165], v[178:181], v[116:119]
	v_mfma_f32_16x16x32_bf16 v[112:115], v[170:173], v[178:181], v[112:115]
	v_mfma_f32_16x16x32_bf16 v[100:103], v[162:165], v[186:189], v[100:103]
	v_mfma_f32_16x16x32_bf16 v[96:99], v[170:173], v[186:189], v[96:99]
	v_mfma_f32_16x16x32_bf16 v[84:87], v[162:165], v[220:223], v[84:87]
	v_mfma_f32_16x16x32_bf16 v[80:83], v[170:173], v[220:223], v[80:83]
	v_mfma_f32_16x16x32_bf16 v[68:71], v[162:165], v[228:231], v[68:71]
	v_mfma_f32_16x16x32_bf16 v[64:67], v[170:173], v[228:231], v[64:67]
	v_mfma_f32_16x16x32_bf16 v[116:119], v[166:169], v[182:185], v[116:119]
	v_mfma_f32_16x16x32_bf16 v[112:115], v[174:177], v[182:185], v[112:115]
	v_mfma_f32_16x16x32_bf16 v[100:103], v[166:169], v[190:193], v[100:103]
	v_mfma_f32_16x16x32_bf16 v[96:99], v[174:177], v[190:193], v[96:99]
	v_mfma_f32_16x16x32_bf16 v[84:87], v[166:169], v[224:227], v[84:87]
	v_mfma_f32_16x16x32_bf16 v[80:83], v[174:177], v[224:227], v[80:83]
	v_mfma_f32_16x16x32_bf16 v[68:71], v[166:169], v[232:235], v[68:71]
	v_mfma_f32_16x16x32_bf16 v[64:67], v[174:177], v[232:235], v[64:67]
	s_setprio 0
	s_barrier
; #define PG8_STAGE(bufoff, gbase, voff) do { _Pragma("unroll") for (int _i = 0; _i < 2; ++_i) \
;         __builtin_amdgcn_global_load_lds((const unsigned*)((const char*)(gbase) + (voff)[_i]), (PG8_LAS unsigned*)(lds + (bufoff) + ldsw + _i * 8192), 16, 0, 0); } while (0)
; #define PG8_LDA(dst, b, h) do { _Pragma("unroll") for (int m = 0; m < 4; ++m) _Pragma("unroll") for (int k = 0; k < 2; ++k) dst[m][k] = *(const PG8_LAS bf16x8*)(lds + PG8_SA(b, h) + aoff + m * 2048 + k * 1024); } while (0)
; #define PG8_LDB(dst, b, h) do { _Pragma("unroll") for (int n = 0; n < 2; ++n) _Pragma("unroll") for (int k = 0; k < 2; ++k) dst[n][k] = *(const PG8_LAS bf16x8*)(lds + PG8_SB(b, h) + boff + n * 2048 + k * 1024); } while (0)
; #define PG8_MMA(ai, bj, At, Bt) do { __builtin_amdgcn_s_setprio(1); _Pragma("unroll") for (int m = 0; m < 4; ++m) _Pragma("unroll") for (int n = 0; n < 2; ++n) _Pragma("unroll") for (int k = 0; k < 2; ++k) \
;         acc[ai][bj][m][n] = __builtin_amdgcn_mfma_f32_16x16x32_bf16(Bt[n][k], At[m][k], acc[ai][bj][m][n], 0, 0, 0); __builtin_amdgcn_s_setprio(0); } while (0)
; #define PG8_WAIT_V(n) asm volatile("s_waitcnt vmcnt(" #n ")" ::: "memory")
; #define PG8_WAIT_L(n) asm volatile("s_waitcnt lgkmcnt(" #n ")" ::: "memory")
; #define PG8_BAR __builtin_amdgcn_s_barrier()
; #define PG8_SCHED __builtin_amdgcn_sched_barrier(0)
; template <class Epi, class Sched, bool ALIGN_EPI = false, bool SP2 = false>
; __device__ __forceinline__ void gemm_phase(PG8_LAS unsigned char* lds, const Gemm g, const Sched& S, const Epi& E) {
;     ...
;             PG8_LDA(At, 0, 1); PG8_STAGE(PG8_SB(0, 0), b2, voffB); PG8_STAGE(PG8_SB(0, 1), b2 + hstep, voffB); PG8_STAGE(PG8_SA(0, 0), a2, voffA);
;             PG8_WAIT_V(8); PG8_WAIT_L(0); PG8_BAR; PG8_MMA(1, 0, At, B0); PG8_MMA(1, 1, At, B1); PG8_BAR; PG8_SCHED;
;             PG8_LDB(B0, 1, 0); PG8_LDB(B1, 1, 1); PG8_SCHED; PG8_LDA(At, 1, 0); PG8_STAGE(PG8_SA(0, 1), a2 + hstep, voffA);
;             PG8_WAIT_V(8); PG8_WAIT_L(0); PG8_BAR; PG8_MMA(0, 0, At, B0); PG8_MMA(0, 1, At, B1); PG8_BAR; PG8_SCHED;
;             PG8_LDA(At, 1, 1); PG8_STAGE(PG8_SB(1, 0), b3, voffB); PG8_STAGE(PG8_SB(1, 1), b3 + hstep, voffB); PG8_STAGE(PG8_SA(1, 0), a3, voffA);
;             PG8_WAIT_V(8); PG8_WAIT_L(0); PG8_BAR; PG8_MMA(1, 0, At, B0); PG8_MMA(1, 1, At, B1); PG8_BAR; PG8_SCHED;
	s_add_i32 s49, s49, s2
	v_lshl_add_u64 v[140:141], v[140:141], 0, s[20:21]
	s_mov_b32 m0, s49
	ds_read_b128 v[178:181], v145 offset:49152
	ds_read_b128 v[182:185], v145 offset:50176
	ds_read_b128 v[186:189], v145 offset:51200
	ds_read_b128 v[190:193], v145 offset:52224
	ds_read_b128 v[220:223], v145 offset:53248
	ds_read_b128 v[224:227], v145 offset:54272
	ds_read_b128 v[228:231], v145 offset:55296
	ds_read_b128 v[232:235], v145 offset:56320
	global_load_lds_dwordx4 v[140:141], off
	s_add_i32 m0, s49, 0x2000
	s_add_u32 s52, s68, 0x20080
	v_lshl_add_u64 v[140:141], v[206:207], 0, s[20:21]
	s_addc_u32 s53, s69, 0
	s_add_i32 s49, s63, s2
	global_load_lds_dwordx4 v[140:141], off
	v_lshl_add_u64 v[140:141], s[52:53], 0, v[128:129]
	s_mov_b32 m0, s49
	s_nop 0
	global_load_lds_dwordx4 v[140:141], off
	v_lshl_add_u64 v[140:141], s[52:53], 0, v[130:131]
	s_add_i32 m0, s49, 0x2000
	s_nop 0
	global_load_lds_dwordx4 v[140:141], off
	v_lshl_add_u64 v[140:141], v[214:215], 0, s[20:21]
	s_mov_b32 m0, s27
	s_nop 0
	global_load_lds_dwordx4 v[140:141], off
	v_lshl_add_u64 v[140:141], v[216:217], 0, s[20:21]
	s_mov_b32 m0, s28
	s_nop 0
	global_load_lds_dwordx4 v[140:141], off
	s_waitcnt vmcnt(8)
	s_waitcnt lgkmcnt(0)
	s_barrier
	s_setprio 1
	s_waitcnt lgkmcnt(0)
	v_mfma_f32_16x16x32_bf16 v[60:63], v[146:149], v[178:181], v[60:63]
	v_mfma_f32_16x16x32_bf16 v[56:59], v[154:157], v[178:181], v[56:59]
	v_mfma_f32_16x16x32_bf16 v[44:47], v[146:149], v[186:189], v[44:47]
	v_mfma_f32_16x16x32_bf16 v[40:43], v[154:157], v[186:189], v[40:43]
	v_mfma_f32_16x16x32_bf16 v[28:31], v[146:149], v[220:223], v[28:31]
	v_mfma_f32_16x16x32_bf16 v[24:27], v[154:157], v[220:223], v[24:27]
	v_mfma_f32_16x16x32_bf16 v[12:15], v[146:149], v[228:231], v[12:15]
	v_mfma_f32_16x16x32_bf16 v[8:11], v[154:157], v[228:231], v[8:11]
	v_mfma_f32_16x16x32_bf16 v[60:63], v[150:153], v[182:185], v[60:63]
	v_mfma_f32_16x16x32_bf16 v[56:59], v[158:161], v[182:185], v[56:59]
	v_mfma_f32_16x16x32_bf16 v[44:47], v[150:153], v[190:193], v[44:47]
	v_mfma_f32_16x16x32_bf16 v[40:43], v[158:161], v[190:193], v[40:43]
	v_mfma_f32_16x16x32_bf16 v[28:31], v[150:153], v[224:227], v[28:31]
	v_mfma_f32_16x16x32_bf16 v[24:27], v[158:161], v[224:227], v[24:27]
	v_mfma_f32_16x16x32_bf16 v[12:15], v[150:153], v[232:235], v[12:15]
	v_mfma_f32_16x16x32_bf16 v[8:11], v[158:161], v[232:235], v[8:11]
	s_setprio 0
	s_setprio 1
	v_mfma_f32_16x16x32_bf16 v[52:55], v[162:165], v[178:181], v[52:55]
	v_mfma_f32_16x16x32_bf16 v[48:51], v[170:173], v[178:181], v[48:51]
	v_mfma_f32_16x16x32_bf16 v[36:39], v[162:165], v[186:189], v[36:39]
	v_mfma_f32_16x16x32_bf16 v[32:35], v[170:173], v[186:189], v[32:35]
	v_mfma_f32_16x16x32_bf16 v[20:23], v[162:165], v[220:223], v[20:23]
	v_mfma_f32_16x16x32_bf16 v[16:19], v[170:173], v[220:223], v[16:19]
	v_mfma_f32_16x16x32_bf16 v[4:7], v[162:165], v[228:231], v[4:7]
	v_mfma_f32_16x16x32_bf16 v[0:3], v[170:173], v[228:231], v[0:3]
	v_mfma_f32_16x16x32_bf16 v[52:55], v[166:169], v[182:185], v[52:55]
	v_mfma_f32_16x16x32_bf16 v[48:51], v[174:177], v[182:185], v[48:51]
	v_mfma_f32_16x16x32_bf16 v[36:39], v[166:169], v[190:193], v[36:39]
	v_mfma_f32_16x16x32_bf16 v[32:35], v[174:177], v[190:193], v[32:35]
	v_mfma_f32_16x16x32_bf16 v[20:23], v[166:169], v[224:227], v[20:23]
	v_mfma_f32_16x16x32_bf16 v[16:19], v[174:177], v[224:227], v[16:19]
	v_mfma_f32_16x16x32_bf16 v[4:7], v[166:169], v[232:235], v[4:7]
	v_mfma_f32_16x16x32_bf16 v[0:3], v[174:177], v[232:235], v[0:3]
	s_setprio 0
	s_barrier
	s_add_i32 s47, s47, 2
	s_add_u32 s66, s66, 0x100
	s_addc_u32 s67, s67, 0
	s_add_u32 s35, s35, 0x100
	s_addc_u32 s37, s37, 0
	s_cmp_gt_u32 s47, 29
	s_cbranch_scc0 .LBB0_455
	s_and_b64 vcc, exec, s[12:13]
	s_cbranch_vccz .LBB0_458
	s_barrier

; #define PG8_STAGE(bufoff, gbase, voff) do { _Pragma("unroll") for (int _i = 0; _i < 2; ++_i) \
;         __builtin_amdgcn_global_load_lds((const unsigned*)((const char*)(gbase) + (voff)[_i]), (PG8_LAS unsigned*)(lds + (bufoff) + ldsw + _i * 8192), 16, 0, 0); } while (0)
; #define PG8_LDA(dst, b, h) do { _Pragma("unroll") for (int m = 0; m < 4; ++m) _Pragma("unroll") for (int k = 0; k < 2; ++k) dst[m][k] = *(const PG8_LAS bf16x8*)(lds + PG8_SA(b, h) + aoff + m * 2048 + k * 1024); } while (0)
; #define PG8_LDB(dst, b, h) do { _Pragma("unroll") for (int n = 0; n < 2; ++n) _Pragma("unroll") for (int k = 0; k < 2; ++k) dst[n][k] = *(const PG8_LAS bf16x8*)(lds + PG8_SB(b, h) + boff + n * 2048 + k * 1024); } while (0)
; #define PG8_MMA(ai, bj, At, Bt) do { __builtin_amdgcn_s_setprio(1); _Pragma("unroll") for (int m = 0; m < 4; ++m) _Pragma("unroll") for (int n = 0; n < 2; ++n) _Pragma("unroll") for (int k = 0; k < 2; ++k) \
;         acc[ai][bj][m][n] = __builtin_amdgcn_mfma_f32_16x16x32_bf16(Bt[n][k], At[m][k], acc[ai][bj][m][n], 0, 0, 0); __builtin_amdgcn_s_setprio(0); } while (0)
; #define PG8_WAIT_V(n) asm volatile("s_waitcnt vmcnt(" #n ")" ::: "memory")
; #define PG8_WAIT_L(n) asm volatile("s_waitcnt lgkmcnt(" #n ")" ::: "memory")
; #define PG8_BAR __builtin_amdgcn_s_barrier()
; #define PG8_SCHED __builtin_amdgcn_sched_barrier(0)
; template <class Epi, class Sched, bool ALIGN_EPI = false, bool SP2 = false>
; __device__ __forceinline__ void gemm_phase(PG8_LAS unsigned char* lds, const Gemm g, const Sched& S, const Epi& E) {
;     ...
;         for (int t = 0; t < nt; t += 2) {
;             const bool last = (t == nt - 2);
;             const char* a1 = cA + (size_t)(t + 1) * kstep;
;             const char* a2 = last ? nA : cA + (size_t)(t + 2) * kstep; const char* b2 = last ? nB : cB + (size_t)(t + 2) * kstep;
;             const char* a3 = a2 + kstep; const char* b3 = b2 + kstep;
;             if (last && has_next) S.a_ready(nxt);
;             if constexpr (SP2) {
;             PG8_LDB(B0, 0, 0); PG8_LDB(B1, 0, 1); PG8_SCHED; PG8_LDA(At, 0, 0); PG8_STAGE(PG8_SA(1, 1), a1 + hstep, voffA);
;             PG8_WAIT_V(8); PG8_WAIT_L(0); PG8_BAR; PG8_MMA(0, 0, At, B0); PG8_MMA(0, 1, At, B1); PG8_BAR; PG8_SCHED;
.LBB0_485:
	s_add_u32 s43, s66, 0xfff80080
	s_addc_u32 s45, s67, -1
	s_add_i32 s49, 0, 0x10000
	s_cmp_eq_u32 s37, 28
	s_cselect_b32 s71, s19, s45
	s_cselect_b32 s70, s29, s43
	v_add_u32_e32 v140, s49, v143
	s_cselect_b32 s69, s31, s35
	s_cselect_b32 s68, s33, s34
	s_add_i32 s43, 0, 0x14000
	ds_read_b128 v[146:149], v140
	ds_read_b128 v[150:153], v140 offset:1024
	ds_read_b128 v[154:157], v140 offset:2048
	ds_read_b128 v[158:161], v140 offset:3072
	v_add_u32_e32 v140, s43, v143
	ds_read_b128 v[162:165], v140
	ds_read_b128 v[166:169], v140 offset:1024
	ds_read_b128 v[170:173], v140 offset:2048
	ds_read_b128 v[174:177], v140 offset:3072
	v_lshl_add_u64 v[140:141], s[66:67], 0, v[136:137]
	s_add_i32 m0, s6, 0xc000
	ds_read_b128 v[178:181], v145
	ds_read_b128 v[182:185], v145 offset:1024
	ds_read_b128 v[186:189], v145 offset:2048
	ds_read_b128 v[190:193], v145 offset:3072
	ds_read_b128 v[220:223], v145 offset:4096
	ds_read_b128 v[224:227], v145 offset:5120
	ds_read_b128 v[228:231], v145 offset:6144
	ds_read_b128 v[232:235], v145 offset:7168
	global_load_lds_dwordx4 v[140:141], off
	v_lshl_add_u64 v[140:141], s[66:67], 0, v[138:139]
	s_add_i32 m0, s6, 0xe000
	s_nop 0
	global_load_lds_dwordx4 v[140:141], off
	s_cmp_lt_i32 s37, 0
	s_cbranch_scc0 .Lrx4_0_norm
	s_cmp_lt_u32 s28, 2
	s_cbranch_scc1 .Lrx4_0_norm
	s_waitcnt vmcnt(24)
	s_branch .Lrx4_0_join

; #define PG8_STAGE(bufoff, gbase, voff) do { _Pragma("unroll") for (int _i = 0; _i < 2; ++_i) \
;         __builtin_amdgcn_global_load_lds((const unsigned*)((const char*)(gbase) + (voff)[_i]), (PG8_LAS unsigned*)(lds + (bufoff) + ldsw + _i * 8192), 16, 0, 0); } while (0)
; #define PG8_LDA(dst, b, h) do { _Pragma("unroll") for (int m = 0; m < 4; ++m) _Pragma("unroll") for (int k = 0; k < 2; ++k) dst[m][k] = *(const PG8_LAS bf16x8*)(lds + PG8_SA(b, h) + aoff + m * 2048 + k * 1024); } while (0)
; #define PG8_MMA(ai, bj, At, Bt) do { __builtin_amdgcn_s_setprio(1); _Pragma("unroll") for (int m = 0; m < 4; ++m) _Pragma("unroll") for (int n = 0; n < 2; ++n) _Pragma("unroll") for (int k = 0; k < 2; ++k) \
;         acc[ai][bj][m][n] = __builtin_amdgcn_mfma_f32_16x16x32_bf16(Bt[n][k], At[m][k], acc[ai][bj][m][n], 0, 0, 0); __builtin_amdgcn_s_setprio(0); } while (0)
; #define PG8_WAIT_V(n) asm volatile("s_waitcnt vmcnt(" #n ")" ::: "memory")
; #define PG8_WAIT_L(n) asm volatile("s_waitcnt lgkmcnt(" #n ")" ::: "memory")
; #define PG8_BAR __builtin_amdgcn_s_barrier()
; #define PG8_SCHED __builtin_amdgcn_sched_barrier(0)
; template <class Epi, class Sched, bool ALIGN_EPI = false, bool SP2 = false>
; __device__ __forceinline__ void gemm_phase(PG8_LAS unsigned char* lds, const Gemm g, const Sched& S, const Epi& E) {
;     ...
;             PG8_WAIT_V(8); PG8_WAIT_L(0); PG8_BAR; PG8_MMA(0, 0, At, B0); PG8_MMA(0, 1, At, B1); PG8_BAR; PG8_SCHED;
;             PG8_LDA(At, 0, 1); PG8_STAGE(PG8_SB(0, 0), b2, voffB); PG8_STAGE(PG8_SB(0, 1), b2 + hstep, voffB); PG8_STAGE(PG8_SA(0, 0), a2, voffA);
;             PG8_WAIT_V(8); PG8_WAIT_L(0); PG8_BAR; PG8_MMA(1, 0, At, B0); PG8_MMA(1, 1, At, B1); PG8_BAR; PG8_SCHED;
.Lrx4_0_join:
	s_waitcnt lgkmcnt(0)
	s_barrier
	s_setprio 1
	s_waitcnt lgkmcnt(0)
	v_mfma_f32_16x16x32_bf16 v[124:127], v[146:149], v[178:181], v[124:127]
	v_mfma_f32_16x16x32_bf16 v[120:123], v[154:157], v[178:181], v[120:123]
	v_mfma_f32_16x16x32_bf16 v[116:119], v[146:149], v[186:189], v[116:119]
	v_mfma_f32_16x16x32_bf16 v[108:111], v[154:157], v[186:189], v[108:111]
	v_mfma_f32_16x16x32_bf16 v[100:103], v[146:149], v[220:223], v[100:103]
	v_mfma_f32_16x16x32_bf16 v[92:95], v[154:157], v[220:223], v[92:95]
	v_mfma_f32_16x16x32_bf16 v[84:87], v[146:149], v[228:231], v[84:87]
	v_mfma_f32_16x16x32_bf16 v[76:79], v[154:157], v[228:231], v[76:79]
	v_mfma_f32_16x16x32_bf16 v[124:127], v[150:153], v[182:185], v[124:127]
	v_mfma_f32_16x16x32_bf16 v[120:123], v[158:161], v[182:185], v[120:123]
	v_mfma_f32_16x16x32_bf16 v[116:119], v[150:153], v[190:193], v[116:119]
	v_mfma_f32_16x16x32_bf16 v[108:111], v[158:161], v[190:193], v[108:111]
	v_mfma_f32_16x16x32_bf16 v[100:103], v[150:153], v[224:227], v[100:103]
	v_mfma_f32_16x16x32_bf16 v[92:95], v[158:161], v[224:227], v[92:95]
	v_mfma_f32_16x16x32_bf16 v[84:87], v[150:153], v[232:235], v[84:87]
	v_mfma_f32_16x16x32_bf16 v[76:79], v[158:161], v[232:235], v[76:79]
	s_setprio 0
	s_setprio 1
	v_mfma_f32_16x16x32_bf16 v[112:115], v[162:165], v[178:181], v[112:115]
	v_mfma_f32_16x16x32_bf16 v[104:107], v[170:173], v[178:181], v[104:107]
	v_mfma_f32_16x16x32_bf16 v[96:99], v[162:165], v[186:189], v[96:99]
	v_mfma_f32_16x16x32_bf16 v[88:91], v[170:173], v[186:189], v[88:91]
	v_mfma_f32_16x16x32_bf16 v[80:83], v[162:165], v[220:223], v[80:83]
	v_mfma_f32_16x16x32_bf16 v[72:75], v[170:173], v[220:223], v[72:75]
	v_mfma_f32_16x16x32_bf16 v[68:71], v[162:165], v[228:231], v[68:71]
	v_mfma_f32_16x16x32_bf16 v[64:67], v[170:173], v[228:231], v[64:67]
	v_mfma_f32_16x16x32_bf16 v[112:115], v[166:169], v[182:185], v[112:115]
	v_mfma_f32_16x16x32_bf16 v[104:107], v[174:177], v[182:185], v[104:107]
	v_mfma_f32_16x16x32_bf16 v[96:99], v[166:169], v[190:193], v[96:99]
	v_mfma_f32_16x16x32_bf16 v[88:91], v[174:177], v[190:193], v[88:91]
	v_mfma_f32_16x16x32_bf16 v[80:83], v[166:169], v[224:227], v[80:83]
	v_mfma_f32_16x16x32_bf16 v[72:75], v[174:177], v[224:227], v[72:75]
	v_mfma_f32_16x16x32_bf16 v[68:71], v[166:169], v[232:235], v[68:71]
	v_mfma_f32_16x16x32_bf16 v[64:67], v[174:177], v[232:235], v[64:67]
	s_setprio 0
	s_barrier
	s_add_i32 s45, s49, s2
	v_lshl_add_u64 v[140:141], s[68:69], 0, v[128:129]
	s_mov_b32 m0, s45
	ds_read_b128 v[178:181], v145 offset:16384
	ds_read_b128 v[182:185], v145 offset:17408
	ds_read_b128 v[186:189], v145 offset:18432
	ds_read_b128 v[190:193], v145 offset:19456
	ds_read_b128 v[220:223], v145 offset:20480
	ds_read_b128 v[224:227], v145 offset:21504
	ds_read_b128 v[228:231], v145 offset:22528
	ds_read_b128 v[232:235], v145 offset:23552
	global_load_lds_dwordx4 v[140:141], off
	s_add_i32 m0, s45, 0x2000
	s_add_u32 s52, s68, 0x80000
	v_lshl_add_u64 v[206:207], s[68:69], 0, v[130:131]
	s_addc_u32 s53, s69, 0
	s_add_i32 s43, s43, s2
	global_load_lds_dwordx4 v[206:207], off
	v_lshl_add_u64 v[214:215], s[52:53], 0, v[128:129]
	s_mov_b32 m0, s43
	v_lshl_add_u64 v[216:217], s[70:71], 0, v[132:133]
	global_load_lds_dwordx4 v[214:215], off
	v_lshl_add_u64 v[214:215], s[52:53], 0, v[130:131]
	s_add_i32 m0, s43, 0x2000
	s_nop 0
	global_load_lds_dwordx4 v[214:215], off
	v_lshl_add_u64 v[214:215], s[70:71], 0, v[134:135]
	s_mov_b32 m0, s6
	s_nop 0
	global_load_lds_dwordx4 v[214:215], off
	s_mov_b32 m0, s7
	s_nop 0
	global_load_lds_dwordx4 v[216:217], off
	s_cmp_lt_i32 s37, 0
	s_cbranch_scc0 .Lrx4_1_norm
	s_cmp_lt_u32 s28, 2
	s_cbranch_scc1 .Lrx4_1_norm
	s_waitcnt vmcnt(24)
	s_branch .Lrx4_1_join

; #define PG8_STAGE(bufoff, gbase, voff) do { _Pragma("unroll") for (int _i = 0; _i < 2; ++_i) \
;         __builtin_amdgcn_global_load_lds((const unsigned*)((const char*)(gbase) + (voff)[_i]), (PG8_LAS unsigned*)(lds + (bufoff) + ldsw + _i * 8192), 16, 0, 0); } while (0)
; #define PG8_LDA(dst, b, h) do { _Pragma("unroll") for (int m = 0; m < 4; ++m) _Pragma("unroll") for (int k = 0; k < 2; ++k) dst[m][k] = *(const PG8_LAS bf16x8*)(lds + PG8_SA(b, h) + aoff + m * 2048 + k * 1024); } while (0)
; #define PG8_LDB(dst, b, h) do { _Pragma("unroll") for (int n = 0; n < 2; ++n) _Pragma("unroll") for (int k = 0; k < 2; ++k) dst[n][k] = *(const PG8_LAS bf16x8*)(lds + PG8_SB(b, h) + boff + n * 2048 + k * 1024); } while (0)
; #define PG8_MMA(ai, bj, At, Bt) do { __builtin_amdgcn_s_setprio(1); _Pragma("unroll") for (int m = 0; m < 4; ++m) _Pragma("unroll") for (int n = 0; n < 2; ++n) _Pragma("unroll") for (int k = 0; k < 2; ++k) \
;         acc[ai][bj][m][n] = __builtin_amdgcn_mfma_f32_16x16x32_bf16(Bt[n][k], At[m][k], acc[ai][bj][m][n], 0, 0, 0); __builtin_amdgcn_s_setprio(0); } while (0)
; #define PG8_WAIT_V(n) asm volatile("s_waitcnt vmcnt(" #n ")" ::: "memory")
; #define PG8_WAIT_L(n) asm volatile("s_waitcnt lgkmcnt(" #n ")" ::: "memory")
; #define PG8_BAR __builtin_amdgcn_s_barrier()
; #define PG8_SCHED __builtin_amdgcn_sched_barrier(0)
; template <class Epi, class Sched, bool ALIGN_EPI = false, bool SP2 = false>
; __device__ __forceinline__ void gemm_phase(PG8_LAS unsigned char* lds, const Gemm g, const Sched& S, const Epi& E) {
;     ...
;             PG8_WAIT_V(8); PG8_WAIT_L(0); PG8_BAR; PG8_MMA(1, 0, At, B0); PG8_MMA(1, 1, At, B1); PG8_BAR; PG8_SCHED;
;             PG8_LDB(B0, 1, 0); PG8_LDB(B1, 1, 1); PG8_SCHED; PG8_LDA(At, 1, 0); PG8_STAGE(PG8_SA(0, 1), a2 + hstep, voffA);
;             PG8_WAIT_V(8); PG8_WAIT_L(0); PG8_BAR; PG8_MMA(0, 0, At, B0); PG8_MMA(0, 1, At, B1); PG8_BAR; PG8_SCHED;
.Lrx4_1_join:
	s_waitcnt lgkmcnt(0)
	s_barrier
	s_setprio 1
	s_waitcnt lgkmcnt(0)
	v_mfma_f32_16x16x32_bf16 v[60:63], v[146:149], v[178:181], v[60:63]
	v_mfma_f32_16x16x32_bf16 v[56:59], v[154:157], v[178:181], v[56:59]
	v_mfma_f32_16x16x32_bf16 v[52:55], v[146:149], v[186:189], v[52:55]
	v_mfma_f32_16x16x32_bf16 v[44:47], v[154:157], v[186:189], v[44:47]
	v_mfma_f32_16x16x32_bf16 v[36:39], v[146:149], v[220:223], v[36:39]
	v_mfma_f32_16x16x32_bf16 v[28:31], v[154:157], v[220:223], v[28:31]
	v_mfma_f32_16x16x32_bf16 v[20:23], v[146:149], v[228:231], v[20:23]
	v_mfma_f32_16x16x32_bf16 v[12:15], v[154:157], v[228:231], v[12:15]
	v_mfma_f32_16x16x32_bf16 v[60:63], v[150:153], v[182:185], v[60:63]
	v_mfma_f32_16x16x32_bf16 v[56:59], v[158:161], v[182:185], v[56:59]
	v_mfma_f32_16x16x32_bf16 v[52:55], v[150:153], v[190:193], v[52:55]
	v_mfma_f32_16x16x32_bf16 v[44:47], v[158:161], v[190:193], v[44:47]
	v_mfma_f32_16x16x32_bf16 v[36:39], v[150:153], v[224:227], v[36:39]
	v_mfma_f32_16x16x32_bf16 v[28:31], v[158:161], v[224:227], v[28:31]
	v_mfma_f32_16x16x32_bf16 v[20:23], v[150:153], v[232:235], v[20:23]
	v_mfma_f32_16x16x32_bf16 v[12:15], v[158:161], v[232:235], v[12:15]
	s_setprio 0
	s_setprio 1
	v_mfma_f32_16x16x32_bf16 v[48:51], v[162:165], v[178:181], v[48:51]
	v_mfma_f32_16x16x32_bf16 v[40:43], v[170:173], v[178:181], v[40:43]
	v_mfma_f32_16x16x32_bf16 v[32:35], v[162:165], v[186:189], v[32:35]
	v_mfma_f32_16x16x32_bf16 v[24:27], v[170:173], v[186:189], v[24:27]
	v_mfma_f32_16x16x32_bf16 v[16:19], v[162:165], v[220:223], v[16:19]
	v_mfma_f32_16x16x32_bf16 v[8:11], v[170:173], v[220:223], v[8:11]
	v_mfma_f32_16x16x32_bf16 v[4:7], v[162:165], v[228:231], v[4:7]
	v_mfma_f32_16x16x32_bf16 v[0:3], v[170:173], v[228:231], v[0:3]
	v_mfma_f32_16x16x32_bf16 v[48:51], v[166:169], v[182:185], v[48:51]
	v_mfma_f32_16x16x32_bf16 v[40:43], v[174:177], v[182:185], v[40:43]
	v_mfma_f32_16x16x32_bf16 v[32:35], v[166:169], v[190:193], v[32:35]
	v_mfma_f32_16x16x32_bf16 v[24:27], v[174:177], v[190:193], v[24:27]
	v_mfma_f32_16x16x32_bf16 v[16:19], v[166:169], v[224:227], v[16:19]
	v_mfma_f32_16x16x32_bf16 v[8:11], v[174:177], v[224:227], v[8:11]
	v_mfma_f32_16x16x32_bf16 v[4:7], v[166:169], v[232:235], v[4:7]
	v_mfma_f32_16x16x32_bf16 v[0:3], v[174:177], v[232:235], v[0:3]
	s_setprio 0
	s_barrier
	s_add_i32 s43, 0, 0x18000
	s_add_i32 s45, 0, 0x1c000
	v_add_u32_e32 v158, s43, v143
	v_add_u32_e32 v174, s45, v143
	ds_read_b128 v[146:149], v158
	ds_read_b128 v[150:153], v158 offset:1024
	ds_read_b128 v[154:157], v158 offset:2048
	ds_read_b128 v[158:161], v158 offset:3072
	ds_read_b128 v[162:165], v174
	ds_read_b128 v[166:169], v174 offset:1024
	ds_read_b128 v[170:173], v174 offset:2048
	ds_read_b128 v[174:177], v174 offset:3072
	s_add_u32 s52, s70, 0x80000
	s_addc_u32 s53, s71, 0
	s_mov_b32 m0, s10
	v_lshl_add_u64 v[236:237], s[52:53], 0, v[134:135]
	ds_read_b128 v[178:181], v145 offset:32768
	ds_read_b128 v[182:185], v145 offset:33792
	ds_read_b128 v[186:189], v145 offset:34816
	ds_read_b128 v[190:193], v145 offset:35840
	ds_read_b128 v[220:223], v145 offset:36864
	ds_read_b128 v[224:227], v145 offset:37888
	ds_read_b128 v[228:231], v145 offset:38912
	ds_read_b128 v[232:235], v145 offset:39936
	global_load_lds_dwordx4 v[236:237], off
	v_lshl_add_u64 v[236:237], s[52:53], 0, v[132:133]
	s_mov_b32 m0, s17
	s_nop 0
	global_load_lds_dwordx4 v[236:237], off
	s_waitcnt vmcnt(8)
	s_waitcnt lgkmcnt(0)
	s_barrier
	s_setprio 1
	s_waitcnt lgkmcnt(0)
	v_mfma_f32_16x16x32_bf16 v[124:127], v[146:149], v[178:181], v[124:127]
	v_mfma_f32_16x16x32_bf16 v[120:123], v[154:157], v[178:181], v[120:123]
	v_mfma_f32_16x16x32_bf16 v[116:119], v[146:149], v[186:189], v[116:119]
	v_mfma_f32_16x16x32_bf16 v[108:111], v[154:157], v[186:189], v[108:111]
	v_mfma_f32_16x16x32_bf16 v[100:103], v[146:149], v[220:223], v[100:103]
	v_mfma_f32_16x16x32_bf16 v[92:95], v[154:157], v[220:223], v[92:95]
	v_mfma_f32_16x16x32_bf16 v[84:87], v[146:149], v[228:231], v[84:87]
	v_mfma_f32_16x16x32_bf16 v[76:79], v[154:157], v[228:231], v[76:79]
	v_mfma_f32_16x16x32_bf16 v[124:127], v[150:153], v[182:185], v[124:127]
	v_mfma_f32_16x16x32_bf16 v[120:123], v[158:161], v[182:185], v[120:123]
	v_mfma_f32_16x16x32_bf16 v[116:119], v[150:153], v[190:193], v[116:119]
	v_mfma_f32_16x16x32_bf16 v[108:111], v[158:161], v[190:193], v[108:111]
	v_mfma_f32_16x16x32_bf16 v[100:103], v[150:153], v[224:227], v[100:103]
	v_mfma_f32_16x16x32_bf16 v[92:95], v[158:161], v[224:227], v[92:95]
	v_mfma_f32_16x16x32_bf16 v[84:87], v[150:153], v[232:235], v[84:87]
	v_mfma_f32_16x16x32_bf16 v[76:79], v[158:161], v[232:235], v[76:79]
	s_setprio 0
	s_setprio 1
	v_mfma_f32_16x16x32_bf16 v[112:115], v[162:165], v[178:181], v[112:115]
	v_mfma_f32_16x16x32_bf16 v[104:107], v[170:173], v[178:181], v[104:107]
	v_mfma_f32_16x16x32_bf16 v[96:99], v[162:165], v[186:189], v[96:99]
	v_mfma_f32_16x16x32_bf16 v[88:91], v[170:173], v[186:189], v[88:91]
	v_mfma_f32_16x16x32_bf16 v[80:83], v[162:165], v[220:223], v[80:83]
	v_mfma_f32_16x16x32_bf16 v[72:75], v[170:173], v[220:223], v[72:75]
	v_mfma_f32_16x16x32_bf16 v[68:71], v[162:165], v[228:231], v[68:71]
	v_mfma_f32_16x16x32_bf16 v[64:67], v[170:173], v[228:231], v[64:67]
	v_mfma_f32_16x16x32_bf16 v[112:115], v[166:169], v[182:185], v[112:115]
	v_mfma_f32_16x16x32_bf16 v[104:107], v[174:177], v[182:185], v[104:107]
	v_mfma_f32_16x16x32_bf16 v[96:99], v[166:169], v[190:193], v[96:99]
	v_mfma_f32_16x16x32_bf16 v[88:91], v[174:177], v[190:193], v[88:91]
	v_mfma_f32_16x16x32_bf16 v[80:83], v[166:169], v[224:227], v[80:83]
	v_mfma_f32_16x16x32_bf16 v[72:75], v[174:177], v[224:227], v[72:75]
	v_mfma_f32_16x16x32_bf16 v[68:71], v[166:169], v[232:235], v[68:71]
	v_mfma_f32_16x16x32_bf16 v[64:67], v[174:177], v[232:235], v[64:67]
	s_setprio 0
	s_barrier
; #define PG8_STAGE(bufoff, gbase, voff) do { _Pragma("unroll") for (int _i = 0; _i < 2; ++_i) \
;         __builtin_amdgcn_global_load_lds((const unsigned*)((const char*)(gbase) + (voff)[_i]), (PG8_LAS unsigned*)(lds + (bufoff) + ldsw + _i * 8192), 16, 0, 0); } while (0)
; #define PG8_LDA(dst, b, h) do { _Pragma("unroll") for (int m = 0; m < 4; ++m) _Pragma("unroll") for (int k = 0; k < 2; ++k) dst[m][k] = *(const PG8_LAS bf16x8*)(lds + PG8_SA(b, h) + aoff + m * 2048 + k * 1024); } while (0)
; #define PG8_LDB(dst, b, h) do { _Pragma("unroll") for (int n = 0; n < 2; ++n) _Pragma("unroll") for (int k = 0; k < 2; ++k) dst[n][k] = *(const PG8_LAS bf16x8*)(lds + PG8_SB(b, h) + boff + n * 2048 + k * 1024); } while (0)
; #define PG8_MMA(ai, bj, At, Bt) do { __builtin_amdgcn_s_setprio(1); _Pragma("unroll") for (int m = 0; m < 4; ++m) _Pragma("unroll") for (int n = 0; n < 2; ++n) _Pragma("unroll") for (int k = 0; k < 2; ++k) \
;         acc[ai][bj][m][n] = __builtin_amdgcn_mfma_f32_16x16x32_bf16(Bt[n][k], At[m][k], acc[ai][bj][m][n], 0, 0, 0); __builtin_amdgcn_s_setprio(0); } while (0)
; #define PG8_WAIT_V(n) asm volatile("s_waitcnt vmcnt(" #n ")" ::: "memory")
; #define PG8_WAIT_L(n) asm volatile("s_waitcnt lgkmcnt(" #n ")" ::: "memory")
; #define PG8_BAR __builtin_amdgcn_s_barrier()
; #define PG8_SCHED __builtin_amdgcn_sched_barrier(0)
; template <class Epi, class Sched, bool ALIGN_EPI = false, bool SP2 = false>
; __device__ __forceinline__ void gemm_phase(PG8_LAS unsigned char* lds, const Gemm g, const Sched& S, const Epi& E) {
;     ...
;             PG8_LDA(At, 0, 1); PG8_STAGE(PG8_SB(0, 0), b2, voffB); PG8_STAGE(PG8_SB(0, 1), b2 + hstep, voffB); PG8_STAGE(PG8_SA(0, 0), a2, voffA);
;             PG8_WAIT_V(8); PG8_WAIT_L(0); PG8_BAR; PG8_MMA(1, 0, At, B0); PG8_MMA(1, 1, At, B1); PG8_BAR; PG8_SCHED;
;             PG8_LDB(B0, 1, 0); PG8_LDB(B1, 1, 1); PG8_SCHED; PG8_LDA(At, 1, 0); PG8_STAGE(PG8_SA(0, 1), a2 + hstep, voffA);
;             PG8_WAIT_V(8); PG8_WAIT_L(0); PG8_BAR; PG8_MMA(0, 0, At, B0); PG8_MMA(0, 1, At, B1); PG8_BAR; PG8_SCHED;
;             PG8_LDA(At, 1, 1); PG8_STAGE(PG8_SB(1, 0), b3, voffB); PG8_STAGE(PG8_SB(1, 1), b3 + hstep, voffB); PG8_STAGE(PG8_SA(1, 0), a3, voffA);
;             PG8_WAIT_V(8); PG8_WAIT_L(0); PG8_BAR; PG8_MMA(1, 0, At, B0); PG8_MMA(1, 1, At, B1); PG8_BAR; PG8_SCHED;
	s_add_i32 s43, s43, s2
	v_lshl_add_u64 v[140:141], v[140:141], 0, s[20:21]
	s_mov_b32 m0, s43
	ds_read_b128 v[178:181], v145 offset:49152
	ds_read_b128 v[182:185], v145 offset:50176
	ds_read_b128 v[186:189], v145 offset:51200
	ds_read_b128 v[190:193], v145 offset:52224
	ds_read_b128 v[220:223], v145 offset:53248
	ds_read_b128 v[224:227], v145 offset:54272
	ds_read_b128 v[228:231], v145 offset:55296
	ds_read_b128 v[232:235], v145 offset:56320
	global_load_lds_dwordx4 v[140:141], off
	s_add_i32 m0, s43, 0x2000
	s_add_u32 s52, s68, 0x80080
	v_lshl_add_u64 v[140:141], v[206:207], 0, s[20:21]
	s_addc_u32 s53, s69, 0
	s_add_i32 s43, s45, s2
	global_load_lds_dwordx4 v[140:141], off
	v_lshl_add_u64 v[140:141], s[52:53], 0, v[128:129]
	s_mov_b32 m0, s43
	s_nop 0
	global_load_lds_dwordx4 v[140:141], off
	v_lshl_add_u64 v[140:141], s[52:53], 0, v[130:131]
	s_add_i32 m0, s43, 0x2000
	s_nop 0
	global_load_lds_dwordx4 v[140:141], off
	v_lshl_add_u64 v[140:141], v[214:215], 0, s[20:21]
	s_mov_b32 m0, s26
	s_nop 0
	global_load_lds_dwordx4 v[140:141], off
	v_lshl_add_u64 v[140:141], v[216:217], 0, s[20:21]
	s_mov_b32 m0, s27
	s_nop 0
	global_load_lds_dwordx4 v[140:141], off
	s_waitcnt vmcnt(8)
	s_waitcnt lgkmcnt(0)
	s_barrier
	s_setprio 1
	s_waitcnt lgkmcnt(0)
	v_mfma_f32_16x16x32_bf16 v[60:63], v[146:149], v[178:181], v[60:63]
	v_mfma_f32_16x16x32_bf16 v[56:59], v[154:157], v[178:181], v[56:59]
	v_mfma_f32_16x16x32_bf16 v[52:55], v[146:149], v[186:189], v[52:55]
	v_mfma_f32_16x16x32_bf16 v[44:47], v[154:157], v[186:189], v[44:47]
	v_mfma_f32_16x16x32_bf16 v[36:39], v[146:149], v[220:223], v[36:39]
	v_mfma_f32_16x16x32_bf16 v[28:31], v[154:157], v[220:223], v[28:31]
	v_mfma_f32_16x16x32_bf16 v[20:23], v[146:149], v[228:231], v[20:23]
	v_mfma_f32_16x16x32_bf16 v[12:15], v[154:157], v[228:231], v[12:15]
	v_mfma_f32_16x16x32_bf16 v[60:63], v[150:153], v[182:185], v[60:63]
	v_mfma_f32_16x16x32_bf16 v[56:59], v[158:161], v[182:185], v[56:59]
	v_mfma_f32_16x16x32_bf16 v[52:55], v[150:153], v[190:193], v[52:55]
	v_mfma_f32_16x16x32_bf16 v[44:47], v[158:161], v[190:193], v[44:47]
	v_mfma_f32_16x16x32_bf16 v[36:39], v[150:153], v[224:227], v[36:39]
	v_mfma_f32_16x16x32_bf16 v[28:31], v[158:161], v[224:227], v[28:31]
	v_mfma_f32_16x16x32_bf16 v[20:23], v[150:153], v[232:235], v[20:23]
	v_mfma_f32_16x16x32_bf16 v[12:15], v[158:161], v[232:235], v[12:15]
	s_setprio 0
	s_setprio 1
	v_mfma_f32_16x16x32_bf16 v[48:51], v[162:165], v[178:181], v[48:51]
	v_mfma_f32_16x16x32_bf16 v[40:43], v[170:173], v[178:181], v[40:43]
	v_mfma_f32_16x16x32_bf16 v[32:35], v[162:165], v[186:189], v[32:35]
	v_mfma_f32_16x16x32_bf16 v[24:27], v[170:173], v[186:189], v[24:27]
	v_mfma_f32_16x16x32_bf16 v[16:19], v[162:165], v[220:223], v[16:19]
	v_mfma_f32_16x16x32_bf16 v[8:11], v[170:173], v[220:223], v[8:11]
	v_mfma_f32_16x16x32_bf16 v[4:7], v[162:165], v[228:231], v[4:7]
	v_mfma_f32_16x16x32_bf16 v[0:3], v[170:173], v[228:231], v[0:3]
	v_mfma_f32_16x16x32_bf16 v[48:51], v[166:169], v[182:185], v[48:51]
	v_mfma_f32_16x16x32_bf16 v[40:43], v[174:177], v[182:185], v[40:43]
	v_mfma_f32_16x16x32_bf16 v[32:35], v[166:169], v[190:193], v[32:35]
	v_mfma_f32_16x16x32_bf16 v[24:27], v[174:177], v[190:193], v[24:27]
	v_mfma_f32_16x16x32_bf16 v[16:19], v[166:169], v[224:227], v[16:19]
	v_mfma_f32_16x16x32_bf16 v[8:11], v[174:177], v[224:227], v[8:11]
	v_mfma_f32_16x16x32_bf16 v[4:7], v[166:169], v[232:235], v[4:7]
	v_mfma_f32_16x16x32_bf16 v[0:3], v[174:177], v[232:235], v[0:3]
	s_setprio 0
	s_barrier
	s_add_i32 s37, s37, 2
	s_add_u32 s66, s66, 0x100
	s_addc_u32 s67, s67, 0
	s_add_u32 s34, s34, 0x100
	s_addc_u32 s35, s35, 0
	s_cmp_gt_u32 s37, 29
	s_cbranch_scc0 .LBB0_485
	s_and_b64 vcc, exec, s[12:13]
	s_cbranch_vccz .LBB0_488
	s_barrier

; #define PG8_STAGE(bufoff, gbase, voff) do { _Pragma("unroll") for (int _i = 0; _i < 2; ++_i) \
;         __builtin_amdgcn_global_load_lds((const unsigned*)((const char*)(gbase) + (voff)[_i]), (PG8_LAS unsigned*)(lds + (bufoff) + ldsw + _i * 8192), 16, 0, 0); } while (0)
; #define PG8_LDA(dst, b, h) do { _Pragma("unroll") for (int m = 0; m < 4; ++m) _Pragma("unroll") for (int k = 0; k < 2; ++k) dst[m][k] = *(const PG8_LAS bf16x8*)(lds + PG8_SA(b, h) + aoff + m * 2048 + k * 1024); } while (0)
; #define PG8_LDB(dst, b, h) do { _Pragma("unroll") for (int n = 0; n < 2; ++n) _Pragma("unroll") for (int k = 0; k < 2; ++k) dst[n][k] = *(const PG8_LAS bf16x8*)(lds + PG8_SB(b, h) + boff + n * 2048 + k * 1024); } while (0)
; #define PG8_MMA(ai, bj, At, Bt) do { __builtin_amdgcn_s_setprio(1); _Pragma("unroll") for (int m = 0; m < 4; ++m) _Pragma("unroll") for (int n = 0; n < 2; ++n) _Pragma("unroll") for (int k = 0; k < 2; ++k) \
;         acc[ai][bj][m][n] = __builtin_amdgcn_mfma_f32_16x16x32_bf16(Bt[n][k], At[m][k], acc[ai][bj][m][n], 0, 0, 0); __builtin_amdgcn_s_setprio(0); } while (0)
; #define PG8_WAIT_V(n) asm volatile("s_waitcnt vmcnt(" #n ")" ::: "memory")
; #define PG8_WAIT_L(n) asm volatile("s_waitcnt lgkmcnt(" #n ")" ::: "memory")
; #define PG8_BAR __builtin_amdgcn_s_barrier()
; #define PG8_SCHED __builtin_amdgcn_sched_barrier(0)
; template <class Epi, class Sched, bool ALIGN_EPI = false, bool SP2 = false>
; __device__ __forceinline__ void gemm_phase(PG8_LAS unsigned char* lds, const Gemm g, const Sched& S, const Epi& E) {
;     ...
;         for (int t = 0; t < nt; t += 2) {
;             const bool last = (t == nt - 2);
;             const char* a1 = cA + (size_t)(t + 1) * kstep;
;             const char* a2 = last ? nA : cA + (size_t)(t + 2) * kstep; const char* b2 = last ? nB : cB + (size_t)(t + 2) * kstep;
;             const char* a3 = a2 + kstep; const char* b3 = b2 + kstep;
;             if (last && has_next) S.a_ready(nxt);
;             if constexpr (SP2) {
;             PG8_LDB(B0, 0, 0); PG8_LDB(B1, 0, 1); PG8_SCHED; PG8_LDA(At, 0, 0); PG8_STAGE(PG8_SA(1, 1), a1 + hstep, voffA);
;             PG8_WAIT_V(8); PG8_WAIT_L(0); PG8_BAR; PG8_MMA(0, 0, At, B0); PG8_MMA(0, 1, At, B1); PG8_BAR; PG8_SCHED;
.LBB0_699:
	s_add_u32 s53, s42, 0xfff80080
	s_addc_u32 s63, s43, -1
	s_add_i32 s67, 0, 0x10000
	s_cmp_eq_u32 s52, 28
	s_cselect_b32 s71, s2, s63
	s_cselect_b32 s70, s31, s53
	v_add_u32_e32 v128, s67, v173
	s_cselect_b32 s69, s33, s45
	s_cselect_b32 s68, s34, s35
	s_add_i32 s53, 0, 0x14000
	ds_read_b128 v[130:133], v128
	ds_read_b128 v[134:137], v128 offset:1024
	ds_read_b128 v[158:161], v128 offset:2048
	ds_read_b128 v[162:165], v128 offset:3072
	v_add_u32_e32 v128, s53, v173
	ds_read_b128 v[166:169], v128
	ds_read_b128 v[176:179], v128 offset:1024
	ds_read_b128 v[180:183], v128 offset:2048
	ds_read_b128 v[184:187], v128 offset:3072
	v_lshl_add_u64 v[170:171], s[42:43], 0, v[154:155]
	s_add_i32 m0, s17, 0xc000
	ds_read_b128 v[188:191], v175
	ds_read_b128 v[220:223], v175 offset:1024
	ds_read_b128 v[224:227], v175 offset:2048
	ds_read_b128 v[228:231], v175 offset:3072
	ds_read_b128 v[232:235], v175 offset:4096
	ds_read_b128 v[236:239], v175 offset:5120
	ds_read_b128 v[240:243], v175 offset:6144
	ds_read_b128 v[244:247], v175 offset:7168
	global_load_lds_dwordx4 v[170:171], off
	v_lshl_add_u64 v[170:171], s[42:43], 0, v[156:157]
	s_add_i32 m0, s17, 0xe000
	s_nop 0
	global_load_lds_dwordx4 v[170:171], off
	s_cmp_lt_i32 s52, 0
	s_cbranch_scc0 .Lrx1_0_norm
	s_cmp_lt_u32 s49, 2
	s_cbranch_scc1 .Lrx1_0_norm
	s_waitcnt vmcnt(24)
	s_branch .Lrx1_0_join

; #define PG8_STAGE(bufoff, gbase, voff) do { _Pragma("unroll") for (int _i = 0; _i < 2; ++_i) \
;         __builtin_amdgcn_global_load_lds((const unsigned*)((const char*)(gbase) + (voff)[_i]), (PG8_LAS unsigned*)(lds + (bufoff) + ldsw + _i * 8192), 16, 0, 0); } while (0)
; #define PG8_LDA(dst, b, h) do { _Pragma("unroll") for (int m = 0; m < 4; ++m) _Pragma("unroll") for (int k = 0; k < 2; ++k) dst[m][k] = *(const PG8_LAS bf16x8*)(lds + PG8_SA(b, h) + aoff + m * 2048 + k * 1024); } while (0)
; #define PG8_MMA(ai, bj, At, Bt) do { __builtin_amdgcn_s_setprio(1); _Pragma("unroll") for (int m = 0; m < 4; ++m) _Pragma("unroll") for (int n = 0; n < 2; ++n) _Pragma("unroll") for (int k = 0; k < 2; ++k) \
;         acc[ai][bj][m][n] = __builtin_amdgcn_mfma_f32_16x16x32_bf16(Bt[n][k], At[m][k], acc[ai][bj][m][n], 0, 0, 0); __builtin_amdgcn_s_setprio(0); } while (0)
; #define PG8_WAIT_V(n) asm volatile("s_waitcnt vmcnt(" #n ")" ::: "memory")
; #define PG8_WAIT_L(n) asm volatile("s_waitcnt lgkmcnt(" #n ")" ::: "memory")
; #define PG8_BAR __builtin_amdgcn_s_barrier()
; #define PG8_SCHED __builtin_amdgcn_sched_barrier(0)
; template <class Epi, class Sched, bool ALIGN_EPI = false, bool SP2 = false>
; __device__ __forceinline__ void gemm_phase(PG8_LAS unsigned char* lds, const Gemm g, const Sched& S, const Epi& E) {
;     ...
;             PG8_WAIT_V(8); PG8_WAIT_L(0); PG8_BAR; PG8_MMA(0, 0, At, B0); PG8_MMA(0, 1, At, B1); PG8_BAR; PG8_SCHED;
;             PG8_LDA(At, 0, 1); PG8_STAGE(PG8_SB(0, 0), b2, voffB); PG8_STAGE(PG8_SB(0, 1), b2 + hstep, voffB); PG8_STAGE(PG8_SA(0, 0), a2, voffA);
;             PG8_WAIT_V(8); PG8_WAIT_L(0); PG8_BAR; PG8_MMA(1, 0, At, B0); PG8_MMA(1, 1, At, B1); PG8_BAR; PG8_SCHED;
.Lrx1_0_join:
	s_waitcnt lgkmcnt(0)
	s_barrier
	s_setprio 1
	s_waitcnt lgkmcnt(0)
	v_mfma_f32_16x16x32_bf16 v[124:127], v[130:133], v[188:191], v[124:127]
	v_mfma_f32_16x16x32_bf16 v[120:123], v[158:161], v[188:191], v[120:123]
	v_mfma_f32_16x16x32_bf16 v[108:111], v[130:133], v[224:227], v[108:111]
	v_mfma_f32_16x16x32_bf16 v[104:107], v[158:161], v[224:227], v[104:107]
	v_mfma_f32_16x16x32_bf16 v[92:95], v[130:133], v[232:235], v[92:95]
	v_mfma_f32_16x16x32_bf16 v[88:91], v[158:161], v[232:235], v[88:91]
	v_mfma_f32_16x16x32_bf16 v[76:79], v[130:133], v[240:243], v[76:79]
	v_mfma_f32_16x16x32_bf16 v[72:75], v[158:161], v[240:243], v[72:75]
	v_mfma_f32_16x16x32_bf16 v[124:127], v[134:137], v[220:223], v[124:127]
	v_mfma_f32_16x16x32_bf16 v[120:123], v[162:165], v[220:223], v[120:123]
	v_mfma_f32_16x16x32_bf16 v[108:111], v[134:137], v[228:231], v[108:111]
	v_mfma_f32_16x16x32_bf16 v[104:107], v[162:165], v[228:231], v[104:107]
	v_mfma_f32_16x16x32_bf16 v[92:95], v[134:137], v[236:239], v[92:95]
	v_mfma_f32_16x16x32_bf16 v[88:91], v[162:165], v[236:239], v[88:91]
	v_mfma_f32_16x16x32_bf16 v[76:79], v[134:137], v[244:247], v[76:79]
	v_mfma_f32_16x16x32_bf16 v[72:75], v[162:165], v[244:247], v[72:75]
	s_setprio 0
	s_setprio 1
	v_mfma_f32_16x16x32_bf16 v[116:119], v[166:169], v[188:191], v[116:119]
	v_mfma_f32_16x16x32_bf16 v[112:115], v[180:183], v[188:191], v[112:115]
	v_mfma_f32_16x16x32_bf16 v[100:103], v[166:169], v[224:227], v[100:103]
	v_mfma_f32_16x16x32_bf16 v[96:99], v[180:183], v[224:227], v[96:99]
	v_mfma_f32_16x16x32_bf16 v[84:87], v[166:169], v[232:235], v[84:87]
	v_mfma_f32_16x16x32_bf16 v[80:83], v[180:183], v[232:235], v[80:83]
	v_mfma_f32_16x16x32_bf16 v[68:71], v[166:169], v[240:243], v[68:71]
	v_mfma_f32_16x16x32_bf16 v[64:67], v[180:183], v[240:243], v[64:67]
	v_mfma_f32_16x16x32_bf16 v[116:119], v[176:179], v[220:223], v[116:119]
	v_mfma_f32_16x16x32_bf16 v[112:115], v[184:187], v[220:223], v[112:115]
	v_mfma_f32_16x16x32_bf16 v[100:103], v[176:179], v[228:231], v[100:103]
	v_mfma_f32_16x16x32_bf16 v[96:99], v[184:187], v[228:231], v[96:99]
	v_mfma_f32_16x16x32_bf16 v[84:87], v[176:179], v[236:239], v[84:87]
	v_mfma_f32_16x16x32_bf16 v[80:83], v[184:187], v[236:239], v[80:83]
	v_mfma_f32_16x16x32_bf16 v[68:71], v[176:179], v[244:247], v[68:71]
	v_mfma_f32_16x16x32_bf16 v[64:67], v[184:187], v[244:247], v[64:67]
	s_setprio 0
	s_barrier
	s_add_i32 s63, s67, s10
	v_lshl_add_u64 v[170:171], s[68:69], 0, v[140:141]
	s_mov_b32 m0, s63
	ds_read_b128 v[188:191], v175 offset:16384
	ds_read_b128 v[220:223], v175 offset:17408
	ds_read_b128 v[224:227], v175 offset:18432
	ds_read_b128 v[228:231], v175 offset:19456
	ds_read_b128 v[232:235], v175 offset:20480
	ds_read_b128 v[236:239], v175 offset:21504
	ds_read_b128 v[240:243], v175 offset:22528
	ds_read_b128 v[244:247], v175 offset:23552
	global_load_lds_dwordx4 v[170:171], off
	s_add_i32 m0, s63, 0x2000
	s_add_u32 s72, s68, 0x80000
	v_lshl_add_u64 v[192:193], s[68:69], 0, v[144:145]
	s_addc_u32 s73, s69, 0
	s_add_i32 s53, s53, s10
	global_load_lds_dwordx4 v[192:193], off
	v_lshl_add_u64 v[206:207], s[72:73], 0, v[140:141]
	s_mov_b32 m0, s53
	v_lshl_add_u64 v[214:215], s[70:71], 0, v[142:143]
	global_load_lds_dwordx4 v[206:207], off
	v_lshl_add_u64 v[206:207], s[72:73], 0, v[144:145]
	s_add_i32 m0, s53, 0x2000
	s_nop 0
	global_load_lds_dwordx4 v[206:207], off
	v_lshl_add_u64 v[206:207], s[70:71], 0, v[138:139]
	s_mov_b32 m0, s17
	s_nop 0
	global_load_lds_dwordx4 v[206:207], off
	s_mov_b32 m0, s26
	s_nop 0
	global_load_lds_dwordx4 v[214:215], off
	s_cmp_lt_i32 s52, 0
	s_cbranch_scc0 .Lrx1_1_norm
	s_cmp_lt_u32 s49, 2
	s_cbranch_scc1 .Lrx1_1_norm
	s_waitcnt vmcnt(24)
	s_branch .Lrx1_1_join

; #define PG8_STAGE(bufoff, gbase, voff) do { _Pragma("unroll") for (int _i = 0; _i < 2; ++_i) \
;         __builtin_amdgcn_global_load_lds((const unsigned*)((const char*)(gbase) + (voff)[_i]), (PG8_LAS unsigned*)(lds + (bufoff) + ldsw + _i * 8192), 16, 0, 0); } while (0)
; #define PG8_LDA(dst, b, h) do { _Pragma("unroll") for (int m = 0; m < 4; ++m) _Pragma("unroll") for (int k = 0; k < 2; ++k) dst[m][k] = *(const PG8_LAS bf16x8*)(lds + PG8_SA(b, h) + aoff + m * 2048 + k * 1024); } while (0)
; #define PG8_LDB(dst, b, h) do { _Pragma("unroll") for (int n = 0; n < 2; ++n) _Pragma("unroll") for (int k = 0; k < 2; ++k) dst[n][k] = *(const PG8_LAS bf16x8*)(lds + PG8_SB(b, h) + boff + n * 2048 + k * 1024); } while (0)
; #define PG8_MMA(ai, bj, At, Bt) do { __builtin_amdgcn_s_setprio(1); _Pragma("unroll") for (int m = 0; m < 4; ++m) _Pragma("unroll") for (int n = 0; n < 2; ++n) _Pragma("unroll") for (int k = 0; k < 2; ++k) \
;         acc[ai][bj][m][n] = __builtin_amdgcn_mfma_f32_16x16x32_bf16(Bt[n][k], At[m][k], acc[ai][bj][m][n], 0, 0, 0); __builtin_amdgcn_s_setprio(0); } while (0)
; #define PG8_WAIT_V(n) asm volatile("s_waitcnt vmcnt(" #n ")" ::: "memory")
; #define PG8_WAIT_L(n) asm volatile("s_waitcnt lgkmcnt(" #n ")" ::: "memory")
; #define PG8_BAR __builtin_amdgcn_s_barrier()
; #define PG8_SCHED __builtin_amdgcn_sched_barrier(0)
; template <class Epi, class Sched, bool ALIGN_EPI = false, bool SP2 = false>
; __device__ __forceinline__ void gemm_phase(PG8_LAS unsigned char* lds, const Gemm g, const Sched& S, const Epi& E) {
;     ...
;             PG8_WAIT_V(8); PG8_WAIT_L(0); PG8_BAR; PG8_MMA(1, 0, At, B0); PG8_MMA(1, 1, At, B1); PG8_BAR; PG8_SCHED;
;             PG8_LDB(B0, 1, 0); PG8_LDB(B1, 1, 1); PG8_SCHED; PG8_LDA(At, 1, 0); PG8_STAGE(PG8_SA(0, 1), a2 + hstep, voffA);
;             PG8_WAIT_V(8); PG8_WAIT_L(0); PG8_BAR; PG8_MMA(0, 0, At, B0); PG8_MMA(0, 1, At, B1); PG8_BAR; PG8_SCHED;
.Lrx1_1_join:
	s_waitcnt lgkmcnt(0)
	s_barrier
	s_setprio 1
	s_waitcnt lgkmcnt(0)
	v_mfma_f32_16x16x32_bf16 v[60:63], v[130:133], v[188:191], v[60:63]
	v_mfma_f32_16x16x32_bf16 v[56:59], v[158:161], v[188:191], v[56:59]
	v_mfma_f32_16x16x32_bf16 v[44:47], v[130:133], v[224:227], v[44:47]
	v_mfma_f32_16x16x32_bf16 v[40:43], v[158:161], v[224:227], v[40:43]
	v_mfma_f32_16x16x32_bf16 v[28:31], v[130:133], v[232:235], v[28:31]
	v_mfma_f32_16x16x32_bf16 v[24:27], v[158:161], v[232:235], v[24:27]
	v_mfma_f32_16x16x32_bf16 v[12:15], v[130:133], v[240:243], v[12:15]
	v_mfma_f32_16x16x32_bf16 v[8:11], v[158:161], v[240:243], v[8:11]
	v_mfma_f32_16x16x32_bf16 v[60:63], v[134:137], v[220:223], v[60:63]
	v_mfma_f32_16x16x32_bf16 v[56:59], v[162:165], v[220:223], v[56:59]
	v_mfma_f32_16x16x32_bf16 v[44:47], v[134:137], v[228:231], v[44:47]
	v_mfma_f32_16x16x32_bf16 v[40:43], v[162:165], v[228:231], v[40:43]
	v_mfma_f32_16x16x32_bf16 v[28:31], v[134:137], v[236:239], v[28:31]
	v_mfma_f32_16x16x32_bf16 v[24:27], v[162:165], v[236:239], v[24:27]
	v_mfma_f32_16x16x32_bf16 v[12:15], v[134:137], v[244:247], v[12:15]
	v_mfma_f32_16x16x32_bf16 v[8:11], v[162:165], v[244:247], v[8:11]
	s_setprio 0
	s_setprio 1
	v_mfma_f32_16x16x32_bf16 v[52:55], v[166:169], v[188:191], v[52:55]
	v_mfma_f32_16x16x32_bf16 v[48:51], v[180:183], v[188:191], v[48:51]
	v_mfma_f32_16x16x32_bf16 v[36:39], v[166:169], v[224:227], v[36:39]
	v_mfma_f32_16x16x32_bf16 v[32:35], v[180:183], v[224:227], v[32:35]
	v_mfma_f32_16x16x32_bf16 v[20:23], v[166:169], v[232:235], v[20:23]
	v_mfma_f32_16x16x32_bf16 v[16:19], v[180:183], v[232:235], v[16:19]
	v_mfma_f32_16x16x32_bf16 v[4:7], v[166:169], v[240:243], v[4:7]
	v_mfma_f32_16x16x32_bf16 v[0:3], v[180:183], v[240:243], v[0:3]
	v_mfma_f32_16x16x32_bf16 v[52:55], v[176:179], v[220:223], v[52:55]
	v_mfma_f32_16x16x32_bf16 v[48:51], v[184:187], v[220:223], v[48:51]
	v_mfma_f32_16x16x32_bf16 v[36:39], v[176:179], v[228:231], v[36:39]
	v_mfma_f32_16x16x32_bf16 v[32:35], v[184:187], v[228:231], v[32:35]
	v_mfma_f32_16x16x32_bf16 v[20:23], v[176:179], v[236:239], v[20:23]
	v_mfma_f32_16x16x32_bf16 v[16:19], v[184:187], v[236:239], v[16:19]
	v_mfma_f32_16x16x32_bf16 v[4:7], v[176:179], v[244:247], v[4:7]
	v_mfma_f32_16x16x32_bf16 v[0:3], v[184:187], v[244:247], v[0:3]
	s_setprio 0
	s_barrier
	s_add_i32 s53, 0, 0x18000
	v_add_u32_e32 v128, s53, v173
	s_add_i32 s63, 0, 0x1c000
	ds_read_b128 v[130:133], v128
	ds_read_b128 v[134:137], v128 offset:1024
	ds_read_b128 v[158:161], v128 offset:2048
	ds_read_b128 v[162:165], v128 offset:3072
	v_add_u32_e32 v128, s63, v173
	ds_read_b128 v[166:169], v128
	ds_read_b128 v[176:179], v128 offset:1024
	ds_read_b128 v[180:183], v128 offset:2048
	ds_read_b128 v[184:187], v128 offset:3072
	s_add_u32 s70, s70, 0x80000
	s_addc_u32 s71, s71, 0
	s_mov_b32 m0, s27
	v_lshl_add_u64 v[216:217], s[70:71], 0, v[138:139]
	ds_read_b128 v[188:191], v175 offset:32768
	ds_read_b128 v[220:223], v175 offset:33792
	ds_read_b128 v[224:227], v175 offset:34816
	ds_read_b128 v[228:231], v175 offset:35840
	ds_read_b128 v[232:235], v175 offset:36864
	ds_read_b128 v[236:239], v175 offset:37888
	ds_read_b128 v[240:243], v175 offset:38912
	ds_read_b128 v[244:247], v175 offset:39936
	global_load_lds_dwordx4 v[216:217], off
	v_lshl_add_u64 v[216:217], s[70:71], 0, v[142:143]
	s_mov_b32 m0, s28
	s_nop 0
	global_load_lds_dwordx4 v[216:217], off
	s_waitcnt vmcnt(8)
	s_waitcnt lgkmcnt(0)
	s_barrier
	s_setprio 1
	s_waitcnt lgkmcnt(0)
	v_mfma_f32_16x16x32_bf16 v[124:127], v[130:133], v[188:191], v[124:127]
	v_mfma_f32_16x16x32_bf16 v[120:123], v[158:161], v[188:191], v[120:123]
	v_mfma_f32_16x16x32_bf16 v[108:111], v[130:133], v[224:227], v[108:111]
	v_mfma_f32_16x16x32_bf16 v[104:107], v[158:161], v[224:227], v[104:107]
	v_mfma_f32_16x16x32_bf16 v[92:95], v[130:133], v[232:235], v[92:95]
	v_mfma_f32_16x16x32_bf16 v[88:91], v[158:161], v[232:235], v[88:91]
	v_mfma_f32_16x16x32_bf16 v[76:79], v[130:133], v[240:243], v[76:79]
	v_mfma_f32_16x16x32_bf16 v[72:75], v[158:161], v[240:243], v[72:75]
	v_mfma_f32_16x16x32_bf16 v[124:127], v[134:137], v[220:223], v[124:127]
	v_mfma_f32_16x16x32_bf16 v[120:123], v[162:165], v[220:223], v[120:123]
	v_mfma_f32_16x16x32_bf16 v[108:111], v[134:137], v[228:231], v[108:111]
	v_mfma_f32_16x16x32_bf16 v[104:107], v[162:165], v[228:231], v[104:107]
	v_mfma_f32_16x16x32_bf16 v[92:95], v[134:137], v[236:239], v[92:95]
	v_mfma_f32_16x16x32_bf16 v[88:91], v[162:165], v[236:239], v[88:91]
	v_mfma_f32_16x16x32_bf16 v[76:79], v[134:137], v[244:247], v[76:79]
	v_mfma_f32_16x16x32_bf16 v[72:75], v[162:165], v[244:247], v[72:75]
	s_setprio 0
	s_setprio 1
	v_mfma_f32_16x16x32_bf16 v[116:119], v[166:169], v[188:191], v[116:119]
	v_mfma_f32_16x16x32_bf16 v[112:115], v[180:183], v[188:191], v[112:115]
	v_mfma_f32_16x16x32_bf16 v[100:103], v[166:169], v[224:227], v[100:103]
	v_mfma_f32_16x16x32_bf16 v[96:99], v[180:183], v[224:227], v[96:99]
	v_mfma_f32_16x16x32_bf16 v[84:87], v[166:169], v[232:235], v[84:87]
	v_mfma_f32_16x16x32_bf16 v[80:83], v[180:183], v[232:235], v[80:83]
	v_mfma_f32_16x16x32_bf16 v[68:71], v[166:169], v[240:243], v[68:71]
	v_mfma_f32_16x16x32_bf16 v[64:67], v[180:183], v[240:243], v[64:67]
	v_mfma_f32_16x16x32_bf16 v[116:119], v[176:179], v[220:223], v[116:119]
	v_mfma_f32_16x16x32_bf16 v[112:115], v[184:187], v[220:223], v[112:115]
	v_mfma_f32_16x16x32_bf16 v[100:103], v[176:179], v[228:231], v[100:103]
	v_mfma_f32_16x16x32_bf16 v[96:99], v[184:187], v[228:231], v[96:99]
	v_mfma_f32_16x16x32_bf16 v[84:87], v[176:179], v[236:239], v[84:87]
	v_mfma_f32_16x16x32_bf16 v[80:83], v[184:187], v[236:239], v[80:83]
	v_mfma_f32_16x16x32_bf16 v[68:71], v[176:179], v[244:247], v[68:71]
	v_mfma_f32_16x16x32_bf16 v[64:67], v[184:187], v[244:247], v[64:67]
	s_setprio 0
	s_barrier
; #define PG8_STAGE(bufoff, gbase, voff) do { _Pragma("unroll") for (int _i = 0; _i < 2; ++_i) \
;         __builtin_amdgcn_global_load_lds((const unsigned*)((const char*)(gbase) + (voff)[_i]), (PG8_LAS unsigned*)(lds + (bufoff) + ldsw + _i * 8192), 16, 0, 0); } while (0)
; #define PG8_LDA(dst, b, h) do { _Pragma("unroll") for (int m = 0; m < 4; ++m) _Pragma("unroll") for (int k = 0; k < 2; ++k) dst[m][k] = *(const PG8_LAS bf16x8*)(lds + PG8_SA(b, h) + aoff + m * 2048 + k * 1024); } while (0)
; #define PG8_LDB(dst, b, h) do { _Pragma("unroll") for (int n = 0; n < 2; ++n) _Pragma("unroll") for (int k = 0; k < 2; ++k) dst[n][k] = *(const PG8_LAS bf16x8*)(lds + PG8_SB(b, h) + boff + n * 2048 + k * 1024); } while (0)
; #define PG8_MMA(ai, bj, At, Bt) do { __builtin_amdgcn_s_setprio(1); _Pragma("unroll") for (int m = 0; m < 4; ++m) _Pragma("unroll") for (int n = 0; n < 2; ++n) _Pragma("unroll") for (int k = 0; k < 2; ++k) \
;         acc[ai][bj][m][n] = __builtin_amdgcn_mfma_f32_16x16x32_bf16(Bt[n][k], At[m][k], acc[ai][bj][m][n], 0, 0, 0); __builtin_amdgcn_s_setprio(0); } while (0)
; #define PG8_WAIT_V(n) asm volatile("s_waitcnt vmcnt(" #n ")" ::: "memory")
; #define PG8_WAIT_L(n) asm volatile("s_waitcnt lgkmcnt(" #n ")" ::: "memory")
; #define PG8_BAR __builtin_amdgcn_s_barrier()
; #define PG8_SCHED __builtin_amdgcn_sched_barrier(0)
; template <class Epi, class Sched, bool ALIGN_EPI = false, bool SP2 = false>
; __device__ __forceinline__ void gemm_phase(PG8_LAS unsigned char* lds, const Gemm g, const Sched& S, const Epi& E) {
;     ...
;             PG8_LDA(At, 0, 1); PG8_STAGE(PG8_SB(0, 0), b2, voffB); PG8_STAGE(PG8_SB(0, 1), b2 + hstep, voffB); PG8_STAGE(PG8_SA(0, 0), a2, voffA);
;             PG8_WAIT_V(8); PG8_WAIT_L(0); PG8_BAR; PG8_MMA(1, 0, At, B0); PG8_MMA(1, 1, At, B1); PG8_BAR; PG8_SCHED;
;             PG8_LDB(B0, 1, 0); PG8_LDB(B1, 1, 1); PG8_SCHED; PG8_LDA(At, 1, 0); PG8_STAGE(PG8_SA(0, 1), a2 + hstep, voffA);
;             PG8_WAIT_V(8); PG8_WAIT_L(0); PG8_BAR; PG8_MMA(0, 0, At, B0); PG8_MMA(0, 1, At, B1); PG8_BAR; PG8_SCHED;
;             PG8_LDA(At, 1, 1); PG8_STAGE(PG8_SB(1, 0), b3, voffB); PG8_STAGE(PG8_SB(1, 1), b3 + hstep, voffB); PG8_STAGE(PG8_SA(1, 0), a3, voffA);
;             PG8_WAIT_V(8); PG8_WAIT_L(0); PG8_BAR; PG8_MMA(1, 0, At, B0); PG8_MMA(1, 1, At, B1); PG8_BAR; PG8_SCHED;
	s_add_i32 s53, s53, s10
	v_lshl_add_u64 v[170:171], v[170:171], 0, s[20:21]
	s_mov_b32 m0, s53
	ds_read_b128 v[188:191], v175 offset:49152
	ds_read_b128 v[220:223], v175 offset:50176
	ds_read_b128 v[224:227], v175 offset:51200
	ds_read_b128 v[228:231], v175 offset:52224
	ds_read_b128 v[232:235], v175 offset:53248
	ds_read_b128 v[236:239], v175 offset:54272
	ds_read_b128 v[240:243], v175 offset:55296
	ds_read_b128 v[244:247], v175 offset:56320
	global_load_lds_dwordx4 v[170:171], off
	s_add_i32 m0, s53, 0x2000
	s_add_u32 s68, s68, 0x80080
	v_lshl_add_u64 v[170:171], v[192:193], 0, s[20:21]
	s_addc_u32 s69, s69, 0
	s_add_i32 s53, s63, s10
	global_load_lds_dwordx4 v[170:171], off
	v_lshl_add_u64 v[170:171], s[68:69], 0, v[140:141]
	s_mov_b32 m0, s53
	s_nop 0
	global_load_lds_dwordx4 v[170:171], off
	v_lshl_add_u64 v[170:171], s[68:69], 0, v[144:145]
	s_add_i32 m0, s53, 0x2000
	s_nop 0
	global_load_lds_dwordx4 v[170:171], off
	v_lshl_add_u64 v[170:171], v[206:207], 0, s[20:21]
	s_mov_b32 m0, s29
	s_nop 0
	global_load_lds_dwordx4 v[170:171], off
	v_lshl_add_u64 v[170:171], v[214:215], 0, s[20:21]
	s_mov_b32 m0, s37
	s_nop 0
	global_load_lds_dwordx4 v[170:171], off
	s_waitcnt vmcnt(8)
	s_waitcnt lgkmcnt(0)
	s_barrier
	s_setprio 1
	s_waitcnt lgkmcnt(0)
	v_mfma_f32_16x16x32_bf16 v[60:63], v[130:133], v[188:191], v[60:63]
	v_mfma_f32_16x16x32_bf16 v[56:59], v[158:161], v[188:191], v[56:59]
	v_mfma_f32_16x16x32_bf16 v[44:47], v[130:133], v[224:227], v[44:47]
	v_mfma_f32_16x16x32_bf16 v[40:43], v[158:161], v[224:227], v[40:43]
	v_mfma_f32_16x16x32_bf16 v[28:31], v[130:133], v[232:235], v[28:31]
	v_mfma_f32_16x16x32_bf16 v[24:27], v[158:161], v[232:235], v[24:27]
	v_mfma_f32_16x16x32_bf16 v[12:15], v[130:133], v[240:243], v[12:15]
	v_mfma_f32_16x16x32_bf16 v[8:11], v[158:161], v[240:243], v[8:11]
	v_mfma_f32_16x16x32_bf16 v[60:63], v[134:137], v[220:223], v[60:63]
	v_mfma_f32_16x16x32_bf16 v[56:59], v[162:165], v[220:223], v[56:59]
	v_mfma_f32_16x16x32_bf16 v[44:47], v[134:137], v[228:231], v[44:47]
	v_mfma_f32_16x16x32_bf16 v[40:43], v[162:165], v[228:231], v[40:43]
	v_mfma_f32_16x16x32_bf16 v[28:31], v[134:137], v[236:239], v[28:31]
	v_mfma_f32_16x16x32_bf16 v[24:27], v[162:165], v[236:239], v[24:27]
	v_mfma_f32_16x16x32_bf16 v[12:15], v[134:137], v[244:247], v[12:15]
	v_mfma_f32_16x16x32_bf16 v[8:11], v[162:165], v[244:247], v[8:11]
	s_setprio 0
	s_setprio 1
	v_mfma_f32_16x16x32_bf16 v[52:55], v[166:169], v[188:191], v[52:55]
	v_mfma_f32_16x16x32_bf16 v[48:51], v[180:183], v[188:191], v[48:51]
	v_mfma_f32_16x16x32_bf16 v[36:39], v[166:169], v[224:227], v[36:39]
	v_mfma_f32_16x16x32_bf16 v[32:35], v[180:183], v[224:227], v[32:35]
	v_mfma_f32_16x16x32_bf16 v[20:23], v[166:169], v[232:235], v[20:23]
	v_mfma_f32_16x16x32_bf16 v[16:19], v[180:183], v[232:235], v[16:19]
	v_mfma_f32_16x16x32_bf16 v[4:7], v[166:169], v[240:243], v[4:7]
	v_mfma_f32_16x16x32_bf16 v[0:3], v[180:183], v[240:243], v[0:3]
	v_mfma_f32_16x16x32_bf16 v[52:55], v[176:179], v[220:223], v[52:55]
	v_mfma_f32_16x16x32_bf16 v[48:51], v[184:187], v[220:223], v[48:51]
	v_mfma_f32_16x16x32_bf16 v[36:39], v[176:179], v[228:231], v[36:39]
	v_mfma_f32_16x16x32_bf16 v[32:35], v[184:187], v[228:231], v[32:35]
	v_mfma_f32_16x16x32_bf16 v[20:23], v[176:179], v[236:239], v[20:23]
	v_mfma_f32_16x16x32_bf16 v[16:19], v[184:187], v[236:239], v[16:19]
	v_mfma_f32_16x16x32_bf16 v[4:7], v[176:179], v[244:247], v[4:7]
	v_mfma_f32_16x16x32_bf16 v[0:3], v[184:187], v[244:247], v[0:3]
	s_setprio 0
	s_barrier
	s_add_i32 s52, s52, 2
	s_add_u32 s42, s42, 0x100
	s_addc_u32 s43, s43, 0
	s_add_u32 s35, s35, 0x100
	s_addc_u32 s45, s45, 0
	s_cmp_gt_u32 s52, 29
	s_cbranch_scc0 .LBB0_699
	s_and_b64 vcc, exec, s[12:13]
	s_cbranch_vccz .LBB0_702
	s_barrier
